# 256x128 GEMM tuning: A fragments read 7 ahead, B fragment loads issued at position 4 of the step
# speedup vs baseline: 1.1129x; 1.0092x over previous
.Lg256b_w2_first_retry:
	s_cmp_ge_u32 s12, 64
	s_cbranch_scc1 .Lg256b_w2_done
	s_lshr_b32 s3, s12, 6
	s_lshl_b32 s3, s3, 3
	s_add_u32 s3, s3, s65
	s_mov_b32 s17, s3
	s_mov_b32 s3, 0
	s_lshl_b32 s17, s17, 3
	s_bfe_u32 s23, s12, 0x30003
	s_add_u32 s13, s17, s23
	s_lshl_b32 s3, s3, 3
	s_and_b32 s23, s12, 7
	s_add_u32 s14, s3, s23
	s_lshl_b32 s13, s13, 8
	s_lshl_b32 s14, s14, 7
	s_lshl_b32 s3, s15, 6
	s_add_u32 s17, s3, s13
	s_mul_i32 s17, s17, 0x2000
	s_add_u32 s6, s18, s17
	s_addc_u32 s7, s19, 0
	s_lshr_b32 s3, s14, 4
	s_lshl_b32 s17, s15, 1
	s_add_u32 s3, s3, s17
	s_mul_i32 s17, s3, 0x20000
	s_add_u32 s8, s20, s17
	s_addc_u32 s9, s21, 0
	s_barrier
	v_mov_b32_e32 v217, v218
	v_mov_b32_e32 v220, v222
	v_add_u32_e32 v221, 0x20000, v222
	s_add_u32 m0, s22, 0x0
	v_mov_b32_e32 v223, v217
	global_load_lds_dwordx4 v223, s[6:7]
	s_add_u32 m0, s22, 0x400
	v_add_u32_e32 v224, 0x40, v217
	global_load_lds_dwordx4 v224, s[6:7]
	s_add_u32 m0, s22, 0x800
	v_add_u32_e32 v223, 0x20000, v217
	global_load_lds_dwordx4 v223, s[6:7]
	s_add_u32 m0, s22, 0xc00
	v_add_u32_e32 v224, 0x20040, v217
	global_load_lds_dwordx4 v224, s[6:7]
	s_add_u32 m0, s22, 0x1000
	v_add_u32_e32 v223, 0x40000, v217
	global_load_lds_dwordx4 v223, s[6:7]
	s_add_u32 m0, s22, 0x1400
	v_add_u32_e32 v224, 0x40040, v217
	global_load_lds_dwordx4 v224, s[6:7]
	s_add_u32 m0, s22, 0x1800
	v_add_u32_e32 v223, 0x60000, v217
	global_load_lds_dwordx4 v223, s[6:7]
	s_add_u32 m0, s22, 0x1c00
	v_add_u32_e32 v224, 0x60040, v217
	global_load_lds_dwordx4 v224, s[6:7]
	v_add_u32_e32 v217, 0x80, v217
	s_add_u32 m0, s22, 0x8000
	v_mov_b32_e32 v223, v217
	global_load_lds_dwordx4 v223, s[6:7]
	s_add_u32 m0, s22, 0x8400
	v_add_u32_e32 v224, 0x40, v217
	global_load_lds_dwordx4 v224, s[6:7]
	s_add_u32 m0, s22, 0x8800
	v_add_u32_e32 v223, 0x20000, v217
	global_load_lds_dwordx4 v223, s[6:7]
	s_add_u32 m0, s22, 0x8c00
	v_add_u32_e32 v224, 0x20040, v217
	global_load_lds_dwordx4 v224, s[6:7]
	s_add_u32 m0, s22, 0x9000
	v_add_u32_e32 v223, 0x40000, v217
	global_load_lds_dwordx4 v223, s[6:7]
	s_add_u32 m0, s22, 0x9400
	v_add_u32_e32 v224, 0x40040, v217
	global_load_lds_dwordx4 v224, s[6:7]
	s_add_u32 m0, s22, 0x9800
	v_add_u32_e32 v223, 0x60000, v217
	global_load_lds_dwordx4 v223, s[6:7]
	s_add_u32 m0, s22, 0x9c00
	v_add_u32_e32 v224, 0x60040, v217
	global_load_lds_dwordx4 v224, s[6:7]
	v_add_u32_e32 v217, 0x80, v217
	global_load_dwordx4 v[166:169], v220, s[8:9]
	global_load_dwordx4 v[170:173], v220, s[8:9] offset:1024
	global_load_dwordx4 v[174:177], v221, s[8:9]
	global_load_dwordx4 v[178:181], v221, s[8:9] offset:1024
	v_add_u32_e32 v220, 0x800, v220
	v_add_u32_e32 v221, 0x800, v221
	s_waitcnt vmcnt(0)
	s_barrier
	ds_read_b128 v[134:137], v216
	ds_read_b128 v[138:141], v216 offset:2048
	ds_read_b128 v[142:145], v216 offset:4096
	ds_read_b128 v[146:149], v216 offset:6144
	ds_read_b128 v[150:153], v216 offset:8192
	ds_read_b128 v[154:157], v216 offset:10240
	ds_read_b128 v[158:161], v216 offset:12288
.Lg256b_w2_tile:
	s_mul_i32 s17, s13, 0x1000
	s_lshl_b32 s3, s15, 5
	s_add_u32 s3, s3, s14
	s_mul_i32 s3, s3, 4
	s_add_u32 s17, s17, s3
	s_add_u32 s10, s24, s17
	s_addc_u32 s11, s25, 0
	s_lshl_b32 s3, s15, 5
	s_add_u32 s3, s3, s14
	s_lshl_b32 s3, s3, 2
	s_lshr_b32 s17, s13, 12
	s_max_u32 s17, s17, 1
	s_sub_u32 s17, s17, 1
	s_mul_i32 s17, s17, 24576
	s_add_u32 s3, s3, s17
	v_add_u32_e32 v234, s3, v225
	s_mov_b64 s[26:27], s[10:11]
	ds_read_b128 v[162:165], v216 offset:14336
	s_waitcnt vmcnt(16) lgkmcnt(7)
	v_mfma_f32_16x16x32_bf16 v[2:5], v[166:169], v[134:137], 0
	v_mfma_f32_16x16x32_bf16 v[6:9], v[174:177], v[134:137], 0
	ds_read_b128 v[134:137], v216 offset:16384
	s_waitcnt lgkmcnt(7)
	v_mfma_f32_16x16x32_bf16 v[10:13], v[166:169], v[138:141], 0
	v_mfma_f32_16x16x32_bf16 v[14:17], v[174:177], v[138:141], 0
	ds_read_b128 v[138:141], v216 offset:18432
	s_waitcnt lgkmcnt(7)
	v_mfma_f32_16x16x32_bf16 v[18:21], v[166:169], v[142:145], 0
	v_mfma_f32_16x16x32_bf16 v[22:25], v[174:177], v[142:145], 0
	ds_read_b128 v[142:145], v216 offset:20480
	s_waitcnt lgkmcnt(7)
	v_mfma_f32_16x16x32_bf16 v[26:29], v[166:169], v[146:149], 0
	v_mfma_f32_16x16x32_bf16 v[30:33], v[174:177], v[146:149], 0
	ds_read_b128 v[146:149], v216 offset:22528
	s_waitcnt lgkmcnt(7)
	v_mfma_f32_16x16x32_bf16 v[34:37], v[166:169], v[150:153], 0
	global_load_dwordx4 v[196:199], v220, s[8:9]
	v_mfma_f32_16x16x32_bf16 v[38:41], v[174:177], v[150:153], 0
	global_load_dwordx4 v[200:203], v220, s[8:9] offset:1024
	ds_read_b128 v[150:153], v216 offset:24576
	s_waitcnt lgkmcnt(7)
	v_mfma_f32_16x16x32_bf16 v[42:45], v[166:169], v[154:157], 0
	global_load_dwordx4 v[204:207], v221, s[8:9]
	v_mfma_f32_16x16x32_bf16 v[46:49], v[174:177], v[154:157], 0
	global_load_dwordx4 v[212:215], v221, s[8:9] offset:1024
	ds_read_b128 v[154:157], v216 offset:26624
	s_waitcnt lgkmcnt(7)
	v_mfma_f32_16x16x32_bf16 v[50:53], v[166:169], v[158:161], 0
	v_mfma_f32_16x16x32_bf16 v[54:57], v[174:177], v[158:161], 0
	ds_read_b128 v[158:161], v216 offset:28672
	s_waitcnt lgkmcnt(7)
	v_mfma_f32_16x16x32_bf16 v[58:61], v[166:169], v[162:165], 0
	v_mfma_f32_16x16x32_bf16 v[62:65], v[174:177], v[162:165], 0
	ds_read_b128 v[162:165], v216 offset:30720
	s_waitcnt lgkmcnt(7)
	v_mfma_f32_16x16x32_bf16 v[66:69], v[166:169], v[134:137], 0
	v_mfma_f32_16x16x32_bf16 v[70:73], v[174:177], v[134:137], 0
	ds_read_b128 v[134:137], v216 offset:1024
	s_waitcnt lgkmcnt(7)
	v_mfma_f32_16x16x32_bf16 v[74:77], v[166:169], v[138:141], 0
	v_mfma_f32_16x16x32_bf16 v[78:81], v[174:177], v[138:141], 0
	ds_read_b128 v[138:141], v216 offset:3072
	s_waitcnt lgkmcnt(7)
	v_mfma_f32_16x16x32_bf16 v[82:85], v[166:169], v[142:145], 0
	v_mfma_f32_16x16x32_bf16 v[86:89], v[174:177], v[142:145], 0
	ds_read_b128 v[142:145], v216 offset:5120
	s_waitcnt lgkmcnt(7)
	v_mfma_f32_16x16x32_bf16 v[90:93], v[166:169], v[146:149], 0
	v_mfma_f32_16x16x32_bf16 v[94:97], v[174:177], v[146:149], 0
	ds_read_b128 v[146:149], v216 offset:7168
	s_waitcnt lgkmcnt(7)
	v_mfma_f32_16x16x32_bf16 v[98:101], v[166:169], v[150:153], 0
	v_mfma_f32_16x16x32_bf16 v[102:105], v[174:177], v[150:153], 0
	ds_read_b128 v[150:153], v216 offset:9216
	s_waitcnt lgkmcnt(7)
	v_mfma_f32_16x16x32_bf16 v[106:109], v[166:169], v[154:157], 0
	v_mfma_f32_16x16x32_bf16 v[110:113], v[174:177], v[154:157], 0
	ds_read_b128 v[154:157], v216 offset:11264
	s_waitcnt lgkmcnt(7)
	v_mfma_f32_16x16x32_bf16 v[114:117], v[166:169], v[158:161], 0
	v_mfma_f32_16x16x32_bf16 v[118:121], v[174:177], v[158:161], 0
	ds_read_b128 v[158:161], v216 offset:13312
	s_waitcnt lgkmcnt(7)
	v_mfma_f32_16x16x32_bf16 v[122:125], v[166:169], v[162:165], 0
	v_mfma_f32_16x16x32_bf16 v[126:129], v[174:177], v[162:165], 0
	ds_read_b128 v[162:165], v216 offset:15360
	s_waitcnt lgkmcnt(7)
	v_mfma_f32_16x16x32_bf16 v[2:5], v[170:173], v[134:137], v[2:5]
	v_mfma_f32_16x16x32_bf16 v[6:9], v[178:181], v[134:137], v[6:9]
	ds_read_b128 v[134:137], v216 offset:17408
	s_waitcnt lgkmcnt(7)
	v_mfma_f32_16x16x32_bf16 v[10:13], v[170:173], v[138:141], v[10:13]
	v_mfma_f32_16x16x32_bf16 v[14:17], v[178:181], v[138:141], v[14:17]
	ds_read_b128 v[138:141], v216 offset:19456
	s_waitcnt lgkmcnt(7)
	v_mfma_f32_16x16x32_bf16 v[18:21], v[170:173], v[142:145], v[18:21]
	v_mfma_f32_16x16x32_bf16 v[22:25], v[178:181], v[142:145], v[22:25]
	ds_read_b128 v[142:145], v216 offset:21504
	s_waitcnt lgkmcnt(7)
	v_mfma_f32_16x16x32_bf16 v[26:29], v[170:173], v[146:149], v[26:29]
	v_mfma_f32_16x16x32_bf16 v[30:33], v[178:181], v[146:149], v[30:33]
	ds_read_b128 v[146:149], v216 offset:23552
	s_waitcnt lgkmcnt(7)
	v_mfma_f32_16x16x32_bf16 v[34:37], v[170:173], v[150:153], v[34:37]
	v_mfma_f32_16x16x32_bf16 v[38:41], v[178:181], v[150:153], v[38:41]
	ds_read_b128 v[150:153], v216 offset:25600
	s_waitcnt lgkmcnt(7)
	v_mfma_f32_16x16x32_bf16 v[42:45], v[170:173], v[154:157], v[42:45]
	v_mfma_f32_16x16x32_bf16 v[46:49], v[178:181], v[154:157], v[46:49]
	ds_read_b128 v[154:157], v216 offset:27648
	s_waitcnt lgkmcnt(7)
	v_mfma_f32_16x16x32_bf16 v[50:53], v[170:173], v[158:161], v[50:53]
	v_mfma_f32_16x16x32_bf16 v[54:57], v[178:181], v[158:161], v[54:57]
	ds_read_b128 v[158:161], v216 offset:29696
	s_waitcnt lgkmcnt(7)
	v_mfma_f32_16x16x32_bf16 v[58:61], v[170:173], v[162:165], v[58:61]
	v_mfma_f32_16x16x32_bf16 v[62:65], v[178:181], v[162:165], v[62:65]
	ds_read_b128 v[162:165], v216 offset:31744
	s_waitcnt vmcnt(12) lgkmcnt(0)
	s_barrier
	v_mfma_f32_16x16x32_bf16 v[66:69], v[170:173], v[134:137], v[66:69]
	s_add_u32 m0, s22, 0x0
	v_mov_b32_e32 v223, v217
	global_load_lds_dwordx4 v223, s[6:7]
	v_mfma_f32_16x16x32_bf16 v[70:73], v[178:181], v[134:137], v[70:73]
	s_add_u32 m0, s22, 0x400
	v_add_u32_e32 v224, 0x40, v217
	global_load_lds_dwordx4 v224, s[6:7]
	ds_read_b128 v[134:137], v216 offset:32768
	s_waitcnt lgkmcnt(7)
	v_mfma_f32_16x16x32_bf16 v[74:77], v[170:173], v[138:141], v[74:77]
	s_add_u32 m0, s22, 0x800
	v_add_u32_e32 v223, 0x20000, v217
	global_load_lds_dwordx4 v223, s[6:7]
	v_mfma_f32_16x16x32_bf16 v[78:81], v[178:181], v[138:141], v[78:81]
	s_add_u32 m0, s22, 0xc00
	v_add_u32_e32 v224, 0x20040, v217
	global_load_lds_dwordx4 v224, s[6:7]
	ds_read_b128 v[138:141], v216 offset:34816
	s_waitcnt lgkmcnt(7)
	v_mfma_f32_16x16x32_bf16 v[82:85], v[170:173], v[142:145], v[82:85]
	s_add_u32 m0, s22, 0x1000
	v_add_u32_e32 v223, 0x40000, v217
	global_load_lds_dwordx4 v223, s[6:7]
	v_mfma_f32_16x16x32_bf16 v[86:89], v[178:181], v[142:145], v[86:89]
	s_add_u32 m0, s22, 0x1400
	v_add_u32_e32 v224, 0x40040, v217
	global_load_lds_dwordx4 v224, s[6:7]
	ds_read_b128 v[142:145], v216 offset:36864
	s_waitcnt lgkmcnt(7)
	v_mfma_f32_16x16x32_bf16 v[90:93], v[170:173], v[146:149], v[90:93]
	s_add_u32 m0, s22, 0x1800
	v_add_u32_e32 v223, 0x60000, v217
	global_load_lds_dwordx4 v223, s[6:7]
	v_mfma_f32_16x16x32_bf16 v[94:97], v[178:181], v[146:149], v[94:97]
	s_add_u32 m0, s22, 0x1c00
	v_add_u32_e32 v224, 0x60040, v217
	global_load_lds_dwordx4 v224, s[6:7]
	ds_read_b128 v[146:149], v216 offset:38912
	s_waitcnt lgkmcnt(7)
	v_mfma_f32_16x16x32_bf16 v[98:101], v[170:173], v[150:153], v[98:101]
	v_mfma_f32_16x16x32_bf16 v[102:105], v[178:181], v[150:153], v[102:105]
	ds_read_b128 v[150:153], v216 offset:40960
	s_waitcnt lgkmcnt(7)
	v_mfma_f32_16x16x32_bf16 v[106:109], v[170:173], v[154:157], v[106:109]
	v_mfma_f32_16x16x32_bf16 v[110:113], v[178:181], v[154:157], v[110:113]
	ds_read_b128 v[154:157], v216 offset:43008
	s_waitcnt lgkmcnt(7)
	v_mfma_f32_16x16x32_bf16 v[114:117], v[170:173], v[158:161], v[114:117]
	v_mfma_f32_16x16x32_bf16 v[118:121], v[178:181], v[158:161], v[118:121]
	ds_read_b128 v[158:161], v216 offset:45056
	s_waitcnt lgkmcnt(7)
	v_mfma_f32_16x16x32_bf16 v[122:125], v[170:173], v[162:165], v[122:125]
	v_mfma_f32_16x16x32_bf16 v[126:129], v[178:181], v[162:165], v[126:129]
	v_add_u32_e32 v217, 0x80, v217
	v_add_u32_e32 v220, 0x800, v220
	v_add_u32_e32 v221, 0x800, v221
	ds_read_b128 v[162:165], v216 offset:47104
	s_waitcnt vmcnt(8) lgkmcnt(7)
	v_mfma_f32_16x16x32_bf16 v[2:5], v[196:199], v[134:137], v[2:5]
	v_mfma_f32_16x16x32_bf16 v[6:9], v[204:207], v[134:137], v[6:9]
	ds_read_b128 v[134:137], v216 offset:49152
	s_waitcnt lgkmcnt(7)
	v_mfma_f32_16x16x32_bf16 v[10:13], v[196:199], v[138:141], v[10:13]
	v_mfma_f32_16x16x32_bf16 v[14:17], v[204:207], v[138:141], v[14:17]
	ds_read_b128 v[138:141], v216 offset:51200
	s_waitcnt lgkmcnt(7)
	v_mfma_f32_16x16x32_bf16 v[18:21], v[196:199], v[142:145], v[18:21]
	v_mfma_f32_16x16x32_bf16 v[22:25], v[204:207], v[142:145], v[22:25]
	ds_read_b128 v[142:145], v216 offset:53248
	s_waitcnt lgkmcnt(7)
	v_mfma_f32_16x16x32_bf16 v[26:29], v[196:199], v[146:149], v[26:29]
	v_mfma_f32_16x16x32_bf16 v[30:33], v[204:207], v[146:149], v[30:33]
	ds_read_b128 v[146:149], v216 offset:55296
	s_waitcnt lgkmcnt(7)
	v_mfma_f32_16x16x32_bf16 v[34:37], v[196:199], v[150:153], v[34:37]
	global_load_dwordx4 v[166:169], v220, s[8:9]
	v_mfma_f32_16x16x32_bf16 v[38:41], v[204:207], v[150:153], v[38:41]
	global_load_dwordx4 v[170:173], v220, s[8:9] offset:1024
	ds_read_b128 v[150:153], v216 offset:57344
	s_waitcnt lgkmcnt(7)
	v_mfma_f32_16x16x32_bf16 v[42:45], v[196:199], v[154:157], v[42:45]
	global_load_dwordx4 v[174:177], v221, s[8:9]
	v_mfma_f32_16x16x32_bf16 v[46:49], v[204:207], v[154:157], v[46:49]
	global_load_dwordx4 v[178:181], v221, s[8:9] offset:1024
	ds_read_b128 v[154:157], v216 offset:59392
	s_waitcnt lgkmcnt(7)
	v_mfma_f32_16x16x32_bf16 v[50:53], v[196:199], v[158:161], v[50:53]
	v_mfma_f32_16x16x32_bf16 v[54:57], v[204:207], v[158:161], v[54:57]
	ds_read_b128 v[158:161], v216 offset:61440
	s_waitcnt lgkmcnt(7)
	v_mfma_f32_16x16x32_bf16 v[58:61], v[196:199], v[162:165], v[58:61]
	v_mfma_f32_16x16x32_bf16 v[62:65], v[204:207], v[162:165], v[62:65]
	ds_read_b128 v[162:165], v216 offset:63488
	s_waitcnt lgkmcnt(7)
	v_mfma_f32_16x16x32_bf16 v[66:69], v[196:199], v[134:137], v[66:69]
	v_mfma_f32_16x16x32_bf16 v[70:73], v[204:207], v[134:137], v[70:73]
	ds_read_b128 v[134:137], v216 offset:33792
	s_waitcnt lgkmcnt(7)
	v_mfma_f32_16x16x32_bf16 v[74:77], v[196:199], v[138:141], v[74:77]
	v_mfma_f32_16x16x32_bf16 v[78:81], v[204:207], v[138:141], v[78:81]
	ds_read_b128 v[138:141], v216 offset:35840
	s_waitcnt lgkmcnt(7)
	v_mfma_f32_16x16x32_bf16 v[82:85], v[196:199], v[142:145], v[82:85]
	v_mfma_f32_16x16x32_bf16 v[86:89], v[204:207], v[142:145], v[86:89]
	ds_read_b128 v[142:145], v216 offset:37888
	s_waitcnt lgkmcnt(7)
	v_mfma_f32_16x16x32_bf16 v[90:93], v[196:199], v[146:149], v[90:93]
	v_mfma_f32_16x16x32_bf16 v[94:97], v[204:207], v[146:149], v[94:97]
	ds_read_b128 v[146:149], v216 offset:39936
	s_waitcnt lgkmcnt(7)
	v_mfma_f32_16x16x32_bf16 v[98:101], v[196:199], v[150:153], v[98:101]
	v_mfma_f32_16x16x32_bf16 v[102:105], v[204:207], v[150:153], v[102:105]
	ds_read_b128 v[150:153], v216 offset:41984
	s_waitcnt lgkmcnt(7)
	v_mfma_f32_16x16x32_bf16 v[106:109], v[196:199], v[154:157], v[106:109]
	v_mfma_f32_16x16x32_bf16 v[110:113], v[204:207], v[154:157], v[110:113]
	ds_read_b128 v[154:157], v216 offset:44032
	s_waitcnt lgkmcnt(7)
	v_mfma_f32_16x16x32_bf16 v[114:117], v[196:199], v[158:161], v[114:117]
	v_mfma_f32_16x16x32_bf16 v[118:121], v[204:207], v[158:161], v[118:121]
	ds_read_b128 v[158:161], v216 offset:46080
	s_waitcnt lgkmcnt(7)
	v_mfma_f32_16x16x32_bf16 v[122:125], v[196:199], v[162:165], v[122:125]
	v_mfma_f32_16x16x32_bf16 v[126:129], v[204:207], v[162:165], v[126:129]
	ds_read_b128 v[162:165], v216 offset:48128
	s_waitcnt lgkmcnt(7)
	v_mfma_f32_16x16x32_bf16 v[2:5], v[200:203], v[134:137], v[2:5]
	v_mfma_f32_16x16x32_bf16 v[6:9], v[212:215], v[134:137], v[6:9]
	ds_read_b128 v[134:137], v216 offset:50176
	s_waitcnt lgkmcnt(7)
	v_mfma_f32_16x16x32_bf16 v[10:13], v[200:203], v[138:141], v[10:13]
	v_mfma_f32_16x16x32_bf16 v[14:17], v[212:215], v[138:141], v[14:17]
	ds_read_b128 v[138:141], v216 offset:52224
	s_waitcnt lgkmcnt(7)
	v_mfma_f32_16x16x32_bf16 v[18:21], v[200:203], v[142:145], v[18:21]
	v_mfma_f32_16x16x32_bf16 v[22:25], v[212:215], v[142:145], v[22:25]
	ds_read_b128 v[142:145], v216 offset:54272
	s_waitcnt lgkmcnt(7)
	v_mfma_f32_16x16x32_bf16 v[26:29], v[200:203], v[146:149], v[26:29]
	v_mfma_f32_16x16x32_bf16 v[30:33], v[212:215], v[146:149], v[30:33]
	ds_read_b128 v[146:149], v216 offset:56320
	s_waitcnt lgkmcnt(7)
	v_mfma_f32_16x16x32_bf16 v[34:37], v[200:203], v[150:153], v[34:37]
	v_mfma_f32_16x16x32_bf16 v[38:41], v[212:215], v[150:153], v[38:41]
	ds_read_b128 v[150:153], v216 offset:58368
	s_waitcnt lgkmcnt(7)
	v_mfma_f32_16x16x32_bf16 v[42:45], v[200:203], v[154:157], v[42:45]
	v_mfma_f32_16x16x32_bf16 v[46:49], v[212:215], v[154:157], v[46:49]
	ds_read_b128 v[154:157], v216 offset:60416
	s_waitcnt lgkmcnt(7)
	v_mfma_f32_16x16x32_bf16 v[50:53], v[200:203], v[158:161], v[50:53]
	v_mfma_f32_16x16x32_bf16 v[54:57], v[212:215], v[158:161], v[54:57]
	ds_read_b128 v[158:161], v216 offset:62464
	s_waitcnt lgkmcnt(7)
	v_mfma_f32_16x16x32_bf16 v[58:61], v[200:203], v[162:165], v[58:61]
	v_mfma_f32_16x16x32_bf16 v[62:65], v[212:215], v[162:165], v[62:65]
	ds_read_b128 v[162:165], v216 offset:64512
	s_waitcnt vmcnt(4) lgkmcnt(0)
	s_barrier
	v_mfma_f32_16x16x32_bf16 v[66:69], v[200:203], v[134:137], v[66:69]
	s_add_u32 m0, s22, 0x8000
	v_mov_b32_e32 v223, v217
	global_load_lds_dwordx4 v223, s[6:7]
	v_mfma_f32_16x16x32_bf16 v[70:73], v[212:215], v[134:137], v[70:73]
	s_add_u32 m0, s22, 0x8400
	v_add_u32_e32 v224, 0x40, v217
	global_load_lds_dwordx4 v224, s[6:7]
	ds_read_b128 v[134:137], v216
	s_waitcnt lgkmcnt(7)
	v_mfma_f32_16x16x32_bf16 v[74:77], v[200:203], v[138:141], v[74:77]
	s_add_u32 m0, s22, 0x8800
	v_add_u32_e32 v223, 0x20000, v217
	global_load_lds_dwordx4 v223, s[6:7]
	v_mfma_f32_16x16x32_bf16 v[78:81], v[212:215], v[138:141], v[78:81]
	s_add_u32 m0, s22, 0x8c00
	v_add_u32_e32 v224, 0x20040, v217
	global_load_lds_dwordx4 v224, s[6:7]
	ds_read_b128 v[138:141], v216 offset:2048
	s_waitcnt lgkmcnt(7)
	v_mfma_f32_16x16x32_bf16 v[82:85], v[200:203], v[142:145], v[82:85]
	s_add_u32 m0, s22, 0x9000
	v_add_u32_e32 v223, 0x40000, v217
	global_load_lds_dwordx4 v223, s[6:7]
	v_mfma_f32_16x16x32_bf16 v[86:89], v[212:215], v[142:145], v[86:89]
	s_add_u32 m0, s22, 0x9400
	v_add_u32_e32 v224, 0x40040, v217
	global_load_lds_dwordx4 v224, s[6:7]
	ds_read_b128 v[142:145], v216 offset:4096
	s_waitcnt lgkmcnt(7)
	v_mfma_f32_16x16x32_bf16 v[90:93], v[200:203], v[146:149], v[90:93]
	s_add_u32 m0, s22, 0x9800
	v_add_u32_e32 v223, 0x60000, v217
	global_load_lds_dwordx4 v223, s[6:7]
	v_mfma_f32_16x16x32_bf16 v[94:97], v[212:215], v[146:149], v[94:97]
	s_add_u32 m0, s22, 0x9c00
	v_add_u32_e32 v224, 0x60040, v217
	global_load_lds_dwordx4 v224, s[6:7]
	ds_read_b128 v[146:149], v216 offset:6144
	s_waitcnt lgkmcnt(7)
	v_mfma_f32_16x16x32_bf16 v[98:101], v[200:203], v[150:153], v[98:101]
	v_mfma_f32_16x16x32_bf16 v[102:105], v[212:215], v[150:153], v[102:105]
	ds_read_b128 v[150:153], v216 offset:8192
	s_waitcnt lgkmcnt(7)
	v_mfma_f32_16x16x32_bf16 v[106:109], v[200:203], v[154:157], v[106:109]
	v_mfma_f32_16x16x32_bf16 v[110:113], v[212:215], v[154:157], v[110:113]
	ds_read_b128 v[154:157], v216 offset:10240
	s_waitcnt lgkmcnt(7)
	v_mfma_f32_16x16x32_bf16 v[114:117], v[200:203], v[158:161], v[114:117]
	v_mfma_f32_16x16x32_bf16 v[118:121], v[212:215], v[158:161], v[118:121]
	ds_read_b128 v[158:161], v216 offset:12288
	s_waitcnt lgkmcnt(7)
	v_mfma_f32_16x16x32_bf16 v[122:125], v[200:203], v[162:165], v[122:125]
	v_mfma_f32_16x16x32_bf16 v[126:129], v[212:215], v[162:165], v[126:129]
	v_add_u32_e32 v217, 0x80, v217
	v_add_u32_e32 v220, 0x800, v220
	v_add_u32_e32 v221, 0x800, v221
	s_mov_b32 s16, 30
.Lg256b_w2_loop:
	ds_read_b128 v[162:165], v216 offset:14336
	s_waitcnt vmcnt(8) lgkmcnt(7)
	v_mfma_f32_16x16x32_bf16 v[2:5], v[166:169], v[134:137], v[2:5]
	v_mfma_f32_16x16x32_bf16 v[6:9], v[174:177], v[134:137], v[6:9]
	ds_read_b128 v[134:137], v216 offset:16384
	s_waitcnt lgkmcnt(7)
	v_mfma_f32_16x16x32_bf16 v[10:13], v[166:169], v[138:141], v[10:13]
	v_mfma_f32_16x16x32_bf16 v[14:17], v[174:177], v[138:141], v[14:17]
	ds_read_b128 v[138:141], v216 offset:18432
	s_waitcnt lgkmcnt(7)
	v_mfma_f32_16x16x32_bf16 v[18:21], v[166:169], v[142:145], v[18:21]
	v_mfma_f32_16x16x32_bf16 v[22:25], v[174:177], v[142:145], v[22:25]
	ds_read_b128 v[142:145], v216 offset:20480
	s_waitcnt lgkmcnt(7)
	v_mfma_f32_16x16x32_bf16 v[26:29], v[166:169], v[146:149], v[26:29]
	v_mfma_f32_16x16x32_bf16 v[30:33], v[174:177], v[146:149], v[30:33]
	ds_read_b128 v[146:149], v216 offset:22528
	s_waitcnt lgkmcnt(7)
	v_mfma_f32_16x16x32_bf16 v[34:37], v[166:169], v[150:153], v[34:37]
	global_load_dwordx4 v[196:199], v220, s[8:9]
	v_mfma_f32_16x16x32_bf16 v[38:41], v[174:177], v[150:153], v[38:41]
	global_load_dwordx4 v[200:203], v220, s[8:9] offset:1024
	ds_read_b128 v[150:153], v216 offset:24576
	s_waitcnt lgkmcnt(7)
	v_mfma_f32_16x16x32_bf16 v[42:45], v[166:169], v[154:157], v[42:45]
	global_load_dwordx4 v[204:207], v221, s[8:9]
	v_mfma_f32_16x16x32_bf16 v[46:49], v[174:177], v[154:157], v[46:49]
	global_load_dwordx4 v[212:215], v221, s[8:9] offset:1024
	ds_read_b128 v[154:157], v216 offset:26624
	s_waitcnt lgkmcnt(7)
	v_mfma_f32_16x16x32_bf16 v[50:53], v[166:169], v[158:161], v[50:53]
	v_mfma_f32_16x16x32_bf16 v[54:57], v[174:177], v[158:161], v[54:57]
	ds_read_b128 v[158:161], v216 offset:28672
	s_waitcnt lgkmcnt(7)
	v_mfma_f32_16x16x32_bf16 v[58:61], v[166:169], v[162:165], v[58:61]
	v_mfma_f32_16x16x32_bf16 v[62:65], v[174:177], v[162:165], v[62:65]
	ds_read_b128 v[162:165], v216 offset:30720
	s_waitcnt lgkmcnt(7)
	v_mfma_f32_16x16x32_bf16 v[66:69], v[166:169], v[134:137], v[66:69]
	v_mfma_f32_16x16x32_bf16 v[70:73], v[174:177], v[134:137], v[70:73]
	ds_read_b128 v[134:137], v216 offset:1024
	s_waitcnt lgkmcnt(7)
	v_mfma_f32_16x16x32_bf16 v[74:77], v[166:169], v[138:141], v[74:77]
	v_mfma_f32_16x16x32_bf16 v[78:81], v[174:177], v[138:141], v[78:81]
	ds_read_b128 v[138:141], v216 offset:3072
	s_waitcnt lgkmcnt(7)
	v_mfma_f32_16x16x32_bf16 v[82:85], v[166:169], v[142:145], v[82:85]
	v_mfma_f32_16x16x32_bf16 v[86:89], v[174:177], v[142:145], v[86:89]
	ds_read_b128 v[142:145], v216 offset:5120
	s_waitcnt lgkmcnt(7)
	v_mfma_f32_16x16x32_bf16 v[90:93], v[166:169], v[146:149], v[90:93]
	v_mfma_f32_16x16x32_bf16 v[94:97], v[174:177], v[146:149], v[94:97]
	ds_read_b128 v[146:149], v216 offset:7168
	s_waitcnt lgkmcnt(7)
	v_mfma_f32_16x16x32_bf16 v[98:101], v[166:169], v[150:153], v[98:101]
	v_mfma_f32_16x16x32_bf16 v[102:105], v[174:177], v[150:153], v[102:105]
	ds_read_b128 v[150:153], v216 offset:9216
	s_waitcnt lgkmcnt(7)
	v_mfma_f32_16x16x32_bf16 v[106:109], v[166:169], v[154:157], v[106:109]
	v_mfma_f32_16x16x32_bf16 v[110:113], v[174:177], v[154:157], v[110:113]
	ds_read_b128 v[154:157], v216 offset:11264
	s_waitcnt lgkmcnt(7)
	v_mfma_f32_16x16x32_bf16 v[114:117], v[166:169], v[158:161], v[114:117]
	v_mfma_f32_16x16x32_bf16 v[118:121], v[174:177], v[158:161], v[118:121]
	ds_read_b128 v[158:161], v216 offset:13312
	s_waitcnt lgkmcnt(7)
	v_mfma_f32_16x16x32_bf16 v[122:125], v[166:169], v[162:165], v[122:125]
	v_mfma_f32_16x16x32_bf16 v[126:129], v[174:177], v[162:165], v[126:129]
	ds_read_b128 v[162:165], v216 offset:15360
	s_waitcnt lgkmcnt(7)
	v_mfma_f32_16x16x32_bf16 v[2:5], v[170:173], v[134:137], v[2:5]
	v_mfma_f32_16x16x32_bf16 v[6:9], v[178:181], v[134:137], v[6:9]
	ds_read_b128 v[134:137], v216 offset:17408
	s_waitcnt lgkmcnt(7)
	v_mfma_f32_16x16x32_bf16 v[10:13], v[170:173], v[138:141], v[10:13]
	v_mfma_f32_16x16x32_bf16 v[14:17], v[178:181], v[138:141], v[14:17]
	ds_read_b128 v[138:141], v216 offset:19456
	s_waitcnt lgkmcnt(7)
	v_mfma_f32_16x16x32_bf16 v[18:21], v[170:173], v[142:145], v[18:21]
	v_mfma_f32_16x16x32_bf16 v[22:25], v[178:181], v[142:145], v[22:25]
	ds_read_b128 v[142:145], v216 offset:21504
	s_waitcnt lgkmcnt(7)
	v_mfma_f32_16x16x32_bf16 v[26:29], v[170:173], v[146:149], v[26:29]
	v_mfma_f32_16x16x32_bf16 v[30:33], v[178:181], v[146:149], v[30:33]
	ds_read_b128 v[146:149], v216 offset:23552
	s_waitcnt lgkmcnt(7)
	v_mfma_f32_16x16x32_bf16 v[34:37], v[170:173], v[150:153], v[34:37]
	v_mfma_f32_16x16x32_bf16 v[38:41], v[178:181], v[150:153], v[38:41]
	ds_read_b128 v[150:153], v216 offset:25600
	s_waitcnt lgkmcnt(7)
	v_mfma_f32_16x16x32_bf16 v[42:45], v[170:173], v[154:157], v[42:45]
	v_mfma_f32_16x16x32_bf16 v[46:49], v[178:181], v[154:157], v[46:49]
	ds_read_b128 v[154:157], v216 offset:27648
	s_waitcnt lgkmcnt(7)
	v_mfma_f32_16x16x32_bf16 v[50:53], v[170:173], v[158:161], v[50:53]
	v_mfma_f32_16x16x32_bf16 v[54:57], v[178:181], v[158:161], v[54:57]
	ds_read_b128 v[158:161], v216 offset:29696
	s_waitcnt lgkmcnt(7)
	v_mfma_f32_16x16x32_bf16 v[58:61], v[170:173], v[162:165], v[58:61]
	v_mfma_f32_16x16x32_bf16 v[62:65], v[178:181], v[162:165], v[62:65]
	ds_read_b128 v[162:165], v216 offset:31744
	s_waitcnt vmcnt(4) lgkmcnt(0)
	s_barrier
	v_mfma_f32_16x16x32_bf16 v[66:69], v[170:173], v[134:137], v[66:69]
	s_add_u32 m0, s22, 0x0
	v_mov_b32_e32 v223, v217
	global_load_lds_dwordx4 v223, s[6:7]
	v_mfma_f32_16x16x32_bf16 v[70:73], v[178:181], v[134:137], v[70:73]
	s_add_u32 m0, s22, 0x400
	v_add_u32_e32 v224, 0x40, v217
	global_load_lds_dwordx4 v224, s[6:7]
	ds_read_b128 v[134:137], v216 offset:32768
	s_waitcnt lgkmcnt(7)
	v_mfma_f32_16x16x32_bf16 v[74:77], v[170:173], v[138:141], v[74:77]
	s_add_u32 m0, s22, 0x800
	v_add_u32_e32 v223, 0x20000, v217
	global_load_lds_dwordx4 v223, s[6:7]
	v_mfma_f32_16x16x32_bf16 v[78:81], v[178:181], v[138:141], v[78:81]
	s_add_u32 m0, s22, 0xc00
	v_add_u32_e32 v224, 0x20040, v217
	global_load_lds_dwordx4 v224, s[6:7]
	ds_read_b128 v[138:141], v216 offset:34816
	s_waitcnt lgkmcnt(7)
	v_mfma_f32_16x16x32_bf16 v[82:85], v[170:173], v[142:145], v[82:85]
	s_add_u32 m0, s22, 0x1000
	v_add_u32_e32 v223, 0x40000, v217
	global_load_lds_dwordx4 v223, s[6:7]
	v_mfma_f32_16x16x32_bf16 v[86:89], v[178:181], v[142:145], v[86:89]
	s_add_u32 m0, s22, 0x1400
	v_add_u32_e32 v224, 0x40040, v217
	global_load_lds_dwordx4 v224, s[6:7]
	ds_read_b128 v[142:145], v216 offset:36864
	s_waitcnt lgkmcnt(7)
	v_mfma_f32_16x16x32_bf16 v[90:93], v[170:173], v[146:149], v[90:93]
	s_add_u32 m0, s22, 0x1800
	v_add_u32_e32 v223, 0x60000, v217
	global_load_lds_dwordx4 v223, s[6:7]
	v_mfma_f32_16x16x32_bf16 v[94:97], v[178:181], v[146:149], v[94:97]
	s_add_u32 m0, s22, 0x1c00
	v_add_u32_e32 v224, 0x60040, v217
	global_load_lds_dwordx4 v224, s[6:7]
	ds_read_b128 v[146:149], v216 offset:38912
	s_waitcnt lgkmcnt(7)
	v_mfma_f32_16x16x32_bf16 v[98:101], v[170:173], v[150:153], v[98:101]
	v_mfma_f32_16x16x32_bf16 v[102:105], v[178:181], v[150:153], v[102:105]
	ds_read_b128 v[150:153], v216 offset:40960
	s_waitcnt lgkmcnt(7)
	v_mfma_f32_16x16x32_bf16 v[106:109], v[170:173], v[154:157], v[106:109]
	v_mfma_f32_16x16x32_bf16 v[110:113], v[178:181], v[154:157], v[110:113]
	ds_read_b128 v[154:157], v216 offset:43008
	s_waitcnt lgkmcnt(7)
	v_mfma_f32_16x16x32_bf16 v[114:117], v[170:173], v[158:161], v[114:117]
	v_mfma_f32_16x16x32_bf16 v[118:121], v[178:181], v[158:161], v[118:121]
	ds_read_b128 v[158:161], v216 offset:45056
	s_waitcnt lgkmcnt(7)
	v_mfma_f32_16x16x32_bf16 v[122:125], v[170:173], v[162:165], v[122:125]
	v_mfma_f32_16x16x32_bf16 v[126:129], v[178:181], v[162:165], v[126:129]
	v_add_u32_e32 v217, 0x80, v217
	v_add_u32_e32 v220, 0x800, v220
	v_add_u32_e32 v221, 0x800, v221
	ds_read_b128 v[162:165], v216 offset:47104
	s_waitcnt vmcnt(8) lgkmcnt(7)
	v_mfma_f32_16x16x32_bf16 v[2:5], v[196:199], v[134:137], v[2:5]
	v_mfma_f32_16x16x32_bf16 v[6:9], v[204:207], v[134:137], v[6:9]
	ds_read_b128 v[134:137], v216 offset:49152
	s_waitcnt lgkmcnt(7)
	v_mfma_f32_16x16x32_bf16 v[10:13], v[196:199], v[138:141], v[10:13]
	v_mfma_f32_16x16x32_bf16 v[14:17], v[204:207], v[138:141], v[14:17]
	ds_read_b128 v[138:141], v216 offset:51200
	s_waitcnt lgkmcnt(7)
	v_mfma_f32_16x16x32_bf16 v[18:21], v[196:199], v[142:145], v[18:21]
	v_mfma_f32_16x16x32_bf16 v[22:25], v[204:207], v[142:145], v[22:25]
	ds_read_b128 v[142:145], v216 offset:53248
	s_waitcnt lgkmcnt(7)
	v_mfma_f32_16x16x32_bf16 v[26:29], v[196:199], v[146:149], v[26:29]
	v_mfma_f32_16x16x32_bf16 v[30:33], v[204:207], v[146:149], v[30:33]
	ds_read_b128 v[146:149], v216 offset:55296
	s_waitcnt lgkmcnt(7)
	v_mfma_f32_16x16x32_bf16 v[34:37], v[196:199], v[150:153], v[34:37]
	global_load_dwordx4 v[166:169], v220, s[8:9]
	v_mfma_f32_16x16x32_bf16 v[38:41], v[204:207], v[150:153], v[38:41]
	global_load_dwordx4 v[170:173], v220, s[8:9] offset:1024
	ds_read_b128 v[150:153], v216 offset:57344
	s_waitcnt lgkmcnt(7)
	v_mfma_f32_16x16x32_bf16 v[42:45], v[196:199], v[154:157], v[42:45]
	global_load_dwordx4 v[174:177], v221, s[8:9]
	v_mfma_f32_16x16x32_bf16 v[46:49], v[204:207], v[154:157], v[46:49]
	global_load_dwordx4 v[178:181], v221, s[8:9] offset:1024
	ds_read_b128 v[154:157], v216 offset:59392
	s_waitcnt lgkmcnt(7)
	v_mfma_f32_16x16x32_bf16 v[50:53], v[196:199], v[158:161], v[50:53]
	v_mfma_f32_16x16x32_bf16 v[54:57], v[204:207], v[158:161], v[54:57]
	ds_read_b128 v[158:161], v216 offset:61440
	s_waitcnt lgkmcnt(7)
	v_mfma_f32_16x16x32_bf16 v[58:61], v[196:199], v[162:165], v[58:61]
	v_mfma_f32_16x16x32_bf16 v[62:65], v[204:207], v[162:165], v[62:65]
	ds_read_b128 v[162:165], v216 offset:63488
	s_waitcnt lgkmcnt(7)
	v_mfma_f32_16x16x32_bf16 v[66:69], v[196:199], v[134:137], v[66:69]
	v_mfma_f32_16x16x32_bf16 v[70:73], v[204:207], v[134:137], v[70:73]
	ds_read_b128 v[134:137], v216 offset:33792
	s_waitcnt lgkmcnt(7)
	v_mfma_f32_16x16x32_bf16 v[74:77], v[196:199], v[138:141], v[74:77]
	v_mfma_f32_16x16x32_bf16 v[78:81], v[204:207], v[138:141], v[78:81]
	ds_read_b128 v[138:141], v216 offset:35840
	s_waitcnt lgkmcnt(7)
	v_mfma_f32_16x16x32_bf16 v[82:85], v[196:199], v[142:145], v[82:85]
	v_mfma_f32_16x16x32_bf16 v[86:89], v[204:207], v[142:145], v[86:89]
	ds_read_b128 v[142:145], v216 offset:37888
	s_waitcnt lgkmcnt(7)
	v_mfma_f32_16x16x32_bf16 v[90:93], v[196:199], v[146:149], v[90:93]
	v_mfma_f32_16x16x32_bf16 v[94:97], v[204:207], v[146:149], v[94:97]
	ds_read_b128 v[146:149], v216 offset:39936
	s_waitcnt lgkmcnt(7)
	v_mfma_f32_16x16x32_bf16 v[98:101], v[196:199], v[150:153], v[98:101]
	v_mfma_f32_16x16x32_bf16 v[102:105], v[204:207], v[150:153], v[102:105]
	ds_read_b128 v[150:153], v216 offset:41984
	s_waitcnt lgkmcnt(7)
	v_mfma_f32_16x16x32_bf16 v[106:109], v[196:199], v[154:157], v[106:109]
	v_mfma_f32_16x16x32_bf16 v[110:113], v[204:207], v[154:157], v[110:113]
	ds_read_b128 v[154:157], v216 offset:44032
	s_waitcnt lgkmcnt(7)
	v_mfma_f32_16x16x32_bf16 v[114:117], v[196:199], v[158:161], v[114:117]
	v_mfma_f32_16x16x32_bf16 v[118:121], v[204:207], v[158:161], v[118:121]
	ds_read_b128 v[158:161], v216 offset:46080
	s_waitcnt lgkmcnt(7)
	v_mfma_f32_16x16x32_bf16 v[122:125], v[196:199], v[162:165], v[122:125]
	v_mfma_f32_16x16x32_bf16 v[126:129], v[204:207], v[162:165], v[126:129]
	ds_read_b128 v[162:165], v216 offset:48128
	s_waitcnt lgkmcnt(7)
	v_mfma_f32_16x16x32_bf16 v[2:5], v[200:203], v[134:137], v[2:5]
	v_mfma_f32_16x16x32_bf16 v[6:9], v[212:215], v[134:137], v[6:9]
	ds_read_b128 v[134:137], v216 offset:50176
	s_waitcnt lgkmcnt(7)
	v_mfma_f32_16x16x32_bf16 v[10:13], v[200:203], v[138:141], v[10:13]
	v_mfma_f32_16x16x32_bf16 v[14:17], v[212:215], v[138:141], v[14:17]
	ds_read_b128 v[138:141], v216 offset:52224
	s_waitcnt lgkmcnt(7)
	v_mfma_f32_16x16x32_bf16 v[18:21], v[200:203], v[142:145], v[18:21]
	v_mfma_f32_16x16x32_bf16 v[22:25], v[212:215], v[142:145], v[22:25]
	ds_read_b128 v[142:145], v216 offset:54272
	s_waitcnt lgkmcnt(7)
	v_mfma_f32_16x16x32_bf16 v[26:29], v[200:203], v[146:149], v[26:29]
	v_mfma_f32_16x16x32_bf16 v[30:33], v[212:215], v[146:149], v[30:33]
	ds_read_b128 v[146:149], v216 offset:56320
	s_waitcnt lgkmcnt(7)
	v_mfma_f32_16x16x32_bf16 v[34:37], v[200:203], v[150:153], v[34:37]
	v_mfma_f32_16x16x32_bf16 v[38:41], v[212:215], v[150:153], v[38:41]
	ds_read_b128 v[150:153], v216 offset:58368
	s_waitcnt lgkmcnt(7)
	v_mfma_f32_16x16x32_bf16 v[42:45], v[200:203], v[154:157], v[42:45]
	v_mfma_f32_16x16x32_bf16 v[46:49], v[212:215], v[154:157], v[46:49]
	ds_read_b128 v[154:157], v216 offset:60416
	s_waitcnt lgkmcnt(7)
	v_mfma_f32_16x16x32_bf16 v[50:53], v[200:203], v[158:161], v[50:53]
	v_mfma_f32_16x16x32_bf16 v[54:57], v[212:215], v[158:161], v[54:57]
	ds_read_b128 v[158:161], v216 offset:62464
	s_waitcnt lgkmcnt(7)
	v_mfma_f32_16x16x32_bf16 v[58:61], v[200:203], v[162:165], v[58:61]
	v_mfma_f32_16x16x32_bf16 v[62:65], v[212:215], v[162:165], v[62:65]
	ds_read_b128 v[162:165], v216 offset:64512
	s_waitcnt vmcnt(4) lgkmcnt(0)
	s_barrier
	v_mfma_f32_16x16x32_bf16 v[66:69], v[200:203], v[134:137], v[66:69]
	s_add_u32 m0, s22, 0x8000
	v_mov_b32_e32 v223, v217
	global_load_lds_dwordx4 v223, s[6:7]
	v_mfma_f32_16x16x32_bf16 v[70:73], v[212:215], v[134:137], v[70:73]
	s_add_u32 m0, s22, 0x8400
	v_add_u32_e32 v224, 0x40, v217
	global_load_lds_dwordx4 v224, s[6:7]
	ds_read_b128 v[134:137], v216
	s_waitcnt lgkmcnt(7)
	v_mfma_f32_16x16x32_bf16 v[74:77], v[200:203], v[138:141], v[74:77]
	s_add_u32 m0, s22, 0x8800
	v_add_u32_e32 v223, 0x20000, v217
	global_load_lds_dwordx4 v223, s[6:7]
	v_mfma_f32_16x16x32_bf16 v[78:81], v[212:215], v[138:141], v[78:81]
	s_add_u32 m0, s22, 0x8c00
	v_add_u32_e32 v224, 0x20040, v217
	global_load_lds_dwordx4 v224, s[6:7]
	ds_read_b128 v[138:141], v216 offset:2048
	s_waitcnt lgkmcnt(7)
	v_mfma_f32_16x16x32_bf16 v[82:85], v[200:203], v[142:145], v[82:85]
	s_add_u32 m0, s22, 0x9000
	v_add_u32_e32 v223, 0x40000, v217
	global_load_lds_dwordx4 v223, s[6:7]
	v_mfma_f32_16x16x32_bf16 v[86:89], v[212:215], v[142:145], v[86:89]
	s_add_u32 m0, s22, 0x9400
	v_add_u32_e32 v224, 0x40040, v217
	global_load_lds_dwordx4 v224, s[6:7]
	ds_read_b128 v[142:145], v216 offset:4096
	s_waitcnt lgkmcnt(7)
	v_mfma_f32_16x16x32_bf16 v[90:93], v[200:203], v[146:149], v[90:93]
	s_add_u32 m0, s22, 0x9800
	v_add_u32_e32 v223, 0x60000, v217
	global_load_lds_dwordx4 v223, s[6:7]
	v_mfma_f32_16x16x32_bf16 v[94:97], v[212:215], v[146:149], v[94:97]
	s_add_u32 m0, s22, 0x9c00
	v_add_u32_e32 v224, 0x60040, v217
	global_load_lds_dwordx4 v224, s[6:7]
	ds_read_b128 v[146:149], v216 offset:6144
	s_waitcnt lgkmcnt(7)
	v_mfma_f32_16x16x32_bf16 v[98:101], v[200:203], v[150:153], v[98:101]
	v_mfma_f32_16x16x32_bf16 v[102:105], v[212:215], v[150:153], v[102:105]
	ds_read_b128 v[150:153], v216 offset:8192
	s_waitcnt lgkmcnt(7)
	v_mfma_f32_16x16x32_bf16 v[106:109], v[200:203], v[154:157], v[106:109]
	v_mfma_f32_16x16x32_bf16 v[110:113], v[212:215], v[154:157], v[110:113]
	ds_read_b128 v[154:157], v216 offset:10240
	s_waitcnt lgkmcnt(7)
	v_mfma_f32_16x16x32_bf16 v[114:117], v[200:203], v[158:161], v[114:117]
	v_mfma_f32_16x16x32_bf16 v[118:121], v[212:215], v[158:161], v[118:121]
	ds_read_b128 v[158:161], v216 offset:12288
	s_waitcnt lgkmcnt(7)
	v_mfma_f32_16x16x32_bf16 v[122:125], v[200:203], v[162:165], v[122:125]
	v_mfma_f32_16x16x32_bf16 v[126:129], v[212:215], v[162:165], v[126:129]
	v_add_u32_e32 v217, 0x80, v217
	v_add_u32_e32 v220, 0x800, v220
	v_add_u32_e32 v221, 0x800, v221
	s_sub_u32 s16, s16, 1
	s_cmp_lg_u32 s16, 0
	s_cbranch_scc1 .Lg256b_w2_loop
	s_add_u32 s12, s12, s83
.Lg256b_w2_next_retry:
	s_cmp_ge_u32 s12, 64
	s_cbranch_scc1 .Lg256b_w2_nonext
	s_lshr_b32 s3, s12, 6
	s_lshl_b32 s3, s3, 3
	s_add_u32 s3, s3, s65
	s_mov_b32 s17, s3
	s_mov_b32 s3, 0
	s_lshl_b32 s17, s17, 3
	s_bfe_u32 s23, s12, 0x30003
	s_add_u32 s13, s17, s23
	s_lshl_b32 s3, s3, 3
	s_and_b32 s23, s12, 7
	s_add_u32 s14, s3, s23
	s_lshl_b32 s13, s13, 8
	s_lshl_b32 s14, s14, 7
	s_lshl_b32 s3, s15, 6
	s_add_u32 s17, s3, s13
	s_mul_i32 s17, s17, 0x2000
	s_add_u32 s6, s18, s17
	s_addc_u32 s7, s19, 0
	v_mov_b32_e32 v217, v218
	ds_read_b128 v[162:165], v216 offset:14336
	s_waitcnt vmcnt(8) lgkmcnt(7)
	v_mfma_f32_16x16x32_bf16 v[2:5], v[166:169], v[134:137], v[2:5]
	v_mfma_f32_16x16x32_bf16 v[6:9], v[174:177], v[134:137], v[6:9]
	ds_read_b128 v[134:137], v216 offset:16384
	s_waitcnt lgkmcnt(7)
	v_mfma_f32_16x16x32_bf16 v[10:13], v[166:169], v[138:141], v[10:13]
	v_mfma_f32_16x16x32_bf16 v[14:17], v[174:177], v[138:141], v[14:17]
	ds_read_b128 v[138:141], v216 offset:18432
	s_waitcnt lgkmcnt(7)
	v_mfma_f32_16x16x32_bf16 v[18:21], v[166:169], v[142:145], v[18:21]
	v_mfma_f32_16x16x32_bf16 v[22:25], v[174:177], v[142:145], v[22:25]
	ds_read_b128 v[142:145], v216 offset:20480
	s_waitcnt lgkmcnt(7)
	v_mfma_f32_16x16x32_bf16 v[26:29], v[166:169], v[146:149], v[26:29]
	v_mfma_f32_16x16x32_bf16 v[30:33], v[174:177], v[146:149], v[30:33]
	ds_read_b128 v[146:149], v216 offset:22528
	s_waitcnt lgkmcnt(7)
	v_mfma_f32_16x16x32_bf16 v[34:37], v[166:169], v[150:153], v[34:37]
	global_load_dwordx4 v[196:199], v220, s[8:9]
	v_mfma_f32_16x16x32_bf16 v[38:41], v[174:177], v[150:153], v[38:41]
	global_load_dwordx4 v[200:203], v220, s[8:9] offset:1024
	ds_read_b128 v[150:153], v216 offset:24576
	s_waitcnt lgkmcnt(7)
	v_mfma_f32_16x16x32_bf16 v[42:45], v[166:169], v[154:157], v[42:45]
	global_load_dwordx4 v[204:207], v221, s[8:9]
	v_mfma_f32_16x16x32_bf16 v[46:49], v[174:177], v[154:157], v[46:49]
	global_load_dwordx4 v[212:215], v221, s[8:9] offset:1024
	ds_read_b128 v[154:157], v216 offset:26624
	s_waitcnt lgkmcnt(7)
	v_mfma_f32_16x16x32_bf16 v[50:53], v[166:169], v[158:161], v[50:53]
	v_mfma_f32_16x16x32_bf16 v[54:57], v[174:177], v[158:161], v[54:57]
	ds_read_b128 v[158:161], v216 offset:28672
	s_waitcnt lgkmcnt(7)
	v_mfma_f32_16x16x32_bf16 v[58:61], v[166:169], v[162:165], v[58:61]
	v_mfma_f32_16x16x32_bf16 v[62:65], v[174:177], v[162:165], v[62:65]
	ds_read_b128 v[162:165], v216 offset:30720
	s_waitcnt lgkmcnt(7)
	v_mfma_f32_16x16x32_bf16 v[66:69], v[166:169], v[134:137], v[66:69]
	v_mfma_f32_16x16x32_bf16 v[70:73], v[174:177], v[134:137], v[70:73]
	ds_read_b128 v[134:137], v216 offset:1024
	s_waitcnt lgkmcnt(7)
	v_mfma_f32_16x16x32_bf16 v[74:77], v[166:169], v[138:141], v[74:77]
	v_mfma_f32_16x16x32_bf16 v[78:81], v[174:177], v[138:141], v[78:81]
	ds_read_b128 v[138:141], v216 offset:3072
	s_waitcnt lgkmcnt(7)
	v_mfma_f32_16x16x32_bf16 v[82:85], v[166:169], v[142:145], v[82:85]
	v_mfma_f32_16x16x32_bf16 v[86:89], v[174:177], v[142:145], v[86:89]
	ds_read_b128 v[142:145], v216 offset:5120
	s_waitcnt lgkmcnt(7)
	v_mfma_f32_16x16x32_bf16 v[90:93], v[166:169], v[146:149], v[90:93]
	v_mfma_f32_16x16x32_bf16 v[94:97], v[174:177], v[146:149], v[94:97]
	ds_read_b128 v[146:149], v216 offset:7168
	s_waitcnt lgkmcnt(7)
	v_mfma_f32_16x16x32_bf16 v[98:101], v[166:169], v[150:153], v[98:101]
	v_mfma_f32_16x16x32_bf16 v[102:105], v[174:177], v[150:153], v[102:105]
	ds_read_b128 v[150:153], v216 offset:9216
	s_waitcnt lgkmcnt(7)
	v_mfma_f32_16x16x32_bf16 v[106:109], v[166:169], v[154:157], v[106:109]
	v_mfma_f32_16x16x32_bf16 v[110:113], v[174:177], v[154:157], v[110:113]
	ds_read_b128 v[154:157], v216 offset:11264
	s_waitcnt lgkmcnt(7)
	v_mfma_f32_16x16x32_bf16 v[114:117], v[166:169], v[158:161], v[114:117]
	v_mfma_f32_16x16x32_bf16 v[118:121], v[174:177], v[158:161], v[118:121]
	ds_read_b128 v[158:161], v216 offset:13312
	s_waitcnt lgkmcnt(7)
	v_mfma_f32_16x16x32_bf16 v[122:125], v[166:169], v[162:165], v[122:125]
	v_mfma_f32_16x16x32_bf16 v[126:129], v[174:177], v[162:165], v[126:129]
	ds_read_b128 v[162:165], v216 offset:15360
	s_waitcnt lgkmcnt(7)
	v_mfma_f32_16x16x32_bf16 v[2:5], v[170:173], v[134:137], v[2:5]
	v_mfma_f32_16x16x32_bf16 v[6:9], v[178:181], v[134:137], v[6:9]
	ds_read_b128 v[134:137], v216 offset:17408
	s_waitcnt lgkmcnt(7)
	v_mfma_f32_16x16x32_bf16 v[10:13], v[170:173], v[138:141], v[10:13]
	v_mfma_f32_16x16x32_bf16 v[14:17], v[178:181], v[138:141], v[14:17]
	ds_read_b128 v[138:141], v216 offset:19456
	s_waitcnt lgkmcnt(7)
	v_mfma_f32_16x16x32_bf16 v[18:21], v[170:173], v[142:145], v[18:21]
	v_mfma_f32_16x16x32_bf16 v[22:25], v[178:181], v[142:145], v[22:25]
	ds_read_b128 v[142:145], v216 offset:21504
	s_waitcnt lgkmcnt(7)
	v_mfma_f32_16x16x32_bf16 v[26:29], v[170:173], v[146:149], v[26:29]
	v_mfma_f32_16x16x32_bf16 v[30:33], v[178:181], v[146:149], v[30:33]
	ds_read_b128 v[146:149], v216 offset:23552
	s_waitcnt lgkmcnt(7)
	v_mfma_f32_16x16x32_bf16 v[34:37], v[170:173], v[150:153], v[34:37]
	v_mfma_f32_16x16x32_bf16 v[38:41], v[178:181], v[150:153], v[38:41]
	ds_read_b128 v[150:153], v216 offset:25600
	s_waitcnt lgkmcnt(7)
	v_mfma_f32_16x16x32_bf16 v[42:45], v[170:173], v[154:157], v[42:45]
	v_mfma_f32_16x16x32_bf16 v[46:49], v[178:181], v[154:157], v[46:49]
	ds_read_b128 v[154:157], v216 offset:27648
	s_waitcnt lgkmcnt(7)
	v_mfma_f32_16x16x32_bf16 v[50:53], v[170:173], v[158:161], v[50:53]
	v_mfma_f32_16x16x32_bf16 v[54:57], v[178:181], v[158:161], v[54:57]
	ds_read_b128 v[158:161], v216 offset:29696
	s_waitcnt lgkmcnt(7)
	v_mfma_f32_16x16x32_bf16 v[58:61], v[170:173], v[162:165], v[58:61]
	v_mfma_f32_16x16x32_bf16 v[62:65], v[178:181], v[162:165], v[62:65]
	ds_read_b128 v[162:165], v216 offset:31744
	s_waitcnt vmcnt(4) lgkmcnt(0)
	s_barrier
	v_mfma_f32_16x16x32_bf16 v[66:69], v[170:173], v[134:137], v[66:69]
	s_add_u32 m0, s22, 0x0
	v_mov_b32_e32 v223, v217
	global_load_lds_dwordx4 v223, s[6:7]
	v_mfma_f32_16x16x32_bf16 v[70:73], v[178:181], v[134:137], v[70:73]
	s_add_u32 m0, s22, 0x400
	v_add_u32_e32 v224, 0x40, v217
	global_load_lds_dwordx4 v224, s[6:7]
	ds_read_b128 v[134:137], v216 offset:32768
	s_waitcnt lgkmcnt(7)
	v_mfma_f32_16x16x32_bf16 v[74:77], v[170:173], v[138:141], v[74:77]
	s_add_u32 m0, s22, 0x800
	v_add_u32_e32 v223, 0x20000, v217
	global_load_lds_dwordx4 v223, s[6:7]
	v_mfma_f32_16x16x32_bf16 v[78:81], v[178:181], v[138:141], v[78:81]
	s_add_u32 m0, s22, 0xc00
	v_add_u32_e32 v224, 0x20040, v217
	global_load_lds_dwordx4 v224, s[6:7]
	ds_read_b128 v[138:141], v216 offset:34816
	s_waitcnt lgkmcnt(7)
	v_mfma_f32_16x16x32_bf16 v[82:85], v[170:173], v[142:145], v[82:85]
	s_add_u32 m0, s22, 0x1000
	v_add_u32_e32 v223, 0x40000, v217
	global_load_lds_dwordx4 v223, s[6:7]
	v_mfma_f32_16x16x32_bf16 v[86:89], v[178:181], v[142:145], v[86:89]
	s_add_u32 m0, s22, 0x1400
	v_add_u32_e32 v224, 0x40040, v217
	global_load_lds_dwordx4 v224, s[6:7]
	ds_read_b128 v[142:145], v216 offset:36864
	s_waitcnt lgkmcnt(7)
	v_mfma_f32_16x16x32_bf16 v[90:93], v[170:173], v[146:149], v[90:93]
	s_add_u32 m0, s22, 0x1800
	v_add_u32_e32 v223, 0x60000, v217
	global_load_lds_dwordx4 v223, s[6:7]
	v_mfma_f32_16x16x32_bf16 v[94:97], v[178:181], v[146:149], v[94:97]
	s_add_u32 m0, s22, 0x1c00
	v_add_u32_e32 v224, 0x60040, v217
	global_load_lds_dwordx4 v224, s[6:7]
	ds_read_b128 v[146:149], v216 offset:38912
	s_waitcnt lgkmcnt(7)
	v_mfma_f32_16x16x32_bf16 v[98:101], v[170:173], v[150:153], v[98:101]
	v_mfma_f32_16x16x32_bf16 v[102:105], v[178:181], v[150:153], v[102:105]
	ds_read_b128 v[150:153], v216 offset:40960
	s_waitcnt lgkmcnt(7)
	v_mfma_f32_16x16x32_bf16 v[106:109], v[170:173], v[154:157], v[106:109]
	v_mfma_f32_16x16x32_bf16 v[110:113], v[178:181], v[154:157], v[110:113]
	ds_read_b128 v[154:157], v216 offset:43008
	s_waitcnt lgkmcnt(7)
	v_mfma_f32_16x16x32_bf16 v[114:117], v[170:173], v[158:161], v[114:117]
	v_mfma_f32_16x16x32_bf16 v[118:121], v[178:181], v[158:161], v[118:121]
	ds_read_b128 v[158:161], v216 offset:45056
	s_waitcnt lgkmcnt(7)
	v_mfma_f32_16x16x32_bf16 v[122:125], v[170:173], v[162:165], v[122:125]
	v_mfma_f32_16x16x32_bf16 v[126:129], v[178:181], v[162:165], v[126:129]
	v_add_u32_e32 v217, 0x80, v217
	v_add_u32_e32 v220, 0x800, v220
	v_add_u32_e32 v221, 0x800, v221
	s_lshr_b32 s3, s14, 4
	s_lshl_b32 s17, s15, 1
	s_add_u32 s3, s3, s17
	s_mul_i32 s17, s3, 0x20000
	s_add_u32 s8, s20, s17
	s_addc_u32 s9, s21, 0
	v_mov_b32_e32 v220, v222
	v_add_u32_e32 v221, 0x20000, v222
	ds_read_b128 v[162:165], v216 offset:47104
	s_waitcnt vmcnt(8) lgkmcnt(7)
	v_mfma_f32_16x16x32_bf16 v[2:5], v[196:199], v[134:137], v[2:5]
	v_mfma_f32_16x16x32_bf16 v[6:9], v[204:207], v[134:137], v[6:9]
	ds_read_b128 v[134:137], v216 offset:49152
	s_waitcnt lgkmcnt(7)
	v_mfma_f32_16x16x32_bf16 v[10:13], v[196:199], v[138:141], v[10:13]
	v_mfma_f32_16x16x32_bf16 v[14:17], v[204:207], v[138:141], v[14:17]
	ds_read_b128 v[138:141], v216 offset:51200
	s_waitcnt lgkmcnt(7)
	v_mfma_f32_16x16x32_bf16 v[18:21], v[196:199], v[142:145], v[18:21]
	v_mfma_f32_16x16x32_bf16 v[22:25], v[204:207], v[142:145], v[22:25]
	ds_read_b128 v[142:145], v216 offset:53248
	s_waitcnt lgkmcnt(7)
	v_mfma_f32_16x16x32_bf16 v[26:29], v[196:199], v[146:149], v[26:29]
	v_mfma_f32_16x16x32_bf16 v[30:33], v[204:207], v[146:149], v[30:33]
	ds_read_b128 v[146:149], v216 offset:55296
	s_waitcnt lgkmcnt(7)
	v_mfma_f32_16x16x32_bf16 v[34:37], v[196:199], v[150:153], v[34:37]
	global_load_dwordx4 v[166:169], v220, s[8:9]
	v_mfma_f32_16x16x32_bf16 v[38:41], v[204:207], v[150:153], v[38:41]
	global_load_dwordx4 v[170:173], v220, s[8:9] offset:1024
	ds_read_b128 v[150:153], v216 offset:57344
	s_waitcnt lgkmcnt(7)
	v_mfma_f32_16x16x32_bf16 v[42:45], v[196:199], v[154:157], v[42:45]
	global_load_dwordx4 v[174:177], v221, s[8:9]
	v_mfma_f32_16x16x32_bf16 v[46:49], v[204:207], v[154:157], v[46:49]
	global_load_dwordx4 v[178:181], v221, s[8:9] offset:1024
	ds_read_b128 v[154:157], v216 offset:59392
	s_waitcnt lgkmcnt(7)
	v_mfma_f32_16x16x32_bf16 v[50:53], v[196:199], v[158:161], v[50:53]
	v_mfma_f32_16x16x32_bf16 v[54:57], v[204:207], v[158:161], v[54:57]
	ds_read_b128 v[158:161], v216 offset:61440
	s_waitcnt lgkmcnt(7)
	v_mfma_f32_16x16x32_bf16 v[58:61], v[196:199], v[162:165], v[58:61]
	v_mfma_f32_16x16x32_bf16 v[62:65], v[204:207], v[162:165], v[62:65]
	ds_read_b128 v[162:165], v216 offset:63488
	s_waitcnt lgkmcnt(7)
	v_mfma_f32_16x16x32_bf16 v[66:69], v[196:199], v[134:137], v[66:69]
	v_mfma_f32_16x16x32_bf16 v[70:73], v[204:207], v[134:137], v[70:73]
	ds_read_b128 v[134:137], v216 offset:33792
	s_waitcnt lgkmcnt(7)
	v_mfma_f32_16x16x32_bf16 v[74:77], v[196:199], v[138:141], v[74:77]
	v_mfma_f32_16x16x32_bf16 v[78:81], v[204:207], v[138:141], v[78:81]
	ds_read_b128 v[138:141], v216 offset:35840
	s_waitcnt lgkmcnt(7)
	v_mfma_f32_16x16x32_bf16 v[82:85], v[196:199], v[142:145], v[82:85]
	v_mfma_f32_16x16x32_bf16 v[86:89], v[204:207], v[142:145], v[86:89]
	ds_read_b128 v[142:145], v216 offset:37888
	s_waitcnt lgkmcnt(7)
	v_mfma_f32_16x16x32_bf16 v[90:93], v[196:199], v[146:149], v[90:93]
	v_mfma_f32_16x16x32_bf16 v[94:97], v[204:207], v[146:149], v[94:97]
	ds_read_b128 v[146:149], v216 offset:39936
	s_waitcnt lgkmcnt(7)
	v_mfma_f32_16x16x32_bf16 v[98:101], v[196:199], v[150:153], v[98:101]
	v_mfma_f32_16x16x32_bf16 v[102:105], v[204:207], v[150:153], v[102:105]
	ds_read_b128 v[150:153], v216 offset:41984
	s_waitcnt lgkmcnt(7)
	v_mfma_f32_16x16x32_bf16 v[106:109], v[196:199], v[154:157], v[106:109]
	v_mfma_f32_16x16x32_bf16 v[110:113], v[204:207], v[154:157], v[110:113]
	ds_read_b128 v[154:157], v216 offset:44032
	s_waitcnt lgkmcnt(7)
	v_mfma_f32_16x16x32_bf16 v[114:117], v[196:199], v[158:161], v[114:117]
	v_mfma_f32_16x16x32_bf16 v[118:121], v[204:207], v[158:161], v[118:121]
	ds_read_b128 v[158:161], v216 offset:46080
	s_waitcnt lgkmcnt(7)
	v_mfma_f32_16x16x32_bf16 v[122:125], v[196:199], v[162:165], v[122:125]
	v_mfma_f32_16x16x32_bf16 v[126:129], v[204:207], v[162:165], v[126:129]
	ds_read_b128 v[162:165], v216 offset:48128
	s_waitcnt lgkmcnt(7)
	v_mfma_f32_16x16x32_bf16 v[2:5], v[200:203], v[134:137], v[2:5]
	v_mfma_f32_16x16x32_bf16 v[6:9], v[212:215], v[134:137], v[6:9]
	ds_read_b128 v[134:137], v216 offset:50176
	s_waitcnt lgkmcnt(7)
	v_mfma_f32_16x16x32_bf16 v[10:13], v[200:203], v[138:141], v[10:13]
	v_mfma_f32_16x16x32_bf16 v[14:17], v[212:215], v[138:141], v[14:17]
	ds_read_b128 v[138:141], v216 offset:52224
	s_waitcnt lgkmcnt(7)
	v_mfma_f32_16x16x32_bf16 v[18:21], v[200:203], v[142:145], v[18:21]
	v_mfma_f32_16x16x32_bf16 v[22:25], v[212:215], v[142:145], v[22:25]
	ds_read_b128 v[142:145], v216 offset:54272
	s_waitcnt lgkmcnt(7)
	v_mfma_f32_16x16x32_bf16 v[26:29], v[200:203], v[146:149], v[26:29]
	v_mfma_f32_16x16x32_bf16 v[30:33], v[212:215], v[146:149], v[30:33]
	ds_read_b128 v[146:149], v216 offset:56320
	s_waitcnt lgkmcnt(7)
	v_mfma_f32_16x16x32_bf16 v[34:37], v[200:203], v[150:153], v[34:37]
	v_mfma_f32_16x16x32_bf16 v[38:41], v[212:215], v[150:153], v[38:41]
	ds_read_b128 v[150:153], v216 offset:58368
	s_waitcnt lgkmcnt(7)
	v_mfma_f32_16x16x32_bf16 v[42:45], v[200:203], v[154:157], v[42:45]
	v_mfma_f32_16x16x32_bf16 v[46:49], v[212:215], v[154:157], v[46:49]
	ds_read_b128 v[154:157], v216 offset:60416
	s_waitcnt lgkmcnt(7)
	v_mfma_f32_16x16x32_bf16 v[50:53], v[200:203], v[158:161], v[50:53]
	v_mfma_f32_16x16x32_bf16 v[54:57], v[212:215], v[158:161], v[54:57]
	ds_read_b128 v[158:161], v216 offset:62464
	s_waitcnt lgkmcnt(7)
	v_mfma_f32_16x16x32_bf16 v[58:61], v[200:203], v[162:165], v[58:61]
	v_mfma_f32_16x16x32_bf16 v[62:65], v[212:215], v[162:165], v[62:65]
	ds_read_b128 v[162:165], v216 offset:64512
	s_waitcnt vmcnt(4) lgkmcnt(0)
	s_barrier
	v_mfma_f32_16x16x32_bf16 v[66:69], v[200:203], v[134:137], v[66:69]
	s_add_u32 m0, s22, 0x8000
	v_mov_b32_e32 v223, v217
	global_load_lds_dwordx4 v223, s[6:7]
	v_mfma_f32_16x16x32_bf16 v[70:73], v[212:215], v[134:137], v[70:73]
	s_add_u32 m0, s22, 0x8400
	v_add_u32_e32 v224, 0x40, v217
	global_load_lds_dwordx4 v224, s[6:7]
	ds_read_b128 v[134:137], v216
	s_waitcnt lgkmcnt(7)
	v_mfma_f32_16x16x32_bf16 v[74:77], v[200:203], v[138:141], v[74:77]
	s_add_u32 m0, s22, 0x8800
	v_add_u32_e32 v223, 0x20000, v217
	global_load_lds_dwordx4 v223, s[6:7]
	v_mfma_f32_16x16x32_bf16 v[78:81], v[212:215], v[138:141], v[78:81]
	s_add_u32 m0, s22, 0x8c00
	v_add_u32_e32 v224, 0x20040, v217
	global_load_lds_dwordx4 v224, s[6:7]
	ds_read_b128 v[138:141], v216 offset:2048
	s_waitcnt lgkmcnt(7)
	v_mfma_f32_16x16x32_bf16 v[82:85], v[200:203], v[142:145], v[82:85]
	s_add_u32 m0, s22, 0x9000
	v_add_u32_e32 v223, 0x40000, v217
	global_load_lds_dwordx4 v223, s[6:7]
	v_mfma_f32_16x16x32_bf16 v[86:89], v[212:215], v[142:145], v[86:89]
	s_add_u32 m0, s22, 0x9400
	v_add_u32_e32 v224, 0x40040, v217
	global_load_lds_dwordx4 v224, s[6:7]
	ds_read_b128 v[142:145], v216 offset:4096
	s_waitcnt lgkmcnt(7)
	v_mfma_f32_16x16x32_bf16 v[90:93], v[200:203], v[146:149], v[90:93]
	s_add_u32 m0, s22, 0x9800
	v_add_u32_e32 v223, 0x60000, v217
	global_load_lds_dwordx4 v223, s[6:7]
	v_mfma_f32_16x16x32_bf16 v[94:97], v[212:215], v[146:149], v[94:97]
	s_add_u32 m0, s22, 0x9c00
	v_add_u32_e32 v224, 0x60040, v217
	global_load_lds_dwordx4 v224, s[6:7]
	ds_read_b128 v[146:149], v216 offset:6144
	s_waitcnt lgkmcnt(7)
	v_mfma_f32_16x16x32_bf16 v[98:101], v[200:203], v[150:153], v[98:101]
	v_mfma_f32_16x16x32_bf16 v[102:105], v[212:215], v[150:153], v[102:105]
	ds_read_b128 v[150:153], v216 offset:8192
	s_waitcnt lgkmcnt(7)
	v_mfma_f32_16x16x32_bf16 v[106:109], v[200:203], v[154:157], v[106:109]
	v_mfma_f32_16x16x32_bf16 v[110:113], v[212:215], v[154:157], v[110:113]
	ds_read_b128 v[154:157], v216 offset:10240
	s_waitcnt lgkmcnt(7)
	v_mfma_f32_16x16x32_bf16 v[114:117], v[200:203], v[158:161], v[114:117]
	v_mfma_f32_16x16x32_bf16 v[118:121], v[212:215], v[158:161], v[118:121]
	ds_read_b128 v[158:161], v216 offset:12288
	s_waitcnt lgkmcnt(7)
	v_mfma_f32_16x16x32_bf16 v[122:125], v[200:203], v[162:165], v[122:125]
	v_mfma_f32_16x16x32_bf16 v[126:129], v[212:215], v[162:165], v[126:129]
	v_add_u32_e32 v217, 0x80, v217
	v_add_u32_e32 v220, 0x800, v220
	v_add_u32_e32 v221, 0x800, v221
	s_mov_b32 s16, 1
	s_branch .Lg256b_w2_epi
.Lg256b_w2_nonext:
	ds_read_b128 v[162:165], v216 offset:14336
	s_waitcnt vmcnt(8) lgkmcnt(7)
	v_mfma_f32_16x16x32_bf16 v[2:5], v[166:169], v[134:137], v[2:5]
	v_mfma_f32_16x16x32_bf16 v[6:9], v[174:177], v[134:137], v[6:9]
	ds_read_b128 v[134:137], v216 offset:16384
	s_waitcnt lgkmcnt(7)
	v_mfma_f32_16x16x32_bf16 v[10:13], v[166:169], v[138:141], v[10:13]
	v_mfma_f32_16x16x32_bf16 v[14:17], v[174:177], v[138:141], v[14:17]
	ds_read_b128 v[138:141], v216 offset:18432
	s_waitcnt lgkmcnt(7)
	v_mfma_f32_16x16x32_bf16 v[18:21], v[166:169], v[142:145], v[18:21]
	v_mfma_f32_16x16x32_bf16 v[22:25], v[174:177], v[142:145], v[22:25]
	ds_read_b128 v[142:145], v216 offset:20480
	s_waitcnt lgkmcnt(7)
	v_mfma_f32_16x16x32_bf16 v[26:29], v[166:169], v[146:149], v[26:29]
	v_mfma_f32_16x16x32_bf16 v[30:33], v[174:177], v[146:149], v[30:33]
	ds_read_b128 v[146:149], v216 offset:22528
	s_waitcnt lgkmcnt(7)
	v_mfma_f32_16x16x32_bf16 v[34:37], v[166:169], v[150:153], v[34:37]
	global_load_dwordx4 v[196:199], v220, s[8:9]
	v_mfma_f32_16x16x32_bf16 v[38:41], v[174:177], v[150:153], v[38:41]
	global_load_dwordx4 v[200:203], v220, s[8:9] offset:1024
	ds_read_b128 v[150:153], v216 offset:24576
	s_waitcnt lgkmcnt(7)
	v_mfma_f32_16x16x32_bf16 v[42:45], v[166:169], v[154:157], v[42:45]
	global_load_dwordx4 v[204:207], v221, s[8:9]
	v_mfma_f32_16x16x32_bf16 v[46:49], v[174:177], v[154:157], v[46:49]
	global_load_dwordx4 v[212:215], v221, s[8:9] offset:1024
	ds_read_b128 v[154:157], v216 offset:26624
	s_waitcnt lgkmcnt(7)
	v_mfma_f32_16x16x32_bf16 v[50:53], v[166:169], v[158:161], v[50:53]
	v_mfma_f32_16x16x32_bf16 v[54:57], v[174:177], v[158:161], v[54:57]
	ds_read_b128 v[158:161], v216 offset:28672
	s_waitcnt lgkmcnt(7)
	v_mfma_f32_16x16x32_bf16 v[58:61], v[166:169], v[162:165], v[58:61]
	v_mfma_f32_16x16x32_bf16 v[62:65], v[174:177], v[162:165], v[62:65]
	ds_read_b128 v[162:165], v216 offset:30720
	s_waitcnt lgkmcnt(7)
	v_mfma_f32_16x16x32_bf16 v[66:69], v[166:169], v[134:137], v[66:69]
	v_mfma_f32_16x16x32_bf16 v[70:73], v[174:177], v[134:137], v[70:73]
	ds_read_b128 v[134:137], v216 offset:1024
	s_waitcnt lgkmcnt(7)
	v_mfma_f32_16x16x32_bf16 v[74:77], v[166:169], v[138:141], v[74:77]
	v_mfma_f32_16x16x32_bf16 v[78:81], v[174:177], v[138:141], v[78:81]
	ds_read_b128 v[138:141], v216 offset:3072
	s_waitcnt lgkmcnt(7)
	v_mfma_f32_16x16x32_bf16 v[82:85], v[166:169], v[142:145], v[82:85]
	v_mfma_f32_16x16x32_bf16 v[86:89], v[174:177], v[142:145], v[86:89]
	ds_read_b128 v[142:145], v216 offset:5120
	s_waitcnt lgkmcnt(7)
	v_mfma_f32_16x16x32_bf16 v[90:93], v[166:169], v[146:149], v[90:93]
	v_mfma_f32_16x16x32_bf16 v[94:97], v[174:177], v[146:149], v[94:97]
	ds_read_b128 v[146:149], v216 offset:7168
	s_waitcnt lgkmcnt(7)
	v_mfma_f32_16x16x32_bf16 v[98:101], v[166:169], v[150:153], v[98:101]
	v_mfma_f32_16x16x32_bf16 v[102:105], v[174:177], v[150:153], v[102:105]
	ds_read_b128 v[150:153], v216 offset:9216
	s_waitcnt lgkmcnt(7)
	v_mfma_f32_16x16x32_bf16 v[106:109], v[166:169], v[154:157], v[106:109]
	v_mfma_f32_16x16x32_bf16 v[110:113], v[174:177], v[154:157], v[110:113]
	ds_read_b128 v[154:157], v216 offset:11264
	s_waitcnt lgkmcnt(7)
	v_mfma_f32_16x16x32_bf16 v[114:117], v[166:169], v[158:161], v[114:117]
	v_mfma_f32_16x16x32_bf16 v[118:121], v[174:177], v[158:161], v[118:121]
	ds_read_b128 v[158:161], v216 offset:13312
	s_waitcnt lgkmcnt(7)
	v_mfma_f32_16x16x32_bf16 v[122:125], v[166:169], v[162:165], v[122:125]
	v_mfma_f32_16x16x32_bf16 v[126:129], v[174:177], v[162:165], v[126:129]
	ds_read_b128 v[162:165], v216 offset:15360
	s_waitcnt lgkmcnt(7)
	v_mfma_f32_16x16x32_bf16 v[2:5], v[170:173], v[134:137], v[2:5]
	v_mfma_f32_16x16x32_bf16 v[6:9], v[178:181], v[134:137], v[6:9]
	ds_read_b128 v[134:137], v216 offset:17408
	s_waitcnt lgkmcnt(7)
	v_mfma_f32_16x16x32_bf16 v[10:13], v[170:173], v[138:141], v[10:13]
	v_mfma_f32_16x16x32_bf16 v[14:17], v[178:181], v[138:141], v[14:17]
	ds_read_b128 v[138:141], v216 offset:19456
	s_waitcnt lgkmcnt(7)
	v_mfma_f32_16x16x32_bf16 v[18:21], v[170:173], v[142:145], v[18:21]
	v_mfma_f32_16x16x32_bf16 v[22:25], v[178:181], v[142:145], v[22:25]
	ds_read_b128 v[142:145], v216 offset:21504
	s_waitcnt lgkmcnt(7)
	v_mfma_f32_16x16x32_bf16 v[26:29], v[170:173], v[146:149], v[26:29]
	v_mfma_f32_16x16x32_bf16 v[30:33], v[178:181], v[146:149], v[30:33]
	ds_read_b128 v[146:149], v216 offset:23552
	s_waitcnt lgkmcnt(7)
	v_mfma_f32_16x16x32_bf16 v[34:37], v[170:173], v[150:153], v[34:37]
	v_mfma_f32_16x16x32_bf16 v[38:41], v[178:181], v[150:153], v[38:41]
	ds_read_b128 v[150:153], v216 offset:25600
	s_waitcnt lgkmcnt(7)
	v_mfma_f32_16x16x32_bf16 v[42:45], v[170:173], v[154:157], v[42:45]
	v_mfma_f32_16x16x32_bf16 v[46:49], v[178:181], v[154:157], v[46:49]
	ds_read_b128 v[154:157], v216 offset:27648
	s_waitcnt lgkmcnt(7)
	v_mfma_f32_16x16x32_bf16 v[50:53], v[170:173], v[158:161], v[50:53]
	v_mfma_f32_16x16x32_bf16 v[54:57], v[178:181], v[158:161], v[54:57]
	ds_read_b128 v[158:161], v216 offset:29696
	s_waitcnt lgkmcnt(7)
	v_mfma_f32_16x16x32_bf16 v[58:61], v[170:173], v[162:165], v[58:61]
	v_mfma_f32_16x16x32_bf16 v[62:65], v[178:181], v[162:165], v[62:65]
	ds_read_b128 v[162:165], v216 offset:31744
	s_waitcnt vmcnt(4) lgkmcnt(0)
	s_barrier
	v_mfma_f32_16x16x32_bf16 v[66:69], v[170:173], v[134:137], v[66:69]
	v_mfma_f32_16x16x32_bf16 v[70:73], v[178:181], v[134:137], v[70:73]
	ds_read_b128 v[134:137], v216 offset:32768
	s_waitcnt lgkmcnt(7)
	v_mfma_f32_16x16x32_bf16 v[74:77], v[170:173], v[138:141], v[74:77]
	v_mfma_f32_16x16x32_bf16 v[78:81], v[178:181], v[138:141], v[78:81]
	ds_read_b128 v[138:141], v216 offset:34816
	s_waitcnt lgkmcnt(7)
	v_mfma_f32_16x16x32_bf16 v[82:85], v[170:173], v[142:145], v[82:85]
	v_mfma_f32_16x16x32_bf16 v[86:89], v[178:181], v[142:145], v[86:89]
	ds_read_b128 v[142:145], v216 offset:36864
	s_waitcnt lgkmcnt(7)
	v_mfma_f32_16x16x32_bf16 v[90:93], v[170:173], v[146:149], v[90:93]
	v_mfma_f32_16x16x32_bf16 v[94:97], v[178:181], v[146:149], v[94:97]
	ds_read_b128 v[146:149], v216 offset:38912
	s_waitcnt lgkmcnt(7)
	v_mfma_f32_16x16x32_bf16 v[98:101], v[170:173], v[150:153], v[98:101]
	v_mfma_f32_16x16x32_bf16 v[102:105], v[178:181], v[150:153], v[102:105]
	ds_read_b128 v[150:153], v216 offset:40960
	s_waitcnt lgkmcnt(7)
	v_mfma_f32_16x16x32_bf16 v[106:109], v[170:173], v[154:157], v[106:109]
	v_mfma_f32_16x16x32_bf16 v[110:113], v[178:181], v[154:157], v[110:113]
	ds_read_b128 v[154:157], v216 offset:43008
	s_waitcnt lgkmcnt(7)
	v_mfma_f32_16x16x32_bf16 v[114:117], v[170:173], v[158:161], v[114:117]
	v_mfma_f32_16x16x32_bf16 v[118:121], v[178:181], v[158:161], v[118:121]
	ds_read_b128 v[158:161], v216 offset:45056
	s_waitcnt lgkmcnt(7)
	v_mfma_f32_16x16x32_bf16 v[122:125], v[170:173], v[162:165], v[122:125]
	v_mfma_f32_16x16x32_bf16 v[126:129], v[178:181], v[162:165], v[126:129]
	v_add_u32_e32 v220, 0x800, v220
	v_add_u32_e32 v221, 0x800, v221
	ds_read_b128 v[162:165], v216 offset:47104
	s_waitcnt vmcnt(0) lgkmcnt(7)
	v_mfma_f32_16x16x32_bf16 v[2:5], v[196:199], v[134:137], v[2:5]
	v_mfma_f32_16x16x32_bf16 v[6:9], v[204:207], v[134:137], v[6:9]
	ds_read_b128 v[134:137], v216 offset:49152
	s_waitcnt lgkmcnt(7)
	v_mfma_f32_16x16x32_bf16 v[10:13], v[196:199], v[138:141], v[10:13]
	v_mfma_f32_16x16x32_bf16 v[14:17], v[204:207], v[138:141], v[14:17]
	ds_read_b128 v[138:141], v216 offset:51200
	s_waitcnt lgkmcnt(7)
	v_mfma_f32_16x16x32_bf16 v[18:21], v[196:199], v[142:145], v[18:21]
	v_mfma_f32_16x16x32_bf16 v[22:25], v[204:207], v[142:145], v[22:25]
	ds_read_b128 v[142:145], v216 offset:53248
	s_waitcnt lgkmcnt(7)
	v_mfma_f32_16x16x32_bf16 v[26:29], v[196:199], v[146:149], v[26:29]
	v_mfma_f32_16x16x32_bf16 v[30:33], v[204:207], v[146:149], v[30:33]
	ds_read_b128 v[146:149], v216 offset:55296
	s_waitcnt lgkmcnt(7)
	v_mfma_f32_16x16x32_bf16 v[34:37], v[196:199], v[150:153], v[34:37]
	v_mfma_f32_16x16x32_bf16 v[38:41], v[204:207], v[150:153], v[38:41]
	ds_read_b128 v[150:153], v216 offset:57344
	s_waitcnt lgkmcnt(7)
	v_mfma_f32_16x16x32_bf16 v[42:45], v[196:199], v[154:157], v[42:45]
	v_mfma_f32_16x16x32_bf16 v[46:49], v[204:207], v[154:157], v[46:49]
	ds_read_b128 v[154:157], v216 offset:59392
	s_waitcnt lgkmcnt(7)
	v_mfma_f32_16x16x32_bf16 v[50:53], v[196:199], v[158:161], v[50:53]
	v_mfma_f32_16x16x32_bf16 v[54:57], v[204:207], v[158:161], v[54:57]
	ds_read_b128 v[158:161], v216 offset:61440
	s_waitcnt lgkmcnt(7)
	v_mfma_f32_16x16x32_bf16 v[58:61], v[196:199], v[162:165], v[58:61]
	v_mfma_f32_16x16x32_bf16 v[62:65], v[204:207], v[162:165], v[62:65]
	ds_read_b128 v[162:165], v216 offset:63488
	s_waitcnt lgkmcnt(7)
	v_mfma_f32_16x16x32_bf16 v[66:69], v[196:199], v[134:137], v[66:69]
	v_mfma_f32_16x16x32_bf16 v[70:73], v[204:207], v[134:137], v[70:73]
	ds_read_b128 v[134:137], v216 offset:33792
	s_waitcnt lgkmcnt(7)
	v_mfma_f32_16x16x32_bf16 v[74:77], v[196:199], v[138:141], v[74:77]
	v_mfma_f32_16x16x32_bf16 v[78:81], v[204:207], v[138:141], v[78:81]
	ds_read_b128 v[138:141], v216 offset:35840
	s_waitcnt lgkmcnt(7)
	v_mfma_f32_16x16x32_bf16 v[82:85], v[196:199], v[142:145], v[82:85]
	v_mfma_f32_16x16x32_bf16 v[86:89], v[204:207], v[142:145], v[86:89]
	ds_read_b128 v[142:145], v216 offset:37888
	s_waitcnt lgkmcnt(7)
	v_mfma_f32_16x16x32_bf16 v[90:93], v[196:199], v[146:149], v[90:93]
	v_mfma_f32_16x16x32_bf16 v[94:97], v[204:207], v[146:149], v[94:97]
	ds_read_b128 v[146:149], v216 offset:39936
	s_waitcnt lgkmcnt(7)
	v_mfma_f32_16x16x32_bf16 v[98:101], v[196:199], v[150:153], v[98:101]
	v_mfma_f32_16x16x32_bf16 v[102:105], v[204:207], v[150:153], v[102:105]
	ds_read_b128 v[150:153], v216 offset:41984
	s_waitcnt lgkmcnt(7)
	v_mfma_f32_16x16x32_bf16 v[106:109], v[196:199], v[154:157], v[106:109]
	v_mfma_f32_16x16x32_bf16 v[110:113], v[204:207], v[154:157], v[110:113]
	ds_read_b128 v[154:157], v216 offset:44032
	s_waitcnt lgkmcnt(7)
	v_mfma_f32_16x16x32_bf16 v[114:117], v[196:199], v[158:161], v[114:117]
	v_mfma_f32_16x16x32_bf16 v[118:121], v[204:207], v[158:161], v[118:121]
	ds_read_b128 v[158:161], v216 offset:46080
	s_waitcnt lgkmcnt(7)
	v_mfma_f32_16x16x32_bf16 v[122:125], v[196:199], v[162:165], v[122:125]
	v_mfma_f32_16x16x32_bf16 v[126:129], v[204:207], v[162:165], v[126:129]
	ds_read_b128 v[162:165], v216 offset:48128
	s_waitcnt lgkmcnt(7)
	v_mfma_f32_16x16x32_bf16 v[2:5], v[200:203], v[134:137], v[2:5]
	v_mfma_f32_16x16x32_bf16 v[6:9], v[212:215], v[134:137], v[6:9]
	ds_read_b128 v[134:137], v216 offset:50176
	s_waitcnt lgkmcnt(7)
	v_mfma_f32_16x16x32_bf16 v[10:13], v[200:203], v[138:141], v[10:13]
	v_mfma_f32_16x16x32_bf16 v[14:17], v[212:215], v[138:141], v[14:17]
	ds_read_b128 v[138:141], v216 offset:52224
	s_waitcnt lgkmcnt(7)
	v_mfma_f32_16x16x32_bf16 v[18:21], v[200:203], v[142:145], v[18:21]
	v_mfma_f32_16x16x32_bf16 v[22:25], v[212:215], v[142:145], v[22:25]
	ds_read_b128 v[142:145], v216 offset:54272
	s_waitcnt lgkmcnt(7)
	v_mfma_f32_16x16x32_bf16 v[26:29], v[200:203], v[146:149], v[26:29]
	v_mfma_f32_16x16x32_bf16 v[30:33], v[212:215], v[146:149], v[30:33]
	ds_read_b128 v[146:149], v216 offset:56320
	s_waitcnt lgkmcnt(7)
	v_mfma_f32_16x16x32_bf16 v[34:37], v[200:203], v[150:153], v[34:37]
	v_mfma_f32_16x16x32_bf16 v[38:41], v[212:215], v[150:153], v[38:41]
	ds_read_b128 v[150:153], v216 offset:58368
	s_waitcnt lgkmcnt(7)
	v_mfma_f32_16x16x32_bf16 v[42:45], v[200:203], v[154:157], v[42:45]
	v_mfma_f32_16x16x32_bf16 v[46:49], v[212:215], v[154:157], v[46:49]
	ds_read_b128 v[154:157], v216 offset:60416
	s_waitcnt lgkmcnt(7)
	v_mfma_f32_16x16x32_bf16 v[50:53], v[200:203], v[158:161], v[50:53]
	v_mfma_f32_16x16x32_bf16 v[54:57], v[212:215], v[158:161], v[54:57]
	ds_read_b128 v[158:161], v216 offset:62464
	s_waitcnt lgkmcnt(7)
	v_mfma_f32_16x16x32_bf16 v[58:61], v[200:203], v[162:165], v[58:61]
	v_mfma_f32_16x16x32_bf16 v[62:65], v[212:215], v[162:165], v[62:65]
	ds_read_b128 v[162:165], v216 offset:64512
	s_waitcnt vmcnt(0) lgkmcnt(0)
	s_barrier
	v_mfma_f32_16x16x32_bf16 v[66:69], v[200:203], v[134:137], v[66:69]
	v_mfma_f32_16x16x32_bf16 v[70:73], v[212:215], v[134:137], v[70:73]
	s_waitcnt lgkmcnt(7)
	v_mfma_f32_16x16x32_bf16 v[74:77], v[200:203], v[138:141], v[74:77]
	v_mfma_f32_16x16x32_bf16 v[78:81], v[212:215], v[138:141], v[78:81]
	s_waitcnt lgkmcnt(7)
	v_mfma_f32_16x16x32_bf16 v[82:85], v[200:203], v[142:145], v[82:85]
	v_mfma_f32_16x16x32_bf16 v[86:89], v[212:215], v[142:145], v[86:89]
	s_waitcnt lgkmcnt(7)
	v_mfma_f32_16x16x32_bf16 v[90:93], v[200:203], v[146:149], v[90:93]
	v_mfma_f32_16x16x32_bf16 v[94:97], v[212:215], v[146:149], v[94:97]
	s_waitcnt lgkmcnt(7)
	v_mfma_f32_16x16x32_bf16 v[98:101], v[200:203], v[150:153], v[98:101]
	v_mfma_f32_16x16x32_bf16 v[102:105], v[212:215], v[150:153], v[102:105]
	s_waitcnt lgkmcnt(7)
	v_mfma_f32_16x16x32_bf16 v[106:109], v[200:203], v[154:157], v[106:109]
	v_mfma_f32_16x16x32_bf16 v[110:113], v[212:215], v[154:157], v[110:113]
	s_waitcnt lgkmcnt(7)
	v_mfma_f32_16x16x32_bf16 v[114:117], v[200:203], v[158:161], v[114:117]
	v_mfma_f32_16x16x32_bf16 v[118:121], v[212:215], v[158:161], v[118:121]
	s_waitcnt lgkmcnt(7)
	v_mfma_f32_16x16x32_bf16 v[122:125], v[200:203], v[162:165], v[122:125]
	v_mfma_f32_16x16x32_bf16 v[126:129], v[212:215], v[162:165], v[126:129]
	s_mov_b32 s16, 0

.Lg256b_w1_first_retry:
	s_cmp_ge_u32 s12, 256
	s_cbranch_scc1 .Lg256b_w1_done
	s_lshr_b32 s3, s12, 6
	s_lshl_b32 s3, s3, 3
	s_add_u32 s3, s3, s65
	s_lshr_b32 s17, s3, 2
	s_and_b32 s3, s3, 3
	s_lshl_b32 s17, s17, 3
	s_bfe_u32 s23, s12, 0x30003
	s_add_u32 s13, s17, s23
	s_lshl_b32 s3, s3, 3
	s_and_b32 s23, s12, 7
	s_add_u32 s14, s3, s23
	s_lshl_b32 s13, s13, 8
	s_lshl_b32 s14, s14, 7
	s_lshl_b32 s3, s15, 6
	s_add_u32 s17, s3, s13
	s_mul_i32 s17, s17, 0x800
	s_add_u32 s6, s18, s17
	s_addc_u32 s7, s19, 0
	s_lshr_b32 s3, s14, 4
	s_lshl_b32 s17, s15, 1
	s_add_u32 s3, s3, s17
	s_mul_i32 s17, s3, 0x8000
	s_add_u32 s8, s20, s17
	s_addc_u32 s9, s21, 0
	s_barrier
	v_mov_b32_e32 v217, v218
	v_mov_b32_e32 v220, v222
	v_add_u32_e32 v221, 0x8000, v222
	s_add_u32 m0, s22, 0x0
	v_mov_b32_e32 v223, v217
	global_load_lds_dwordx4 v223, s[6:7]
	s_add_u32 m0, s22, 0x400
	v_add_u32_e32 v224, 0x40, v217
	global_load_lds_dwordx4 v224, s[6:7]
	s_add_u32 m0, s22, 0x800
	v_add_u32_e32 v223, 0x8000, v217
	global_load_lds_dwordx4 v223, s[6:7]
	s_add_u32 m0, s22, 0xc00
	v_add_u32_e32 v224, 0x8040, v217
	global_load_lds_dwordx4 v224, s[6:7]
	s_add_u32 m0, s22, 0x1000
	v_add_u32_e32 v223, 0x10000, v217
	global_load_lds_dwordx4 v223, s[6:7]
	s_add_u32 m0, s22, 0x1400
	v_add_u32_e32 v224, 0x10040, v217
	global_load_lds_dwordx4 v224, s[6:7]
	s_add_u32 m0, s22, 0x1800
	v_add_u32_e32 v223, 0x18000, v217
	global_load_lds_dwordx4 v223, s[6:7]
	s_add_u32 m0, s22, 0x1c00
	v_add_u32_e32 v224, 0x18040, v217
	global_load_lds_dwordx4 v224, s[6:7]
	v_add_u32_e32 v217, 0x80, v217
	s_add_u32 m0, s22, 0x8000
	v_mov_b32_e32 v223, v217
	global_load_lds_dwordx4 v223, s[6:7]
	s_add_u32 m0, s22, 0x8400
	v_add_u32_e32 v224, 0x40, v217
	global_load_lds_dwordx4 v224, s[6:7]
	s_add_u32 m0, s22, 0x8800
	v_add_u32_e32 v223, 0x8000, v217
	global_load_lds_dwordx4 v223, s[6:7]
	s_add_u32 m0, s22, 0x8c00
	v_add_u32_e32 v224, 0x8040, v217
	global_load_lds_dwordx4 v224, s[6:7]
	s_add_u32 m0, s22, 0x9000
	v_add_u32_e32 v223, 0x10000, v217
	global_load_lds_dwordx4 v223, s[6:7]
	s_add_u32 m0, s22, 0x9400
	v_add_u32_e32 v224, 0x10040, v217
	global_load_lds_dwordx4 v224, s[6:7]
	s_add_u32 m0, s22, 0x9800
	v_add_u32_e32 v223, 0x18000, v217
	global_load_lds_dwordx4 v223, s[6:7]
	s_add_u32 m0, s22, 0x9c00
	v_add_u32_e32 v224, 0x18040, v217
	global_load_lds_dwordx4 v224, s[6:7]
	v_add_u32_e32 v217, 0x80, v217
	global_load_dwordx4 v[166:169], v220, s[8:9]
	global_load_dwordx4 v[170:173], v220, s[8:9] offset:1024
	global_load_dwordx4 v[174:177], v221, s[8:9]
	global_load_dwordx4 v[178:181], v221, s[8:9] offset:1024
	v_add_u32_e32 v220, 0x800, v220
	v_add_u32_e32 v221, 0x800, v221
	s_waitcnt vmcnt(0)
	s_barrier
	ds_read_b128 v[134:137], v216
	ds_read_b128 v[138:141], v216 offset:2048
	ds_read_b128 v[142:145], v216 offset:4096
	ds_read_b128 v[146:149], v216 offset:6144
	ds_read_b128 v[150:153], v216 offset:8192
	ds_read_b128 v[154:157], v216 offset:10240
	ds_read_b128 v[158:161], v216 offset:12288
.Lg256b_w1_tile:
	s_mul_i32 s17, s13, 0x2000
	s_lshl_b32 s3, s15, 5
	s_add_u32 s3, s3, s14
	s_mul_i32 s3, s3, 2
	s_add_u32 s17, s17, s3
	s_add_u32 s10, s24, s17
	s_addc_u32 s11, s25, 0
	ds_read_b128 v[162:165], v216 offset:14336
	s_waitcnt vmcnt(40) lgkmcnt(7)
	v_mfma_f32_16x16x32_bf16 v[2:5], v[166:169], v[134:137], 0
	v_mfma_f32_16x16x32_bf16 v[6:9], v[174:177], v[134:137], 0
	ds_read_b128 v[134:137], v216 offset:16384
	s_waitcnt lgkmcnt(7)
	v_mfma_f32_16x16x32_bf16 v[10:13], v[166:169], v[138:141], 0
	v_mfma_f32_16x16x32_bf16 v[14:17], v[174:177], v[138:141], 0
	ds_read_b128 v[138:141], v216 offset:18432
	s_waitcnt lgkmcnt(7)
	v_mfma_f32_16x16x32_bf16 v[18:21], v[166:169], v[142:145], 0
	v_mfma_f32_16x16x32_bf16 v[22:25], v[174:177], v[142:145], 0
	ds_read_b128 v[142:145], v216 offset:20480
	s_waitcnt lgkmcnt(7)
	v_mfma_f32_16x16x32_bf16 v[26:29], v[166:169], v[146:149], 0
	v_mfma_f32_16x16x32_bf16 v[30:33], v[174:177], v[146:149], 0
	ds_read_b128 v[146:149], v216 offset:22528
	s_waitcnt lgkmcnt(7)
	v_mfma_f32_16x16x32_bf16 v[34:37], v[166:169], v[150:153], 0
	global_load_dwordx4 v[196:199], v220, s[8:9]
	v_mfma_f32_16x16x32_bf16 v[38:41], v[174:177], v[150:153], 0
	global_load_dwordx4 v[200:203], v220, s[8:9] offset:1024
	ds_read_b128 v[150:153], v216 offset:24576
	s_waitcnt lgkmcnt(7)
	v_mfma_f32_16x16x32_bf16 v[42:45], v[166:169], v[154:157], 0
	global_load_dwordx4 v[204:207], v221, s[8:9]
	v_mfma_f32_16x16x32_bf16 v[46:49], v[174:177], v[154:157], 0
	global_load_dwordx4 v[212:215], v221, s[8:9] offset:1024
	ds_read_b128 v[154:157], v216 offset:26624
	s_waitcnt lgkmcnt(7)
	v_mfma_f32_16x16x32_bf16 v[50:53], v[166:169], v[158:161], 0
	v_mfma_f32_16x16x32_bf16 v[54:57], v[174:177], v[158:161], 0
	ds_read_b128 v[158:161], v216 offset:28672
	s_waitcnt lgkmcnt(7)
	v_mfma_f32_16x16x32_bf16 v[58:61], v[166:169], v[162:165], 0
	v_mfma_f32_16x16x32_bf16 v[62:65], v[174:177], v[162:165], 0
	ds_read_b128 v[162:165], v216 offset:30720
	s_waitcnt lgkmcnt(7)
	v_mfma_f32_16x16x32_bf16 v[66:69], v[166:169], v[134:137], 0
	v_mfma_f32_16x16x32_bf16 v[70:73], v[174:177], v[134:137], 0
	ds_read_b128 v[134:137], v216 offset:1024
	s_waitcnt lgkmcnt(7)
	v_mfma_f32_16x16x32_bf16 v[74:77], v[166:169], v[138:141], 0
	v_mfma_f32_16x16x32_bf16 v[78:81], v[174:177], v[138:141], 0
	ds_read_b128 v[138:141], v216 offset:3072
	s_waitcnt lgkmcnt(7)
	v_mfma_f32_16x16x32_bf16 v[82:85], v[166:169], v[142:145], 0
	v_mfma_f32_16x16x32_bf16 v[86:89], v[174:177], v[142:145], 0
	ds_read_b128 v[142:145], v216 offset:5120
	s_waitcnt lgkmcnt(7)
	v_mfma_f32_16x16x32_bf16 v[90:93], v[166:169], v[146:149], 0
	v_mfma_f32_16x16x32_bf16 v[94:97], v[174:177], v[146:149], 0
	ds_read_b128 v[146:149], v216 offset:7168
	s_waitcnt lgkmcnt(7)
	v_mfma_f32_16x16x32_bf16 v[98:101], v[166:169], v[150:153], 0
	v_mfma_f32_16x16x32_bf16 v[102:105], v[174:177], v[150:153], 0
	ds_read_b128 v[150:153], v216 offset:9216
	s_waitcnt lgkmcnt(7)
	v_mfma_f32_16x16x32_bf16 v[106:109], v[166:169], v[154:157], 0
	v_mfma_f32_16x16x32_bf16 v[110:113], v[174:177], v[154:157], 0
	ds_read_b128 v[154:157], v216 offset:11264
	s_waitcnt lgkmcnt(7)
	v_mfma_f32_16x16x32_bf16 v[114:117], v[166:169], v[158:161], 0
	v_mfma_f32_16x16x32_bf16 v[118:121], v[174:177], v[158:161], 0
	ds_read_b128 v[158:161], v216 offset:13312
	s_waitcnt lgkmcnt(7)
	v_mfma_f32_16x16x32_bf16 v[122:125], v[166:169], v[162:165], 0
	v_mfma_f32_16x16x32_bf16 v[126:129], v[174:177], v[162:165], 0
	ds_read_b128 v[162:165], v216 offset:15360
	s_waitcnt lgkmcnt(7)
	v_mfma_f32_16x16x32_bf16 v[2:5], v[170:173], v[134:137], v[2:5]
	v_mfma_f32_16x16x32_bf16 v[6:9], v[178:181], v[134:137], v[6:9]
	ds_read_b128 v[134:137], v216 offset:17408
	s_waitcnt lgkmcnt(7)
	v_mfma_f32_16x16x32_bf16 v[10:13], v[170:173], v[138:141], v[10:13]
	v_mfma_f32_16x16x32_bf16 v[14:17], v[178:181], v[138:141], v[14:17]
	ds_read_b128 v[138:141], v216 offset:19456
	s_waitcnt lgkmcnt(7)
	v_mfma_f32_16x16x32_bf16 v[18:21], v[170:173], v[142:145], v[18:21]
	v_mfma_f32_16x16x32_bf16 v[22:25], v[178:181], v[142:145], v[22:25]
	ds_read_b128 v[142:145], v216 offset:21504
	s_waitcnt lgkmcnt(7)
	v_mfma_f32_16x16x32_bf16 v[26:29], v[170:173], v[146:149], v[26:29]
	v_mfma_f32_16x16x32_bf16 v[30:33], v[178:181], v[146:149], v[30:33]
	ds_read_b128 v[146:149], v216 offset:23552
	s_waitcnt lgkmcnt(7)
	v_mfma_f32_16x16x32_bf16 v[34:37], v[170:173], v[150:153], v[34:37]
	v_mfma_f32_16x16x32_bf16 v[38:41], v[178:181], v[150:153], v[38:41]
	ds_read_b128 v[150:153], v216 offset:25600
	s_waitcnt lgkmcnt(7)
	v_mfma_f32_16x16x32_bf16 v[42:45], v[170:173], v[154:157], v[42:45]
	v_mfma_f32_16x16x32_bf16 v[46:49], v[178:181], v[154:157], v[46:49]
	ds_read_b128 v[154:157], v216 offset:27648
	s_waitcnt lgkmcnt(7)
	v_mfma_f32_16x16x32_bf16 v[50:53], v[170:173], v[158:161], v[50:53]
	v_mfma_f32_16x16x32_bf16 v[54:57], v[178:181], v[158:161], v[54:57]
	ds_read_b128 v[158:161], v216 offset:29696
	s_waitcnt lgkmcnt(7)
	v_mfma_f32_16x16x32_bf16 v[58:61], v[170:173], v[162:165], v[58:61]
	v_mfma_f32_16x16x32_bf16 v[62:65], v[178:181], v[162:165], v[62:65]
	ds_read_b128 v[162:165], v216 offset:31744
	s_waitcnt vmcnt(36) lgkmcnt(0)
	s_barrier
	v_mfma_f32_16x16x32_bf16 v[66:69], v[170:173], v[134:137], v[66:69]
	s_add_u32 m0, s22, 0x0
	v_mov_b32_e32 v223, v217
	global_load_lds_dwordx4 v223, s[6:7]
	v_mfma_f32_16x16x32_bf16 v[70:73], v[178:181], v[134:137], v[70:73]
	s_add_u32 m0, s22, 0x400
	v_add_u32_e32 v224, 0x40, v217
	global_load_lds_dwordx4 v224, s[6:7]
	ds_read_b128 v[134:137], v216 offset:32768
	s_waitcnt lgkmcnt(7)
	v_mfma_f32_16x16x32_bf16 v[74:77], v[170:173], v[138:141], v[74:77]
	s_add_u32 m0, s22, 0x800
	v_add_u32_e32 v223, 0x8000, v217
	global_load_lds_dwordx4 v223, s[6:7]
	v_mfma_f32_16x16x32_bf16 v[78:81], v[178:181], v[138:141], v[78:81]
	s_add_u32 m0, s22, 0xc00
	v_add_u32_e32 v224, 0x8040, v217
	global_load_lds_dwordx4 v224, s[6:7]
	ds_read_b128 v[138:141], v216 offset:34816
	s_waitcnt lgkmcnt(7)
	v_mfma_f32_16x16x32_bf16 v[82:85], v[170:173], v[142:145], v[82:85]
	s_add_u32 m0, s22, 0x1000
	v_add_u32_e32 v223, 0x10000, v217
	global_load_lds_dwordx4 v223, s[6:7]
	v_mfma_f32_16x16x32_bf16 v[86:89], v[178:181], v[142:145], v[86:89]
	s_add_u32 m0, s22, 0x1400
	v_add_u32_e32 v224, 0x10040, v217
	global_load_lds_dwordx4 v224, s[6:7]
	ds_read_b128 v[142:145], v216 offset:36864
	s_waitcnt lgkmcnt(7)
	v_mfma_f32_16x16x32_bf16 v[90:93], v[170:173], v[146:149], v[90:93]
	s_add_u32 m0, s22, 0x1800
	v_add_u32_e32 v223, 0x18000, v217
	global_load_lds_dwordx4 v223, s[6:7]
	v_mfma_f32_16x16x32_bf16 v[94:97], v[178:181], v[146:149], v[94:97]
	s_add_u32 m0, s22, 0x1c00
	v_add_u32_e32 v224, 0x18040, v217
	global_load_lds_dwordx4 v224, s[6:7]
	ds_read_b128 v[146:149], v216 offset:38912
	s_waitcnt lgkmcnt(7)
	v_mfma_f32_16x16x32_bf16 v[98:101], v[170:173], v[150:153], v[98:101]
	v_mfma_f32_16x16x32_bf16 v[102:105], v[178:181], v[150:153], v[102:105]
	ds_read_b128 v[150:153], v216 offset:40960
	s_waitcnt lgkmcnt(7)
	v_mfma_f32_16x16x32_bf16 v[106:109], v[170:173], v[154:157], v[106:109]
	v_mfma_f32_16x16x32_bf16 v[110:113], v[178:181], v[154:157], v[110:113]
	ds_read_b128 v[154:157], v216 offset:43008
	s_waitcnt lgkmcnt(7)
	v_mfma_f32_16x16x32_bf16 v[114:117], v[170:173], v[158:161], v[114:117]
	v_mfma_f32_16x16x32_bf16 v[118:121], v[178:181], v[158:161], v[118:121]
	ds_read_b128 v[158:161], v216 offset:45056
	s_waitcnt lgkmcnt(7)
	v_mfma_f32_16x16x32_bf16 v[122:125], v[170:173], v[162:165], v[122:125]
	v_mfma_f32_16x16x32_bf16 v[126:129], v[178:181], v[162:165], v[126:129]
	v_add_u32_e32 v217, 0x80, v217
	v_add_u32_e32 v220, 0x800, v220
	v_add_u32_e32 v221, 0x800, v221
	ds_read_b128 v[162:165], v216 offset:47104
	s_waitcnt vmcnt(8) lgkmcnt(7)
	v_mfma_f32_16x16x32_bf16 v[2:5], v[196:199], v[134:137], v[2:5]
	v_mfma_f32_16x16x32_bf16 v[6:9], v[204:207], v[134:137], v[6:9]
	ds_read_b128 v[134:137], v216 offset:49152
	s_waitcnt lgkmcnt(7)
	v_mfma_f32_16x16x32_bf16 v[10:13], v[196:199], v[138:141], v[10:13]
	v_mfma_f32_16x16x32_bf16 v[14:17], v[204:207], v[138:141], v[14:17]
	ds_read_b128 v[138:141], v216 offset:51200
	s_waitcnt lgkmcnt(7)
	v_mfma_f32_16x16x32_bf16 v[18:21], v[196:199], v[142:145], v[18:21]
	v_mfma_f32_16x16x32_bf16 v[22:25], v[204:207], v[142:145], v[22:25]
	ds_read_b128 v[142:145], v216 offset:53248
	s_waitcnt lgkmcnt(7)
	v_mfma_f32_16x16x32_bf16 v[26:29], v[196:199], v[146:149], v[26:29]
	v_mfma_f32_16x16x32_bf16 v[30:33], v[204:207], v[146:149], v[30:33]
	ds_read_b128 v[146:149], v216 offset:55296
	s_waitcnt lgkmcnt(7)
	v_mfma_f32_16x16x32_bf16 v[34:37], v[196:199], v[150:153], v[34:37]
	global_load_dwordx4 v[166:169], v220, s[8:9]
	v_mfma_f32_16x16x32_bf16 v[38:41], v[204:207], v[150:153], v[38:41]
	global_load_dwordx4 v[170:173], v220, s[8:9] offset:1024
	ds_read_b128 v[150:153], v216 offset:57344
	s_waitcnt lgkmcnt(7)
	v_mfma_f32_16x16x32_bf16 v[42:45], v[196:199], v[154:157], v[42:45]
	global_load_dwordx4 v[174:177], v221, s[8:9]
	v_mfma_f32_16x16x32_bf16 v[46:49], v[204:207], v[154:157], v[46:49]
	global_load_dwordx4 v[178:181], v221, s[8:9] offset:1024
	ds_read_b128 v[154:157], v216 offset:59392
	s_waitcnt lgkmcnt(7)
	v_mfma_f32_16x16x32_bf16 v[50:53], v[196:199], v[158:161], v[50:53]
	v_mfma_f32_16x16x32_bf16 v[54:57], v[204:207], v[158:161], v[54:57]
	ds_read_b128 v[158:161], v216 offset:61440
	s_waitcnt lgkmcnt(7)
	v_mfma_f32_16x16x32_bf16 v[58:61], v[196:199], v[162:165], v[58:61]
	v_mfma_f32_16x16x32_bf16 v[62:65], v[204:207], v[162:165], v[62:65]
	ds_read_b128 v[162:165], v216 offset:63488
	s_waitcnt lgkmcnt(7)
	v_mfma_f32_16x16x32_bf16 v[66:69], v[196:199], v[134:137], v[66:69]
	v_mfma_f32_16x16x32_bf16 v[70:73], v[204:207], v[134:137], v[70:73]
	ds_read_b128 v[134:137], v216 offset:33792
	s_waitcnt lgkmcnt(7)
	v_mfma_f32_16x16x32_bf16 v[74:77], v[196:199], v[138:141], v[74:77]
	v_mfma_f32_16x16x32_bf16 v[78:81], v[204:207], v[138:141], v[78:81]
	ds_read_b128 v[138:141], v216 offset:35840
	s_waitcnt lgkmcnt(7)
	v_mfma_f32_16x16x32_bf16 v[82:85], v[196:199], v[142:145], v[82:85]
	v_mfma_f32_16x16x32_bf16 v[86:89], v[204:207], v[142:145], v[86:89]
	ds_read_b128 v[142:145], v216 offset:37888
	s_waitcnt lgkmcnt(7)
	v_mfma_f32_16x16x32_bf16 v[90:93], v[196:199], v[146:149], v[90:93]
	v_mfma_f32_16x16x32_bf16 v[94:97], v[204:207], v[146:149], v[94:97]
	ds_read_b128 v[146:149], v216 offset:39936
	s_waitcnt lgkmcnt(7)
	v_mfma_f32_16x16x32_bf16 v[98:101], v[196:199], v[150:153], v[98:101]
	v_mfma_f32_16x16x32_bf16 v[102:105], v[204:207], v[150:153], v[102:105]
	ds_read_b128 v[150:153], v216 offset:41984
	s_waitcnt lgkmcnt(7)
	v_mfma_f32_16x16x32_bf16 v[106:109], v[196:199], v[154:157], v[106:109]
	v_mfma_f32_16x16x32_bf16 v[110:113], v[204:207], v[154:157], v[110:113]
	ds_read_b128 v[154:157], v216 offset:44032
	s_waitcnt lgkmcnt(7)
	v_mfma_f32_16x16x32_bf16 v[114:117], v[196:199], v[158:161], v[114:117]
	v_mfma_f32_16x16x32_bf16 v[118:121], v[204:207], v[158:161], v[118:121]
	ds_read_b128 v[158:161], v216 offset:46080
	s_waitcnt lgkmcnt(7)
	v_mfma_f32_16x16x32_bf16 v[122:125], v[196:199], v[162:165], v[122:125]
	v_mfma_f32_16x16x32_bf16 v[126:129], v[204:207], v[162:165], v[126:129]
	ds_read_b128 v[162:165], v216 offset:48128
	s_waitcnt lgkmcnt(7)
	v_mfma_f32_16x16x32_bf16 v[2:5], v[200:203], v[134:137], v[2:5]
	v_mfma_f32_16x16x32_bf16 v[6:9], v[212:215], v[134:137], v[6:9]
	ds_read_b128 v[134:137], v216 offset:50176
	s_waitcnt lgkmcnt(7)
	v_mfma_f32_16x16x32_bf16 v[10:13], v[200:203], v[138:141], v[10:13]
	v_mfma_f32_16x16x32_bf16 v[14:17], v[212:215], v[138:141], v[14:17]
	ds_read_b128 v[138:141], v216 offset:52224
	s_waitcnt lgkmcnt(7)
	v_mfma_f32_16x16x32_bf16 v[18:21], v[200:203], v[142:145], v[18:21]
	v_mfma_f32_16x16x32_bf16 v[22:25], v[212:215], v[142:145], v[22:25]
	ds_read_b128 v[142:145], v216 offset:54272
	s_waitcnt lgkmcnt(7)
	v_mfma_f32_16x16x32_bf16 v[26:29], v[200:203], v[146:149], v[26:29]
	v_mfma_f32_16x16x32_bf16 v[30:33], v[212:215], v[146:149], v[30:33]
	ds_read_b128 v[146:149], v216 offset:56320
	s_waitcnt lgkmcnt(7)
	v_mfma_f32_16x16x32_bf16 v[34:37], v[200:203], v[150:153], v[34:37]
	v_mfma_f32_16x16x32_bf16 v[38:41], v[212:215], v[150:153], v[38:41]
	ds_read_b128 v[150:153], v216 offset:58368
	s_waitcnt lgkmcnt(7)
	v_mfma_f32_16x16x32_bf16 v[42:45], v[200:203], v[154:157], v[42:45]
	v_mfma_f32_16x16x32_bf16 v[46:49], v[212:215], v[154:157], v[46:49]
	ds_read_b128 v[154:157], v216 offset:60416
	s_waitcnt lgkmcnt(7)
	v_mfma_f32_16x16x32_bf16 v[50:53], v[200:203], v[158:161], v[50:53]
	v_mfma_f32_16x16x32_bf16 v[54:57], v[212:215], v[158:161], v[54:57]
	ds_read_b128 v[158:161], v216 offset:62464
	s_waitcnt lgkmcnt(7)
	v_mfma_f32_16x16x32_bf16 v[58:61], v[200:203], v[162:165], v[58:61]
	v_mfma_f32_16x16x32_bf16 v[62:65], v[212:215], v[162:165], v[62:65]
	ds_read_b128 v[162:165], v216 offset:64512
	s_waitcnt vmcnt(4) lgkmcnt(0)
	s_barrier
	v_mfma_f32_16x16x32_bf16 v[66:69], v[200:203], v[134:137], v[66:69]
	s_add_u32 m0, s22, 0x8000
	v_mov_b32_e32 v223, v217
	global_load_lds_dwordx4 v223, s[6:7]
	v_mfma_f32_16x16x32_bf16 v[70:73], v[212:215], v[134:137], v[70:73]
	s_add_u32 m0, s22, 0x8400
	v_add_u32_e32 v224, 0x40, v217
	global_load_lds_dwordx4 v224, s[6:7]
	ds_read_b128 v[134:137], v216
	s_waitcnt lgkmcnt(7)
	v_mfma_f32_16x16x32_bf16 v[74:77], v[200:203], v[138:141], v[74:77]
	s_add_u32 m0, s22, 0x8800
	v_add_u32_e32 v223, 0x8000, v217
	global_load_lds_dwordx4 v223, s[6:7]
	v_mfma_f32_16x16x32_bf16 v[78:81], v[212:215], v[138:141], v[78:81]
	s_add_u32 m0, s22, 0x8c00
	v_add_u32_e32 v224, 0x8040, v217
	global_load_lds_dwordx4 v224, s[6:7]
	ds_read_b128 v[138:141], v216 offset:2048
	s_waitcnt lgkmcnt(7)
	v_mfma_f32_16x16x32_bf16 v[82:85], v[200:203], v[142:145], v[82:85]
	s_add_u32 m0, s22, 0x9000
	v_add_u32_e32 v223, 0x10000, v217
	global_load_lds_dwordx4 v223, s[6:7]
	v_mfma_f32_16x16x32_bf16 v[86:89], v[212:215], v[142:145], v[86:89]
	s_add_u32 m0, s22, 0x9400
	v_add_u32_e32 v224, 0x10040, v217
	global_load_lds_dwordx4 v224, s[6:7]
	ds_read_b128 v[142:145], v216 offset:4096
	s_waitcnt lgkmcnt(7)
	v_mfma_f32_16x16x32_bf16 v[90:93], v[200:203], v[146:149], v[90:93]
	s_add_u32 m0, s22, 0x9800
	v_add_u32_e32 v223, 0x18000, v217
	global_load_lds_dwordx4 v223, s[6:7]
	v_mfma_f32_16x16x32_bf16 v[94:97], v[212:215], v[146:149], v[94:97]
	s_add_u32 m0, s22, 0x9c00
	v_add_u32_e32 v224, 0x18040, v217
	global_load_lds_dwordx4 v224, s[6:7]
	ds_read_b128 v[146:149], v216 offset:6144
	s_waitcnt lgkmcnt(7)
	v_mfma_f32_16x16x32_bf16 v[98:101], v[200:203], v[150:153], v[98:101]
	v_mfma_f32_16x16x32_bf16 v[102:105], v[212:215], v[150:153], v[102:105]
	ds_read_b128 v[150:153], v216 offset:8192
	s_waitcnt lgkmcnt(7)
	v_mfma_f32_16x16x32_bf16 v[106:109], v[200:203], v[154:157], v[106:109]
	v_mfma_f32_16x16x32_bf16 v[110:113], v[212:215], v[154:157], v[110:113]
	ds_read_b128 v[154:157], v216 offset:10240
	s_waitcnt lgkmcnt(7)
	v_mfma_f32_16x16x32_bf16 v[114:117], v[200:203], v[158:161], v[114:117]
	v_mfma_f32_16x16x32_bf16 v[118:121], v[212:215], v[158:161], v[118:121]
	ds_read_b128 v[158:161], v216 offset:12288
	s_waitcnt lgkmcnt(7)
	v_mfma_f32_16x16x32_bf16 v[122:125], v[200:203], v[162:165], v[122:125]
	v_mfma_f32_16x16x32_bf16 v[126:129], v[212:215], v[162:165], v[126:129]
	v_add_u32_e32 v217, 0x80, v217
	v_add_u32_e32 v220, 0x800, v220
	v_add_u32_e32 v221, 0x800, v221
	s_mov_b32 s16, 6
.Lg256b_w1_loop:
	ds_read_b128 v[162:165], v216 offset:14336
	s_waitcnt vmcnt(8) lgkmcnt(7)
	v_mfma_f32_16x16x32_bf16 v[2:5], v[166:169], v[134:137], v[2:5]
	v_mfma_f32_16x16x32_bf16 v[6:9], v[174:177], v[134:137], v[6:9]
	ds_read_b128 v[134:137], v216 offset:16384
	s_waitcnt lgkmcnt(7)
	v_mfma_f32_16x16x32_bf16 v[10:13], v[166:169], v[138:141], v[10:13]
	v_mfma_f32_16x16x32_bf16 v[14:17], v[174:177], v[138:141], v[14:17]
	ds_read_b128 v[138:141], v216 offset:18432
	s_waitcnt lgkmcnt(7)
	v_mfma_f32_16x16x32_bf16 v[18:21], v[166:169], v[142:145], v[18:21]
	v_mfma_f32_16x16x32_bf16 v[22:25], v[174:177], v[142:145], v[22:25]
	ds_read_b128 v[142:145], v216 offset:20480
	s_waitcnt lgkmcnt(7)
	v_mfma_f32_16x16x32_bf16 v[26:29], v[166:169], v[146:149], v[26:29]
	v_mfma_f32_16x16x32_bf16 v[30:33], v[174:177], v[146:149], v[30:33]
	ds_read_b128 v[146:149], v216 offset:22528
	s_waitcnt lgkmcnt(7)
	v_mfma_f32_16x16x32_bf16 v[34:37], v[166:169], v[150:153], v[34:37]
	global_load_dwordx4 v[196:199], v220, s[8:9]
	v_mfma_f32_16x16x32_bf16 v[38:41], v[174:177], v[150:153], v[38:41]
	global_load_dwordx4 v[200:203], v220, s[8:9] offset:1024
	ds_read_b128 v[150:153], v216 offset:24576
	s_waitcnt lgkmcnt(7)
	v_mfma_f32_16x16x32_bf16 v[42:45], v[166:169], v[154:157], v[42:45]
	global_load_dwordx4 v[204:207], v221, s[8:9]
	v_mfma_f32_16x16x32_bf16 v[46:49], v[174:177], v[154:157], v[46:49]
	global_load_dwordx4 v[212:215], v221, s[8:9] offset:1024
	ds_read_b128 v[154:157], v216 offset:26624
	s_waitcnt lgkmcnt(7)
	v_mfma_f32_16x16x32_bf16 v[50:53], v[166:169], v[158:161], v[50:53]
	v_mfma_f32_16x16x32_bf16 v[54:57], v[174:177], v[158:161], v[54:57]
	ds_read_b128 v[158:161], v216 offset:28672
	s_waitcnt lgkmcnt(7)
	v_mfma_f32_16x16x32_bf16 v[58:61], v[166:169], v[162:165], v[58:61]
	v_mfma_f32_16x16x32_bf16 v[62:65], v[174:177], v[162:165], v[62:65]
	ds_read_b128 v[162:165], v216 offset:30720
	s_waitcnt lgkmcnt(7)
	v_mfma_f32_16x16x32_bf16 v[66:69], v[166:169], v[134:137], v[66:69]
	v_mfma_f32_16x16x32_bf16 v[70:73], v[174:177], v[134:137], v[70:73]
	ds_read_b128 v[134:137], v216 offset:1024
	s_waitcnt lgkmcnt(7)
	v_mfma_f32_16x16x32_bf16 v[74:77], v[166:169], v[138:141], v[74:77]
	v_mfma_f32_16x16x32_bf16 v[78:81], v[174:177], v[138:141], v[78:81]
	ds_read_b128 v[138:141], v216 offset:3072
	s_waitcnt lgkmcnt(7)
	v_mfma_f32_16x16x32_bf16 v[82:85], v[166:169], v[142:145], v[82:85]
	v_mfma_f32_16x16x32_bf16 v[86:89], v[174:177], v[142:145], v[86:89]
	ds_read_b128 v[142:145], v216 offset:5120
	s_waitcnt lgkmcnt(7)
	v_mfma_f32_16x16x32_bf16 v[90:93], v[166:169], v[146:149], v[90:93]
	v_mfma_f32_16x16x32_bf16 v[94:97], v[174:177], v[146:149], v[94:97]
	ds_read_b128 v[146:149], v216 offset:7168
	s_waitcnt lgkmcnt(7)
	v_mfma_f32_16x16x32_bf16 v[98:101], v[166:169], v[150:153], v[98:101]
	v_mfma_f32_16x16x32_bf16 v[102:105], v[174:177], v[150:153], v[102:105]
	ds_read_b128 v[150:153], v216 offset:9216
	s_waitcnt lgkmcnt(7)
	v_mfma_f32_16x16x32_bf16 v[106:109], v[166:169], v[154:157], v[106:109]
	v_mfma_f32_16x16x32_bf16 v[110:113], v[174:177], v[154:157], v[110:113]
	ds_read_b128 v[154:157], v216 offset:11264
	s_waitcnt lgkmcnt(7)
	v_mfma_f32_16x16x32_bf16 v[114:117], v[166:169], v[158:161], v[114:117]
	v_mfma_f32_16x16x32_bf16 v[118:121], v[174:177], v[158:161], v[118:121]
	ds_read_b128 v[158:161], v216 offset:13312
	s_waitcnt lgkmcnt(7)
	v_mfma_f32_16x16x32_bf16 v[122:125], v[166:169], v[162:165], v[122:125]
	v_mfma_f32_16x16x32_bf16 v[126:129], v[174:177], v[162:165], v[126:129]
	ds_read_b128 v[162:165], v216 offset:15360
	s_waitcnt lgkmcnt(7)
	v_mfma_f32_16x16x32_bf16 v[2:5], v[170:173], v[134:137], v[2:5]
	v_mfma_f32_16x16x32_bf16 v[6:9], v[178:181], v[134:137], v[6:9]
	ds_read_b128 v[134:137], v216 offset:17408
	s_waitcnt lgkmcnt(7)
	v_mfma_f32_16x16x32_bf16 v[10:13], v[170:173], v[138:141], v[10:13]
	v_mfma_f32_16x16x32_bf16 v[14:17], v[178:181], v[138:141], v[14:17]
	ds_read_b128 v[138:141], v216 offset:19456
	s_waitcnt lgkmcnt(7)
	v_mfma_f32_16x16x32_bf16 v[18:21], v[170:173], v[142:145], v[18:21]
	v_mfma_f32_16x16x32_bf16 v[22:25], v[178:181], v[142:145], v[22:25]
	ds_read_b128 v[142:145], v216 offset:21504
	s_waitcnt lgkmcnt(7)
	v_mfma_f32_16x16x32_bf16 v[26:29], v[170:173], v[146:149], v[26:29]
	v_mfma_f32_16x16x32_bf16 v[30:33], v[178:181], v[146:149], v[30:33]
	ds_read_b128 v[146:149], v216 offset:23552
	s_waitcnt lgkmcnt(7)
	v_mfma_f32_16x16x32_bf16 v[34:37], v[170:173], v[150:153], v[34:37]
	v_mfma_f32_16x16x32_bf16 v[38:41], v[178:181], v[150:153], v[38:41]
	ds_read_b128 v[150:153], v216 offset:25600
	s_waitcnt lgkmcnt(7)
	v_mfma_f32_16x16x32_bf16 v[42:45], v[170:173], v[154:157], v[42:45]
	v_mfma_f32_16x16x32_bf16 v[46:49], v[178:181], v[154:157], v[46:49]
	ds_read_b128 v[154:157], v216 offset:27648
	s_waitcnt lgkmcnt(7)
	v_mfma_f32_16x16x32_bf16 v[50:53], v[170:173], v[158:161], v[50:53]
	v_mfma_f32_16x16x32_bf16 v[54:57], v[178:181], v[158:161], v[54:57]
	ds_read_b128 v[158:161], v216 offset:29696
	s_waitcnt lgkmcnt(7)
	v_mfma_f32_16x16x32_bf16 v[58:61], v[170:173], v[162:165], v[58:61]
	v_mfma_f32_16x16x32_bf16 v[62:65], v[178:181], v[162:165], v[62:65]
	ds_read_b128 v[162:165], v216 offset:31744
	s_waitcnt vmcnt(4) lgkmcnt(0)
	s_barrier
	v_mfma_f32_16x16x32_bf16 v[66:69], v[170:173], v[134:137], v[66:69]
	s_add_u32 m0, s22, 0x0
	v_mov_b32_e32 v223, v217
	global_load_lds_dwordx4 v223, s[6:7]
	v_mfma_f32_16x16x32_bf16 v[70:73], v[178:181], v[134:137], v[70:73]
	s_add_u32 m0, s22, 0x400
	v_add_u32_e32 v224, 0x40, v217
	global_load_lds_dwordx4 v224, s[6:7]
	ds_read_b128 v[134:137], v216 offset:32768
	s_waitcnt lgkmcnt(7)
	v_mfma_f32_16x16x32_bf16 v[74:77], v[170:173], v[138:141], v[74:77]
	s_add_u32 m0, s22, 0x800
	v_add_u32_e32 v223, 0x8000, v217
	global_load_lds_dwordx4 v223, s[6:7]
	v_mfma_f32_16x16x32_bf16 v[78:81], v[178:181], v[138:141], v[78:81]
	s_add_u32 m0, s22, 0xc00
	v_add_u32_e32 v224, 0x8040, v217
	global_load_lds_dwordx4 v224, s[6:7]
	ds_read_b128 v[138:141], v216 offset:34816
	s_waitcnt lgkmcnt(7)
	v_mfma_f32_16x16x32_bf16 v[82:85], v[170:173], v[142:145], v[82:85]
	s_add_u32 m0, s22, 0x1000
	v_add_u32_e32 v223, 0x10000, v217
	global_load_lds_dwordx4 v223, s[6:7]
	v_mfma_f32_16x16x32_bf16 v[86:89], v[178:181], v[142:145], v[86:89]
	s_add_u32 m0, s22, 0x1400
	v_add_u32_e32 v224, 0x10040, v217
	global_load_lds_dwordx4 v224, s[6:7]
	ds_read_b128 v[142:145], v216 offset:36864
	s_waitcnt lgkmcnt(7)
	v_mfma_f32_16x16x32_bf16 v[90:93], v[170:173], v[146:149], v[90:93]
	s_add_u32 m0, s22, 0x1800
	v_add_u32_e32 v223, 0x18000, v217
	global_load_lds_dwordx4 v223, s[6:7]
	v_mfma_f32_16x16x32_bf16 v[94:97], v[178:181], v[146:149], v[94:97]
	s_add_u32 m0, s22, 0x1c00
	v_add_u32_e32 v224, 0x18040, v217
	global_load_lds_dwordx4 v224, s[6:7]
	ds_read_b128 v[146:149], v216 offset:38912
	s_waitcnt lgkmcnt(7)
	v_mfma_f32_16x16x32_bf16 v[98:101], v[170:173], v[150:153], v[98:101]
	v_mfma_f32_16x16x32_bf16 v[102:105], v[178:181], v[150:153], v[102:105]
	ds_read_b128 v[150:153], v216 offset:40960
	s_waitcnt lgkmcnt(7)
	v_mfma_f32_16x16x32_bf16 v[106:109], v[170:173], v[154:157], v[106:109]
	v_mfma_f32_16x16x32_bf16 v[110:113], v[178:181], v[154:157], v[110:113]
	ds_read_b128 v[154:157], v216 offset:43008
	s_waitcnt lgkmcnt(7)
	v_mfma_f32_16x16x32_bf16 v[114:117], v[170:173], v[158:161], v[114:117]
	v_mfma_f32_16x16x32_bf16 v[118:121], v[178:181], v[158:161], v[118:121]
	ds_read_b128 v[158:161], v216 offset:45056
	s_waitcnt lgkmcnt(7)
	v_mfma_f32_16x16x32_bf16 v[122:125], v[170:173], v[162:165], v[122:125]
	v_mfma_f32_16x16x32_bf16 v[126:129], v[178:181], v[162:165], v[126:129]
	v_add_u32_e32 v217, 0x80, v217
	v_add_u32_e32 v220, 0x800, v220
	v_add_u32_e32 v221, 0x800, v221
	ds_read_b128 v[162:165], v216 offset:47104
	s_waitcnt vmcnt(8) lgkmcnt(7)
	v_mfma_f32_16x16x32_bf16 v[2:5], v[196:199], v[134:137], v[2:5]
	v_mfma_f32_16x16x32_bf16 v[6:9], v[204:207], v[134:137], v[6:9]
	ds_read_b128 v[134:137], v216 offset:49152
	s_waitcnt lgkmcnt(7)
	v_mfma_f32_16x16x32_bf16 v[10:13], v[196:199], v[138:141], v[10:13]
	v_mfma_f32_16x16x32_bf16 v[14:17], v[204:207], v[138:141], v[14:17]
	ds_read_b128 v[138:141], v216 offset:51200
	s_waitcnt lgkmcnt(7)
	v_mfma_f32_16x16x32_bf16 v[18:21], v[196:199], v[142:145], v[18:21]
	v_mfma_f32_16x16x32_bf16 v[22:25], v[204:207], v[142:145], v[22:25]
	ds_read_b128 v[142:145], v216 offset:53248
	s_waitcnt lgkmcnt(7)
	v_mfma_f32_16x16x32_bf16 v[26:29], v[196:199], v[146:149], v[26:29]
	v_mfma_f32_16x16x32_bf16 v[30:33], v[204:207], v[146:149], v[30:33]
	ds_read_b128 v[146:149], v216 offset:55296
	s_waitcnt lgkmcnt(7)
	v_mfma_f32_16x16x32_bf16 v[34:37], v[196:199], v[150:153], v[34:37]
	global_load_dwordx4 v[166:169], v220, s[8:9]
	v_mfma_f32_16x16x32_bf16 v[38:41], v[204:207], v[150:153], v[38:41]
	global_load_dwordx4 v[170:173], v220, s[8:9] offset:1024
	ds_read_b128 v[150:153], v216 offset:57344
	s_waitcnt lgkmcnt(7)
	v_mfma_f32_16x16x32_bf16 v[42:45], v[196:199], v[154:157], v[42:45]
	global_load_dwordx4 v[174:177], v221, s[8:9]
	v_mfma_f32_16x16x32_bf16 v[46:49], v[204:207], v[154:157], v[46:49]
	global_load_dwordx4 v[178:181], v221, s[8:9] offset:1024
	ds_read_b128 v[154:157], v216 offset:59392
	s_waitcnt lgkmcnt(7)
	v_mfma_f32_16x16x32_bf16 v[50:53], v[196:199], v[158:161], v[50:53]
	v_mfma_f32_16x16x32_bf16 v[54:57], v[204:207], v[158:161], v[54:57]
	ds_read_b128 v[158:161], v216 offset:61440
	s_waitcnt lgkmcnt(7)
	v_mfma_f32_16x16x32_bf16 v[58:61], v[196:199], v[162:165], v[58:61]
	v_mfma_f32_16x16x32_bf16 v[62:65], v[204:207], v[162:165], v[62:65]
	ds_read_b128 v[162:165], v216 offset:63488
	s_waitcnt lgkmcnt(7)
	v_mfma_f32_16x16x32_bf16 v[66:69], v[196:199], v[134:137], v[66:69]
	v_mfma_f32_16x16x32_bf16 v[70:73], v[204:207], v[134:137], v[70:73]
	ds_read_b128 v[134:137], v216 offset:33792
	s_waitcnt lgkmcnt(7)
	v_mfma_f32_16x16x32_bf16 v[74:77], v[196:199], v[138:141], v[74:77]
	v_mfma_f32_16x16x32_bf16 v[78:81], v[204:207], v[138:141], v[78:81]
	ds_read_b128 v[138:141], v216 offset:35840
	s_waitcnt lgkmcnt(7)
	v_mfma_f32_16x16x32_bf16 v[82:85], v[196:199], v[142:145], v[82:85]
	v_mfma_f32_16x16x32_bf16 v[86:89], v[204:207], v[142:145], v[86:89]
	ds_read_b128 v[142:145], v216 offset:37888
	s_waitcnt lgkmcnt(7)
	v_mfma_f32_16x16x32_bf16 v[90:93], v[196:199], v[146:149], v[90:93]
	v_mfma_f32_16x16x32_bf16 v[94:97], v[204:207], v[146:149], v[94:97]
	ds_read_b128 v[146:149], v216 offset:39936
	s_waitcnt lgkmcnt(7)
	v_mfma_f32_16x16x32_bf16 v[98:101], v[196:199], v[150:153], v[98:101]
	v_mfma_f32_16x16x32_bf16 v[102:105], v[204:207], v[150:153], v[102:105]
	ds_read_b128 v[150:153], v216 offset:41984
	s_waitcnt lgkmcnt(7)
	v_mfma_f32_16x16x32_bf16 v[106:109], v[196:199], v[154:157], v[106:109]
	v_mfma_f32_16x16x32_bf16 v[110:113], v[204:207], v[154:157], v[110:113]
	ds_read_b128 v[154:157], v216 offset:44032
	s_waitcnt lgkmcnt(7)
	v_mfma_f32_16x16x32_bf16 v[114:117], v[196:199], v[158:161], v[114:117]
	v_mfma_f32_16x16x32_bf16 v[118:121], v[204:207], v[158:161], v[118:121]
	ds_read_b128 v[158:161], v216 offset:46080
	s_waitcnt lgkmcnt(7)
	v_mfma_f32_16x16x32_bf16 v[122:125], v[196:199], v[162:165], v[122:125]
	v_mfma_f32_16x16x32_bf16 v[126:129], v[204:207], v[162:165], v[126:129]
	ds_read_b128 v[162:165], v216 offset:48128
	s_waitcnt lgkmcnt(7)
	v_mfma_f32_16x16x32_bf16 v[2:5], v[200:203], v[134:137], v[2:5]
	v_mfma_f32_16x16x32_bf16 v[6:9], v[212:215], v[134:137], v[6:9]
	ds_read_b128 v[134:137], v216 offset:50176
	s_waitcnt lgkmcnt(7)
	v_mfma_f32_16x16x32_bf16 v[10:13], v[200:203], v[138:141], v[10:13]
	v_mfma_f32_16x16x32_bf16 v[14:17], v[212:215], v[138:141], v[14:17]
	ds_read_b128 v[138:141], v216 offset:52224
	s_waitcnt lgkmcnt(7)
	v_mfma_f32_16x16x32_bf16 v[18:21], v[200:203], v[142:145], v[18:21]
	v_mfma_f32_16x16x32_bf16 v[22:25], v[212:215], v[142:145], v[22:25]
	ds_read_b128 v[142:145], v216 offset:54272
	s_waitcnt lgkmcnt(7)
	v_mfma_f32_16x16x32_bf16 v[26:29], v[200:203], v[146:149], v[26:29]
	v_mfma_f32_16x16x32_bf16 v[30:33], v[212:215], v[146:149], v[30:33]
	ds_read_b128 v[146:149], v216 offset:56320
	s_waitcnt lgkmcnt(7)
	v_mfma_f32_16x16x32_bf16 v[34:37], v[200:203], v[150:153], v[34:37]
	v_mfma_f32_16x16x32_bf16 v[38:41], v[212:215], v[150:153], v[38:41]
	ds_read_b128 v[150:153], v216 offset:58368
	s_waitcnt lgkmcnt(7)
	v_mfma_f32_16x16x32_bf16 v[42:45], v[200:203], v[154:157], v[42:45]
	v_mfma_f32_16x16x32_bf16 v[46:49], v[212:215], v[154:157], v[46:49]
	ds_read_b128 v[154:157], v216 offset:60416
	s_waitcnt lgkmcnt(7)
	v_mfma_f32_16x16x32_bf16 v[50:53], v[200:203], v[158:161], v[50:53]
	v_mfma_f32_16x16x32_bf16 v[54:57], v[212:215], v[158:161], v[54:57]
	ds_read_b128 v[158:161], v216 offset:62464
	s_waitcnt lgkmcnt(7)
	v_mfma_f32_16x16x32_bf16 v[58:61], v[200:203], v[162:165], v[58:61]
	v_mfma_f32_16x16x32_bf16 v[62:65], v[212:215], v[162:165], v[62:65]
	ds_read_b128 v[162:165], v216 offset:64512
	s_waitcnt vmcnt(4) lgkmcnt(0)
	s_barrier
	v_mfma_f32_16x16x32_bf16 v[66:69], v[200:203], v[134:137], v[66:69]
	s_add_u32 m0, s22, 0x8000
	v_mov_b32_e32 v223, v217
	global_load_lds_dwordx4 v223, s[6:7]
	v_mfma_f32_16x16x32_bf16 v[70:73], v[212:215], v[134:137], v[70:73]
	s_add_u32 m0, s22, 0x8400
	v_add_u32_e32 v224, 0x40, v217
	global_load_lds_dwordx4 v224, s[6:7]
	ds_read_b128 v[134:137], v216
	s_waitcnt lgkmcnt(7)
	v_mfma_f32_16x16x32_bf16 v[74:77], v[200:203], v[138:141], v[74:77]
	s_add_u32 m0, s22, 0x8800
	v_add_u32_e32 v223, 0x8000, v217
	global_load_lds_dwordx4 v223, s[6:7]
	v_mfma_f32_16x16x32_bf16 v[78:81], v[212:215], v[138:141], v[78:81]
	s_add_u32 m0, s22, 0x8c00
	v_add_u32_e32 v224, 0x8040, v217
	global_load_lds_dwordx4 v224, s[6:7]
	ds_read_b128 v[138:141], v216 offset:2048
	s_waitcnt lgkmcnt(7)
	v_mfma_f32_16x16x32_bf16 v[82:85], v[200:203], v[142:145], v[82:85]
	s_add_u32 m0, s22, 0x9000
	v_add_u32_e32 v223, 0x10000, v217
	global_load_lds_dwordx4 v223, s[6:7]
	v_mfma_f32_16x16x32_bf16 v[86:89], v[212:215], v[142:145], v[86:89]
	s_add_u32 m0, s22, 0x9400
	v_add_u32_e32 v224, 0x10040, v217
	global_load_lds_dwordx4 v224, s[6:7]
	ds_read_b128 v[142:145], v216 offset:4096
	s_waitcnt lgkmcnt(7)
	v_mfma_f32_16x16x32_bf16 v[90:93], v[200:203], v[146:149], v[90:93]
	s_add_u32 m0, s22, 0x9800
	v_add_u32_e32 v223, 0x18000, v217
	global_load_lds_dwordx4 v223, s[6:7]
	v_mfma_f32_16x16x32_bf16 v[94:97], v[212:215], v[146:149], v[94:97]
	s_add_u32 m0, s22, 0x9c00
	v_add_u32_e32 v224, 0x18040, v217
	global_load_lds_dwordx4 v224, s[6:7]
	ds_read_b128 v[146:149], v216 offset:6144
	s_waitcnt lgkmcnt(7)
	v_mfma_f32_16x16x32_bf16 v[98:101], v[200:203], v[150:153], v[98:101]
	v_mfma_f32_16x16x32_bf16 v[102:105], v[212:215], v[150:153], v[102:105]
	ds_read_b128 v[150:153], v216 offset:8192
	s_waitcnt lgkmcnt(7)
	v_mfma_f32_16x16x32_bf16 v[106:109], v[200:203], v[154:157], v[106:109]
	v_mfma_f32_16x16x32_bf16 v[110:113], v[212:215], v[154:157], v[110:113]
	ds_read_b128 v[154:157], v216 offset:10240
	s_waitcnt lgkmcnt(7)
	v_mfma_f32_16x16x32_bf16 v[114:117], v[200:203], v[158:161], v[114:117]
	v_mfma_f32_16x16x32_bf16 v[118:121], v[212:215], v[158:161], v[118:121]
	ds_read_b128 v[158:161], v216 offset:12288
	s_waitcnt lgkmcnt(7)
	v_mfma_f32_16x16x32_bf16 v[122:125], v[200:203], v[162:165], v[122:125]
	v_mfma_f32_16x16x32_bf16 v[126:129], v[212:215], v[162:165], v[126:129]
	v_add_u32_e32 v217, 0x80, v217
	v_add_u32_e32 v220, 0x800, v220
	v_add_u32_e32 v221, 0x800, v221
	s_sub_u32 s16, s16, 1
	s_cmp_lg_u32 s16, 0
	s_cbranch_scc1 .Lg256b_w1_loop
	s_add_u32 s12, s12, s83
.Lg256b_w1_next_retry:
	s_cmp_ge_u32 s12, 256
	s_cbranch_scc1 .Lg256b_w1_nonext
	s_lshr_b32 s3, s12, 6
	s_lshl_b32 s3, s3, 3
	s_add_u32 s3, s3, s65
	s_lshr_b32 s17, s3, 2
	s_and_b32 s3, s3, 3
	s_lshl_b32 s17, s17, 3
	s_bfe_u32 s23, s12, 0x30003
	s_add_u32 s13, s17, s23
	s_lshl_b32 s3, s3, 3
	s_and_b32 s23, s12, 7
	s_add_u32 s14, s3, s23
	s_lshl_b32 s13, s13, 8
	s_lshl_b32 s14, s14, 7
	s_lshl_b32 s3, s15, 6
	s_add_u32 s17, s3, s13
	s_mul_i32 s17, s17, 0x800
	s_add_u32 s6, s18, s17
	s_addc_u32 s7, s19, 0
	v_mov_b32_e32 v217, v218
	ds_read_b128 v[162:165], v216 offset:14336
	s_waitcnt vmcnt(8) lgkmcnt(7)
	v_mfma_f32_16x16x32_bf16 v[2:5], v[166:169], v[134:137], v[2:5]
	v_mfma_f32_16x16x32_bf16 v[6:9], v[174:177], v[134:137], v[6:9]
	ds_read_b128 v[134:137], v216 offset:16384
	s_waitcnt lgkmcnt(7)
	v_mfma_f32_16x16x32_bf16 v[10:13], v[166:169], v[138:141], v[10:13]
	v_mfma_f32_16x16x32_bf16 v[14:17], v[174:177], v[138:141], v[14:17]
	ds_read_b128 v[138:141], v216 offset:18432
	s_waitcnt lgkmcnt(7)
	v_mfma_f32_16x16x32_bf16 v[18:21], v[166:169], v[142:145], v[18:21]
	v_mfma_f32_16x16x32_bf16 v[22:25], v[174:177], v[142:145], v[22:25]
	ds_read_b128 v[142:145], v216 offset:20480
	s_waitcnt lgkmcnt(7)
	v_mfma_f32_16x16x32_bf16 v[26:29], v[166:169], v[146:149], v[26:29]
	v_mfma_f32_16x16x32_bf16 v[30:33], v[174:177], v[146:149], v[30:33]
	ds_read_b128 v[146:149], v216 offset:22528
	s_waitcnt lgkmcnt(7)
	v_mfma_f32_16x16x32_bf16 v[34:37], v[166:169], v[150:153], v[34:37]
	global_load_dwordx4 v[196:199], v220, s[8:9]
	v_mfma_f32_16x16x32_bf16 v[38:41], v[174:177], v[150:153], v[38:41]
	global_load_dwordx4 v[200:203], v220, s[8:9] offset:1024
	ds_read_b128 v[150:153], v216 offset:24576
	s_waitcnt lgkmcnt(7)
	v_mfma_f32_16x16x32_bf16 v[42:45], v[166:169], v[154:157], v[42:45]
	global_load_dwordx4 v[204:207], v221, s[8:9]
	v_mfma_f32_16x16x32_bf16 v[46:49], v[174:177], v[154:157], v[46:49]
	global_load_dwordx4 v[212:215], v221, s[8:9] offset:1024
	ds_read_b128 v[154:157], v216 offset:26624
	s_waitcnt lgkmcnt(7)
	v_mfma_f32_16x16x32_bf16 v[50:53], v[166:169], v[158:161], v[50:53]
	v_mfma_f32_16x16x32_bf16 v[54:57], v[174:177], v[158:161], v[54:57]
	ds_read_b128 v[158:161], v216 offset:28672
	s_waitcnt lgkmcnt(7)
	v_mfma_f32_16x16x32_bf16 v[58:61], v[166:169], v[162:165], v[58:61]
	v_mfma_f32_16x16x32_bf16 v[62:65], v[174:177], v[162:165], v[62:65]
	ds_read_b128 v[162:165], v216 offset:30720
	s_waitcnt lgkmcnt(7)
	v_mfma_f32_16x16x32_bf16 v[66:69], v[166:169], v[134:137], v[66:69]
	v_mfma_f32_16x16x32_bf16 v[70:73], v[174:177], v[134:137], v[70:73]
	ds_read_b128 v[134:137], v216 offset:1024
	s_waitcnt lgkmcnt(7)
	v_mfma_f32_16x16x32_bf16 v[74:77], v[166:169], v[138:141], v[74:77]
	v_mfma_f32_16x16x32_bf16 v[78:81], v[174:177], v[138:141], v[78:81]
	ds_read_b128 v[138:141], v216 offset:3072
	s_waitcnt lgkmcnt(7)
	v_mfma_f32_16x16x32_bf16 v[82:85], v[166:169], v[142:145], v[82:85]
	v_mfma_f32_16x16x32_bf16 v[86:89], v[174:177], v[142:145], v[86:89]
	ds_read_b128 v[142:145], v216 offset:5120
	s_waitcnt lgkmcnt(7)
	v_mfma_f32_16x16x32_bf16 v[90:93], v[166:169], v[146:149], v[90:93]
	v_mfma_f32_16x16x32_bf16 v[94:97], v[174:177], v[146:149], v[94:97]
	ds_read_b128 v[146:149], v216 offset:7168
	s_waitcnt lgkmcnt(7)
	v_mfma_f32_16x16x32_bf16 v[98:101], v[166:169], v[150:153], v[98:101]
	v_mfma_f32_16x16x32_bf16 v[102:105], v[174:177], v[150:153], v[102:105]
	ds_read_b128 v[150:153], v216 offset:9216
	s_waitcnt lgkmcnt(7)
	v_mfma_f32_16x16x32_bf16 v[106:109], v[166:169], v[154:157], v[106:109]
	v_mfma_f32_16x16x32_bf16 v[110:113], v[174:177], v[154:157], v[110:113]
	ds_read_b128 v[154:157], v216 offset:11264
	s_waitcnt lgkmcnt(7)
	v_mfma_f32_16x16x32_bf16 v[114:117], v[166:169], v[158:161], v[114:117]
	v_mfma_f32_16x16x32_bf16 v[118:121], v[174:177], v[158:161], v[118:121]
	ds_read_b128 v[158:161], v216 offset:13312
	s_waitcnt lgkmcnt(7)
	v_mfma_f32_16x16x32_bf16 v[122:125], v[166:169], v[162:165], v[122:125]
	v_mfma_f32_16x16x32_bf16 v[126:129], v[174:177], v[162:165], v[126:129]
	ds_read_b128 v[162:165], v216 offset:15360
	s_waitcnt lgkmcnt(7)
	v_mfma_f32_16x16x32_bf16 v[2:5], v[170:173], v[134:137], v[2:5]
	v_mfma_f32_16x16x32_bf16 v[6:9], v[178:181], v[134:137], v[6:9]
	ds_read_b128 v[134:137], v216 offset:17408
	s_waitcnt lgkmcnt(7)
	v_mfma_f32_16x16x32_bf16 v[10:13], v[170:173], v[138:141], v[10:13]
	v_mfma_f32_16x16x32_bf16 v[14:17], v[178:181], v[138:141], v[14:17]
	ds_read_b128 v[138:141], v216 offset:19456
	s_waitcnt lgkmcnt(7)
	v_mfma_f32_16x16x32_bf16 v[18:21], v[170:173], v[142:145], v[18:21]
	v_mfma_f32_16x16x32_bf16 v[22:25], v[178:181], v[142:145], v[22:25]
	ds_read_b128 v[142:145], v216 offset:21504
	s_waitcnt lgkmcnt(7)
	v_mfma_f32_16x16x32_bf16 v[26:29], v[170:173], v[146:149], v[26:29]
	v_mfma_f32_16x16x32_bf16 v[30:33], v[178:181], v[146:149], v[30:33]
	ds_read_b128 v[146:149], v216 offset:23552
	s_waitcnt lgkmcnt(7)
	v_mfma_f32_16x16x32_bf16 v[34:37], v[170:173], v[150:153], v[34:37]
	v_mfma_f32_16x16x32_bf16 v[38:41], v[178:181], v[150:153], v[38:41]
	ds_read_b128 v[150:153], v216 offset:25600
	s_waitcnt lgkmcnt(7)
	v_mfma_f32_16x16x32_bf16 v[42:45], v[170:173], v[154:157], v[42:45]
	v_mfma_f32_16x16x32_bf16 v[46:49], v[178:181], v[154:157], v[46:49]
	ds_read_b128 v[154:157], v216 offset:27648
	s_waitcnt lgkmcnt(7)
	v_mfma_f32_16x16x32_bf16 v[50:53], v[170:173], v[158:161], v[50:53]
	v_mfma_f32_16x16x32_bf16 v[54:57], v[178:181], v[158:161], v[54:57]
	ds_read_b128 v[158:161], v216 offset:29696
	s_waitcnt lgkmcnt(7)
	v_mfma_f32_16x16x32_bf16 v[58:61], v[170:173], v[162:165], v[58:61]
	v_mfma_f32_16x16x32_bf16 v[62:65], v[178:181], v[162:165], v[62:65]
	ds_read_b128 v[162:165], v216 offset:31744
	s_waitcnt vmcnt(4) lgkmcnt(0)
	s_barrier
	v_mfma_f32_16x16x32_bf16 v[66:69], v[170:173], v[134:137], v[66:69]
	s_add_u32 m0, s22, 0x0
	v_mov_b32_e32 v223, v217
	global_load_lds_dwordx4 v223, s[6:7]
	v_mfma_f32_16x16x32_bf16 v[70:73], v[178:181], v[134:137], v[70:73]
	s_add_u32 m0, s22, 0x400
	v_add_u32_e32 v224, 0x40, v217
	global_load_lds_dwordx4 v224, s[6:7]
	ds_read_b128 v[134:137], v216 offset:32768
	s_waitcnt lgkmcnt(7)
	v_mfma_f32_16x16x32_bf16 v[74:77], v[170:173], v[138:141], v[74:77]
	s_add_u32 m0, s22, 0x800
	v_add_u32_e32 v223, 0x8000, v217
	global_load_lds_dwordx4 v223, s[6:7]
	v_mfma_f32_16x16x32_bf16 v[78:81], v[178:181], v[138:141], v[78:81]
	s_add_u32 m0, s22, 0xc00
	v_add_u32_e32 v224, 0x8040, v217
	global_load_lds_dwordx4 v224, s[6:7]
	ds_read_b128 v[138:141], v216 offset:34816
	s_waitcnt lgkmcnt(7)
	v_mfma_f32_16x16x32_bf16 v[82:85], v[170:173], v[142:145], v[82:85]
	s_add_u32 m0, s22, 0x1000
	v_add_u32_e32 v223, 0x10000, v217
	global_load_lds_dwordx4 v223, s[6:7]
	v_mfma_f32_16x16x32_bf16 v[86:89], v[178:181], v[142:145], v[86:89]
	s_add_u32 m0, s22, 0x1400
	v_add_u32_e32 v224, 0x10040, v217
	global_load_lds_dwordx4 v224, s[6:7]
	ds_read_b128 v[142:145], v216 offset:36864
	s_waitcnt lgkmcnt(7)
	v_mfma_f32_16x16x32_bf16 v[90:93], v[170:173], v[146:149], v[90:93]
	s_add_u32 m0, s22, 0x1800
	v_add_u32_e32 v223, 0x18000, v217
	global_load_lds_dwordx4 v223, s[6:7]
	v_mfma_f32_16x16x32_bf16 v[94:97], v[178:181], v[146:149], v[94:97]
	s_add_u32 m0, s22, 0x1c00
	v_add_u32_e32 v224, 0x18040, v217
	global_load_lds_dwordx4 v224, s[6:7]
	ds_read_b128 v[146:149], v216 offset:38912
	s_waitcnt lgkmcnt(7)
	v_mfma_f32_16x16x32_bf16 v[98:101], v[170:173], v[150:153], v[98:101]
	v_mfma_f32_16x16x32_bf16 v[102:105], v[178:181], v[150:153], v[102:105]
	ds_read_b128 v[150:153], v216 offset:40960
	s_waitcnt lgkmcnt(7)
	v_mfma_f32_16x16x32_bf16 v[106:109], v[170:173], v[154:157], v[106:109]
	v_mfma_f32_16x16x32_bf16 v[110:113], v[178:181], v[154:157], v[110:113]
	ds_read_b128 v[154:157], v216 offset:43008
	s_waitcnt lgkmcnt(7)
	v_mfma_f32_16x16x32_bf16 v[114:117], v[170:173], v[158:161], v[114:117]
	v_mfma_f32_16x16x32_bf16 v[118:121], v[178:181], v[158:161], v[118:121]
	ds_read_b128 v[158:161], v216 offset:45056
	s_waitcnt lgkmcnt(7)
	v_mfma_f32_16x16x32_bf16 v[122:125], v[170:173], v[162:165], v[122:125]
	v_mfma_f32_16x16x32_bf16 v[126:129], v[178:181], v[162:165], v[126:129]
	v_add_u32_e32 v217, 0x80, v217
	v_add_u32_e32 v220, 0x800, v220
	v_add_u32_e32 v221, 0x800, v221
	s_lshr_b32 s3, s14, 4
	s_lshl_b32 s17, s15, 1
	s_add_u32 s3, s3, s17
	s_mul_i32 s17, s3, 0x8000
	s_add_u32 s8, s20, s17
	s_addc_u32 s9, s21, 0
	v_mov_b32_e32 v220, v222
	v_add_u32_e32 v221, 0x8000, v222
	ds_read_b128 v[162:165], v216 offset:47104
	s_waitcnt vmcnt(8) lgkmcnt(7)
	v_mfma_f32_16x16x32_bf16 v[2:5], v[196:199], v[134:137], v[2:5]
	v_mfma_f32_16x16x32_bf16 v[6:9], v[204:207], v[134:137], v[6:9]
	ds_read_b128 v[134:137], v216 offset:49152
	s_waitcnt lgkmcnt(7)
	v_mfma_f32_16x16x32_bf16 v[10:13], v[196:199], v[138:141], v[10:13]
	v_mfma_f32_16x16x32_bf16 v[14:17], v[204:207], v[138:141], v[14:17]
	ds_read_b128 v[138:141], v216 offset:51200
	s_waitcnt lgkmcnt(7)
	v_mfma_f32_16x16x32_bf16 v[18:21], v[196:199], v[142:145], v[18:21]
	v_mfma_f32_16x16x32_bf16 v[22:25], v[204:207], v[142:145], v[22:25]
	ds_read_b128 v[142:145], v216 offset:53248
	s_waitcnt lgkmcnt(7)
	v_mfma_f32_16x16x32_bf16 v[26:29], v[196:199], v[146:149], v[26:29]
	v_mfma_f32_16x16x32_bf16 v[30:33], v[204:207], v[146:149], v[30:33]
	ds_read_b128 v[146:149], v216 offset:55296
	s_waitcnt lgkmcnt(7)
	v_mfma_f32_16x16x32_bf16 v[34:37], v[196:199], v[150:153], v[34:37]
	global_load_dwordx4 v[166:169], v220, s[8:9]
	v_mfma_f32_16x16x32_bf16 v[38:41], v[204:207], v[150:153], v[38:41]
	global_load_dwordx4 v[170:173], v220, s[8:9] offset:1024
	ds_read_b128 v[150:153], v216 offset:57344
	s_waitcnt lgkmcnt(7)
	v_mfma_f32_16x16x32_bf16 v[42:45], v[196:199], v[154:157], v[42:45]
	global_load_dwordx4 v[174:177], v221, s[8:9]
	v_mfma_f32_16x16x32_bf16 v[46:49], v[204:207], v[154:157], v[46:49]
	global_load_dwordx4 v[178:181], v221, s[8:9] offset:1024
	ds_read_b128 v[154:157], v216 offset:59392
	s_waitcnt lgkmcnt(7)
	v_mfma_f32_16x16x32_bf16 v[50:53], v[196:199], v[158:161], v[50:53]
	v_mfma_f32_16x16x32_bf16 v[54:57], v[204:207], v[158:161], v[54:57]
	ds_read_b128 v[158:161], v216 offset:61440
	s_waitcnt lgkmcnt(7)
	v_mfma_f32_16x16x32_bf16 v[58:61], v[196:199], v[162:165], v[58:61]
	v_mfma_f32_16x16x32_bf16 v[62:65], v[204:207], v[162:165], v[62:65]
	ds_read_b128 v[162:165], v216 offset:63488
	s_waitcnt lgkmcnt(7)
	v_mfma_f32_16x16x32_bf16 v[66:69], v[196:199], v[134:137], v[66:69]
	v_mfma_f32_16x16x32_bf16 v[70:73], v[204:207], v[134:137], v[70:73]
	ds_read_b128 v[134:137], v216 offset:33792
	s_waitcnt lgkmcnt(7)
	v_mfma_f32_16x16x32_bf16 v[74:77], v[196:199], v[138:141], v[74:77]
	v_mfma_f32_16x16x32_bf16 v[78:81], v[204:207], v[138:141], v[78:81]
	ds_read_b128 v[138:141], v216 offset:35840
	s_waitcnt lgkmcnt(7)
	v_mfma_f32_16x16x32_bf16 v[82:85], v[196:199], v[142:145], v[82:85]
	v_mfma_f32_16x16x32_bf16 v[86:89], v[204:207], v[142:145], v[86:89]
	ds_read_b128 v[142:145], v216 offset:37888
	s_waitcnt lgkmcnt(7)
	v_mfma_f32_16x16x32_bf16 v[90:93], v[196:199], v[146:149], v[90:93]
	v_mfma_f32_16x16x32_bf16 v[94:97], v[204:207], v[146:149], v[94:97]
	ds_read_b128 v[146:149], v216 offset:39936
	s_waitcnt lgkmcnt(7)
	v_mfma_f32_16x16x32_bf16 v[98:101], v[196:199], v[150:153], v[98:101]
	v_mfma_f32_16x16x32_bf16 v[102:105], v[204:207], v[150:153], v[102:105]
	ds_read_b128 v[150:153], v216 offset:41984
	s_waitcnt lgkmcnt(7)
	v_mfma_f32_16x16x32_bf16 v[106:109], v[196:199], v[154:157], v[106:109]
	v_mfma_f32_16x16x32_bf16 v[110:113], v[204:207], v[154:157], v[110:113]
	ds_read_b128 v[154:157], v216 offset:44032
	s_waitcnt lgkmcnt(7)
	v_mfma_f32_16x16x32_bf16 v[114:117], v[196:199], v[158:161], v[114:117]
	v_mfma_f32_16x16x32_bf16 v[118:121], v[204:207], v[158:161], v[118:121]
	ds_read_b128 v[158:161], v216 offset:46080
	s_waitcnt lgkmcnt(7)
	v_mfma_f32_16x16x32_bf16 v[122:125], v[196:199], v[162:165], v[122:125]
	v_mfma_f32_16x16x32_bf16 v[126:129], v[204:207], v[162:165], v[126:129]
	ds_read_b128 v[162:165], v216 offset:48128
	s_waitcnt lgkmcnt(7)
	v_mfma_f32_16x16x32_bf16 v[2:5], v[200:203], v[134:137], v[2:5]
	v_mfma_f32_16x16x32_bf16 v[6:9], v[212:215], v[134:137], v[6:9]
	ds_read_b128 v[134:137], v216 offset:50176
	s_waitcnt lgkmcnt(7)
	v_mfma_f32_16x16x32_bf16 v[10:13], v[200:203], v[138:141], v[10:13]
	v_mfma_f32_16x16x32_bf16 v[14:17], v[212:215], v[138:141], v[14:17]
	ds_read_b128 v[138:141], v216 offset:52224
	s_waitcnt lgkmcnt(7)
	v_mfma_f32_16x16x32_bf16 v[18:21], v[200:203], v[142:145], v[18:21]
	v_mfma_f32_16x16x32_bf16 v[22:25], v[212:215], v[142:145], v[22:25]
	ds_read_b128 v[142:145], v216 offset:54272
	s_waitcnt lgkmcnt(7)
	v_mfma_f32_16x16x32_bf16 v[26:29], v[200:203], v[146:149], v[26:29]
	v_mfma_f32_16x16x32_bf16 v[30:33], v[212:215], v[146:149], v[30:33]
	ds_read_b128 v[146:149], v216 offset:56320
	s_waitcnt lgkmcnt(7)
	v_mfma_f32_16x16x32_bf16 v[34:37], v[200:203], v[150:153], v[34:37]
	v_mfma_f32_16x16x32_bf16 v[38:41], v[212:215], v[150:153], v[38:41]
	ds_read_b128 v[150:153], v216 offset:58368
	s_waitcnt lgkmcnt(7)
	v_mfma_f32_16x16x32_bf16 v[42:45], v[200:203], v[154:157], v[42:45]
	v_mfma_f32_16x16x32_bf16 v[46:49], v[212:215], v[154:157], v[46:49]
	ds_read_b128 v[154:157], v216 offset:60416
	s_waitcnt lgkmcnt(7)
	v_mfma_f32_16x16x32_bf16 v[50:53], v[200:203], v[158:161], v[50:53]
	v_mfma_f32_16x16x32_bf16 v[54:57], v[212:215], v[158:161], v[54:57]
	ds_read_b128 v[158:161], v216 offset:62464
	s_waitcnt lgkmcnt(7)
	v_mfma_f32_16x16x32_bf16 v[58:61], v[200:203], v[162:165], v[58:61]
	v_mfma_f32_16x16x32_bf16 v[62:65], v[212:215], v[162:165], v[62:65]
	ds_read_b128 v[162:165], v216 offset:64512
	s_waitcnt vmcnt(4) lgkmcnt(0)
	s_barrier
	v_mfma_f32_16x16x32_bf16 v[66:69], v[200:203], v[134:137], v[66:69]
	s_add_u32 m0, s22, 0x8000
	v_mov_b32_e32 v223, v217
	global_load_lds_dwordx4 v223, s[6:7]
	v_mfma_f32_16x16x32_bf16 v[70:73], v[212:215], v[134:137], v[70:73]
	s_add_u32 m0, s22, 0x8400
	v_add_u32_e32 v224, 0x40, v217
	global_load_lds_dwordx4 v224, s[6:7]
	ds_read_b128 v[134:137], v216
	s_waitcnt lgkmcnt(7)
	v_mfma_f32_16x16x32_bf16 v[74:77], v[200:203], v[138:141], v[74:77]
	s_add_u32 m0, s22, 0x8800
	v_add_u32_e32 v223, 0x8000, v217
	global_load_lds_dwordx4 v223, s[6:7]
	v_mfma_f32_16x16x32_bf16 v[78:81], v[212:215], v[138:141], v[78:81]
	s_add_u32 m0, s22, 0x8c00
	v_add_u32_e32 v224, 0x8040, v217
	global_load_lds_dwordx4 v224, s[6:7]
	ds_read_b128 v[138:141], v216 offset:2048
	s_waitcnt lgkmcnt(7)
	v_mfma_f32_16x16x32_bf16 v[82:85], v[200:203], v[142:145], v[82:85]
	s_add_u32 m0, s22, 0x9000
	v_add_u32_e32 v223, 0x10000, v217
	global_load_lds_dwordx4 v223, s[6:7]
	v_mfma_f32_16x16x32_bf16 v[86:89], v[212:215], v[142:145], v[86:89]
	s_add_u32 m0, s22, 0x9400
	v_add_u32_e32 v224, 0x10040, v217
	global_load_lds_dwordx4 v224, s[6:7]
	ds_read_b128 v[142:145], v216 offset:4096
	s_waitcnt lgkmcnt(7)
	v_mfma_f32_16x16x32_bf16 v[90:93], v[200:203], v[146:149], v[90:93]
	s_add_u32 m0, s22, 0x9800
	v_add_u32_e32 v223, 0x18000, v217
	global_load_lds_dwordx4 v223, s[6:7]
	v_mfma_f32_16x16x32_bf16 v[94:97], v[212:215], v[146:149], v[94:97]
	s_add_u32 m0, s22, 0x9c00
	v_add_u32_e32 v224, 0x18040, v217
	global_load_lds_dwordx4 v224, s[6:7]
	ds_read_b128 v[146:149], v216 offset:6144
	s_waitcnt lgkmcnt(7)
	v_mfma_f32_16x16x32_bf16 v[98:101], v[200:203], v[150:153], v[98:101]
	v_mfma_f32_16x16x32_bf16 v[102:105], v[212:215], v[150:153], v[102:105]
	ds_read_b128 v[150:153], v216 offset:8192
	s_waitcnt lgkmcnt(7)
	v_mfma_f32_16x16x32_bf16 v[106:109], v[200:203], v[154:157], v[106:109]
	v_mfma_f32_16x16x32_bf16 v[110:113], v[212:215], v[154:157], v[110:113]
	ds_read_b128 v[154:157], v216 offset:10240
	s_waitcnt lgkmcnt(7)
	v_mfma_f32_16x16x32_bf16 v[114:117], v[200:203], v[158:161], v[114:117]
	v_mfma_f32_16x16x32_bf16 v[118:121], v[212:215], v[158:161], v[118:121]
	ds_read_b128 v[158:161], v216 offset:12288
	s_waitcnt lgkmcnt(7)
	v_mfma_f32_16x16x32_bf16 v[122:125], v[200:203], v[162:165], v[122:125]
	v_mfma_f32_16x16x32_bf16 v[126:129], v[212:215], v[162:165], v[126:129]
	v_add_u32_e32 v217, 0x80, v217
	v_add_u32_e32 v220, 0x800, v220
	v_add_u32_e32 v221, 0x800, v221
	s_mov_b32 s16, 1
	s_branch .Lg256b_w1_epi

.Lg256b_wo_first_retry:
	s_cmp_ge_u32 s12, 64
	s_cbranch_scc1 .Lg256b_wo_done
	s_lshr_b32 s3, s12, 6
	s_lshl_b32 s3, s3, 3
	s_add_u32 s3, s3, s65
	s_mov_b32 s17, s3
	s_mov_b32 s3, 0
	s_lshl_b32 s17, s17, 3
	s_bfe_u32 s23, s12, 0x30003
	s_add_u32 s13, s17, s23
	s_lshl_b32 s3, s3, 3
	s_and_b32 s23, s12, 7
	s_add_u32 s14, s3, s23
	s_lshl_b32 s13, s13, 8
	s_lshl_b32 s14, s14, 7
	s_lshl_b32 s3, s15, 6
	s_add_u32 s17, s3, s13
	s_mul_i32 s17, s17, 0x800
	s_add_u32 s6, s18, s17
	s_addc_u32 s7, s19, 0
	s_lshr_b32 s3, s14, 4
	s_lshl_b32 s17, s15, 1
	s_add_u32 s3, s3, s17
	s_mul_i32 s17, s3, 0x8000
	s_add_u32 s8, s20, s17
	s_addc_u32 s9, s21, 0
	s_barrier
	v_mov_b32_e32 v217, v218
	v_mov_b32_e32 v220, v222
	v_add_u32_e32 v221, 0x8000, v222
	s_add_u32 m0, s22, 0x0
	v_mov_b32_e32 v223, v217
	global_load_lds_dwordx4 v223, s[6:7]
	s_add_u32 m0, s22, 0x400
	v_add_u32_e32 v224, 0x40, v217
	global_load_lds_dwordx4 v224, s[6:7]
	s_add_u32 m0, s22, 0x800
	v_add_u32_e32 v223, 0x8000, v217
	global_load_lds_dwordx4 v223, s[6:7]
	s_add_u32 m0, s22, 0xc00
	v_add_u32_e32 v224, 0x8040, v217
	global_load_lds_dwordx4 v224, s[6:7]
	s_add_u32 m0, s22, 0x1000
	v_add_u32_e32 v223, 0x10000, v217
	global_load_lds_dwordx4 v223, s[6:7]
	s_add_u32 m0, s22, 0x1400
	v_add_u32_e32 v224, 0x10040, v217
	global_load_lds_dwordx4 v224, s[6:7]
	s_add_u32 m0, s22, 0x1800
	v_add_u32_e32 v223, 0x18000, v217
	global_load_lds_dwordx4 v223, s[6:7]
	s_add_u32 m0, s22, 0x1c00
	v_add_u32_e32 v224, 0x18040, v217
	global_load_lds_dwordx4 v224, s[6:7]
	v_add_u32_e32 v217, 0x80, v217
	s_add_u32 m0, s22, 0x8000
	v_mov_b32_e32 v223, v217
	global_load_lds_dwordx4 v223, s[6:7]
	s_add_u32 m0, s22, 0x8400
	v_add_u32_e32 v224, 0x40, v217
	global_load_lds_dwordx4 v224, s[6:7]
	s_add_u32 m0, s22, 0x8800
	v_add_u32_e32 v223, 0x8000, v217
	global_load_lds_dwordx4 v223, s[6:7]
	s_add_u32 m0, s22, 0x8c00
	v_add_u32_e32 v224, 0x8040, v217
	global_load_lds_dwordx4 v224, s[6:7]
	s_add_u32 m0, s22, 0x9000
	v_add_u32_e32 v223, 0x10000, v217
	global_load_lds_dwordx4 v223, s[6:7]
	s_add_u32 m0, s22, 0x9400
	v_add_u32_e32 v224, 0x10040, v217
	global_load_lds_dwordx4 v224, s[6:7]
	s_add_u32 m0, s22, 0x9800
	v_add_u32_e32 v223, 0x18000, v217
	global_load_lds_dwordx4 v223, s[6:7]
	s_add_u32 m0, s22, 0x9c00
	v_add_u32_e32 v224, 0x18040, v217
	global_load_lds_dwordx4 v224, s[6:7]
	v_add_u32_e32 v217, 0x80, v217
	global_load_dwordx4 v[166:169], v220, s[8:9]
	global_load_dwordx4 v[170:173], v220, s[8:9] offset:1024
	global_load_dwordx4 v[174:177], v221, s[8:9]
	global_load_dwordx4 v[178:181], v221, s[8:9] offset:1024
	v_add_u32_e32 v220, 0x800, v220
	v_add_u32_e32 v221, 0x800, v221
	s_waitcnt vmcnt(0)
	s_barrier
	ds_read_b128 v[134:137], v216
	ds_read_b128 v[138:141], v216 offset:2048
	ds_read_b128 v[142:145], v216 offset:4096
	ds_read_b128 v[146:149], v216 offset:6144
	ds_read_b128 v[150:153], v216 offset:8192
	ds_read_b128 v[154:157], v216 offset:10240
	ds_read_b128 v[158:161], v216 offset:12288
.Lg256b_wo_tile:
	s_mul_i32 s17, s13, 0x1000
	s_lshl_b32 s3, s15, 5
	s_add_u32 s3, s3, s14
	s_mul_i32 s3, s3, 4
	s_add_u32 s17, s17, s3
	s_add_u32 s10, s24, s17
	s_addc_u32 s11, s25, 0
	s_lshl_b32 s3, s15, 5
	s_add_u32 s3, s3, s14
	s_lshl_b32 s3, s3, 2
	s_lshr_b32 s17, s13, 12
	s_max_u32 s17, s17, 1
	s_sub_u32 s17, s17, 1
	s_mul_i32 s17, s17, 24576
	s_add_u32 s3, s3, s17
	v_add_u32_e32 v234, s3, v225
	s_cmp_lg_u32 s62, 0
	s_cbranch_scc1 .Lg256b_wo_x_l1
	s_lshr_b32 s3, s13, 13
	s_lshl_b32 s3, s3, 3
	s_load_dwordx2 s[26:27], s[0:1], s3
	s_lshl_b32 s17, s13, 12
	s_and_b32 s17, s17, 0x1ffffff
	s_lshl_b32 s3, s15, 5
	s_add_u32 s3, s3, s14
	s_lshl_b32 s3, s3, 2
	s_add_u32 s17, s17, s3
	s_waitcnt lgkmcnt(7)
	s_waitcnt lgkmcnt(0)
	s_add_u32 s26, s26, s17
	s_addc_u32 s27, s27, 0
	s_branch .Lg256b_wo_x_go

.Lg256b_wo_x_go:
	ds_read_b128 v[162:165], v216 offset:14336
	s_waitcnt vmcnt(16) lgkmcnt(7)
	v_mfma_f32_16x16x32_bf16 v[2:5], v[166:169], v[134:137], 0
	v_mfma_f32_16x16x32_bf16 v[6:9], v[174:177], v[134:137], 0
	ds_read_b128 v[134:137], v216 offset:16384
	s_waitcnt lgkmcnt(7)
	v_mfma_f32_16x16x32_bf16 v[10:13], v[166:169], v[138:141], 0
	v_mfma_f32_16x16x32_bf16 v[14:17], v[174:177], v[138:141], 0
	ds_read_b128 v[138:141], v216 offset:18432
	s_waitcnt lgkmcnt(7)
	v_mfma_f32_16x16x32_bf16 v[18:21], v[166:169], v[142:145], 0
	v_mfma_f32_16x16x32_bf16 v[22:25], v[174:177], v[142:145], 0
	ds_read_b128 v[142:145], v216 offset:20480
	s_waitcnt lgkmcnt(7)
	v_mfma_f32_16x16x32_bf16 v[26:29], v[166:169], v[146:149], 0
	v_mfma_f32_16x16x32_bf16 v[30:33], v[174:177], v[146:149], 0
	ds_read_b128 v[146:149], v216 offset:22528
	s_waitcnt lgkmcnt(7)
	v_mfma_f32_16x16x32_bf16 v[34:37], v[166:169], v[150:153], 0
	global_load_dwordx4 v[196:199], v220, s[8:9]
	v_mfma_f32_16x16x32_bf16 v[38:41], v[174:177], v[150:153], 0
	global_load_dwordx4 v[200:203], v220, s[8:9] offset:1024
	ds_read_b128 v[150:153], v216 offset:24576
	s_waitcnt lgkmcnt(7)
	v_mfma_f32_16x16x32_bf16 v[42:45], v[166:169], v[154:157], 0
	global_load_dwordx4 v[204:207], v221, s[8:9]
	v_mfma_f32_16x16x32_bf16 v[46:49], v[174:177], v[154:157], 0
	global_load_dwordx4 v[212:215], v221, s[8:9] offset:1024
	ds_read_b128 v[154:157], v216 offset:26624
	s_waitcnt lgkmcnt(7)
	v_mfma_f32_16x16x32_bf16 v[50:53], v[166:169], v[158:161], 0
	v_mfma_f32_16x16x32_bf16 v[54:57], v[174:177], v[158:161], 0
	ds_read_b128 v[158:161], v216 offset:28672
	s_waitcnt lgkmcnt(7)
	v_mfma_f32_16x16x32_bf16 v[58:61], v[166:169], v[162:165], 0
	v_mfma_f32_16x16x32_bf16 v[62:65], v[174:177], v[162:165], 0
	ds_read_b128 v[162:165], v216 offset:30720
	s_waitcnt lgkmcnt(7)
	v_mfma_f32_16x16x32_bf16 v[66:69], v[166:169], v[134:137], 0
	v_mfma_f32_16x16x32_bf16 v[70:73], v[174:177], v[134:137], 0
	ds_read_b128 v[134:137], v216 offset:1024
	s_waitcnt lgkmcnt(7)
	v_mfma_f32_16x16x32_bf16 v[74:77], v[166:169], v[138:141], 0
	v_mfma_f32_16x16x32_bf16 v[78:81], v[174:177], v[138:141], 0
	ds_read_b128 v[138:141], v216 offset:3072
	s_waitcnt lgkmcnt(7)
	v_mfma_f32_16x16x32_bf16 v[82:85], v[166:169], v[142:145], 0
	v_mfma_f32_16x16x32_bf16 v[86:89], v[174:177], v[142:145], 0
	ds_read_b128 v[142:145], v216 offset:5120
	s_waitcnt lgkmcnt(7)
	v_mfma_f32_16x16x32_bf16 v[90:93], v[166:169], v[146:149], 0
	v_mfma_f32_16x16x32_bf16 v[94:97], v[174:177], v[146:149], 0
	ds_read_b128 v[146:149], v216 offset:7168
	s_waitcnt lgkmcnt(7)
	v_mfma_f32_16x16x32_bf16 v[98:101], v[166:169], v[150:153], 0
	v_mfma_f32_16x16x32_bf16 v[102:105], v[174:177], v[150:153], 0
	ds_read_b128 v[150:153], v216 offset:9216
	s_waitcnt lgkmcnt(7)
	v_mfma_f32_16x16x32_bf16 v[106:109], v[166:169], v[154:157], 0
	v_mfma_f32_16x16x32_bf16 v[110:113], v[174:177], v[154:157], 0
	ds_read_b128 v[154:157], v216 offset:11264
	s_waitcnt lgkmcnt(7)
	v_mfma_f32_16x16x32_bf16 v[114:117], v[166:169], v[158:161], 0
	v_mfma_f32_16x16x32_bf16 v[118:121], v[174:177], v[158:161], 0
	ds_read_b128 v[158:161], v216 offset:13312
	s_waitcnt lgkmcnt(7)
	v_mfma_f32_16x16x32_bf16 v[122:125], v[166:169], v[162:165], 0
	v_mfma_f32_16x16x32_bf16 v[126:129], v[174:177], v[162:165], 0
	ds_read_b128 v[162:165], v216 offset:15360
	s_waitcnt lgkmcnt(7)
	v_mfma_f32_16x16x32_bf16 v[2:5], v[170:173], v[134:137], v[2:5]
	v_mfma_f32_16x16x32_bf16 v[6:9], v[178:181], v[134:137], v[6:9]
	ds_read_b128 v[134:137], v216 offset:17408
	s_waitcnt lgkmcnt(7)
	v_mfma_f32_16x16x32_bf16 v[10:13], v[170:173], v[138:141], v[10:13]
	v_mfma_f32_16x16x32_bf16 v[14:17], v[178:181], v[138:141], v[14:17]
	ds_read_b128 v[138:141], v216 offset:19456
	s_waitcnt lgkmcnt(7)
	v_mfma_f32_16x16x32_bf16 v[18:21], v[170:173], v[142:145], v[18:21]
	v_mfma_f32_16x16x32_bf16 v[22:25], v[178:181], v[142:145], v[22:25]
	ds_read_b128 v[142:145], v216 offset:21504
	s_waitcnt lgkmcnt(7)
	v_mfma_f32_16x16x32_bf16 v[26:29], v[170:173], v[146:149], v[26:29]
	v_mfma_f32_16x16x32_bf16 v[30:33], v[178:181], v[146:149], v[30:33]
	ds_read_b128 v[146:149], v216 offset:23552
	s_waitcnt lgkmcnt(7)
	v_mfma_f32_16x16x32_bf16 v[34:37], v[170:173], v[150:153], v[34:37]
	v_mfma_f32_16x16x32_bf16 v[38:41], v[178:181], v[150:153], v[38:41]
	ds_read_b128 v[150:153], v216 offset:25600
	s_waitcnt lgkmcnt(7)
	v_mfma_f32_16x16x32_bf16 v[42:45], v[170:173], v[154:157], v[42:45]
	v_mfma_f32_16x16x32_bf16 v[46:49], v[178:181], v[154:157], v[46:49]
	ds_read_b128 v[154:157], v216 offset:27648
	s_waitcnt lgkmcnt(7)
	v_mfma_f32_16x16x32_bf16 v[50:53], v[170:173], v[158:161], v[50:53]
	v_mfma_f32_16x16x32_bf16 v[54:57], v[178:181], v[158:161], v[54:57]
	ds_read_b128 v[158:161], v216 offset:29696
	s_waitcnt lgkmcnt(7)
	v_mfma_f32_16x16x32_bf16 v[58:61], v[170:173], v[162:165], v[58:61]
	v_mfma_f32_16x16x32_bf16 v[62:65], v[178:181], v[162:165], v[62:65]
	ds_read_b128 v[162:165], v216 offset:31744
	s_waitcnt vmcnt(12) lgkmcnt(0)
	s_barrier
	v_mfma_f32_16x16x32_bf16 v[66:69], v[170:173], v[134:137], v[66:69]
	s_add_u32 m0, s22, 0x0
	v_mov_b32_e32 v223, v217
	global_load_lds_dwordx4 v223, s[6:7]
	v_mfma_f32_16x16x32_bf16 v[70:73], v[178:181], v[134:137], v[70:73]
	s_add_u32 m0, s22, 0x400
	v_add_u32_e32 v224, 0x40, v217
	global_load_lds_dwordx4 v224, s[6:7]
	ds_read_b128 v[134:137], v216 offset:32768
	s_waitcnt lgkmcnt(7)
	v_mfma_f32_16x16x32_bf16 v[74:77], v[170:173], v[138:141], v[74:77]
	s_add_u32 m0, s22, 0x800
	v_add_u32_e32 v223, 0x8000, v217
	global_load_lds_dwordx4 v223, s[6:7]
	v_mfma_f32_16x16x32_bf16 v[78:81], v[178:181], v[138:141], v[78:81]
	s_add_u32 m0, s22, 0xc00
	v_add_u32_e32 v224, 0x8040, v217
	global_load_lds_dwordx4 v224, s[6:7]
	ds_read_b128 v[138:141], v216 offset:34816
	s_waitcnt lgkmcnt(7)
	v_mfma_f32_16x16x32_bf16 v[82:85], v[170:173], v[142:145], v[82:85]
	s_add_u32 m0, s22, 0x1000
	v_add_u32_e32 v223, 0x10000, v217
	global_load_lds_dwordx4 v223, s[6:7]
	v_mfma_f32_16x16x32_bf16 v[86:89], v[178:181], v[142:145], v[86:89]
	s_add_u32 m0, s22, 0x1400
	v_add_u32_e32 v224, 0x10040, v217
	global_load_lds_dwordx4 v224, s[6:7]
	ds_read_b128 v[142:145], v216 offset:36864
	s_waitcnt lgkmcnt(7)
	v_mfma_f32_16x16x32_bf16 v[90:93], v[170:173], v[146:149], v[90:93]
	s_add_u32 m0, s22, 0x1800
	v_add_u32_e32 v223, 0x18000, v217
	global_load_lds_dwordx4 v223, s[6:7]
	v_mfma_f32_16x16x32_bf16 v[94:97], v[178:181], v[146:149], v[94:97]
	s_add_u32 m0, s22, 0x1c00
	v_add_u32_e32 v224, 0x18040, v217
	global_load_lds_dwordx4 v224, s[6:7]
	ds_read_b128 v[146:149], v216 offset:38912
	s_waitcnt lgkmcnt(7)
	v_mfma_f32_16x16x32_bf16 v[98:101], v[170:173], v[150:153], v[98:101]
	v_mfma_f32_16x16x32_bf16 v[102:105], v[178:181], v[150:153], v[102:105]
	ds_read_b128 v[150:153], v216 offset:40960
	s_waitcnt lgkmcnt(7)
	v_mfma_f32_16x16x32_bf16 v[106:109], v[170:173], v[154:157], v[106:109]
	v_mfma_f32_16x16x32_bf16 v[110:113], v[178:181], v[154:157], v[110:113]
	ds_read_b128 v[154:157], v216 offset:43008
	s_waitcnt lgkmcnt(7)
	v_mfma_f32_16x16x32_bf16 v[114:117], v[170:173], v[158:161], v[114:117]
	v_mfma_f32_16x16x32_bf16 v[118:121], v[178:181], v[158:161], v[118:121]
	ds_read_b128 v[158:161], v216 offset:45056
	s_waitcnt lgkmcnt(7)
	v_mfma_f32_16x16x32_bf16 v[122:125], v[170:173], v[162:165], v[122:125]
	v_mfma_f32_16x16x32_bf16 v[126:129], v[178:181], v[162:165], v[126:129]
	v_add_u32_e32 v217, 0x80, v217
	v_add_u32_e32 v220, 0x800, v220
	v_add_u32_e32 v221, 0x800, v221
	ds_read_b128 v[162:165], v216 offset:47104
	s_waitcnt vmcnt(8) lgkmcnt(7)
	v_mfma_f32_16x16x32_bf16 v[2:5], v[196:199], v[134:137], v[2:5]
	v_mfma_f32_16x16x32_bf16 v[6:9], v[204:207], v[134:137], v[6:9]
	ds_read_b128 v[134:137], v216 offset:49152
	s_waitcnt lgkmcnt(7)
	v_mfma_f32_16x16x32_bf16 v[10:13], v[196:199], v[138:141], v[10:13]
	v_mfma_f32_16x16x32_bf16 v[14:17], v[204:207], v[138:141], v[14:17]
	ds_read_b128 v[138:141], v216 offset:51200
	s_waitcnt lgkmcnt(7)
	v_mfma_f32_16x16x32_bf16 v[18:21], v[196:199], v[142:145], v[18:21]
	v_mfma_f32_16x16x32_bf16 v[22:25], v[204:207], v[142:145], v[22:25]
	ds_read_b128 v[142:145], v216 offset:53248
	s_waitcnt lgkmcnt(7)
	v_mfma_f32_16x16x32_bf16 v[26:29], v[196:199], v[146:149], v[26:29]
	v_mfma_f32_16x16x32_bf16 v[30:33], v[204:207], v[146:149], v[30:33]
	ds_read_b128 v[146:149], v216 offset:55296
	s_waitcnt lgkmcnt(7)
	v_mfma_f32_16x16x32_bf16 v[34:37], v[196:199], v[150:153], v[34:37]
	global_load_dwordx4 v[166:169], v220, s[8:9]
	v_mfma_f32_16x16x32_bf16 v[38:41], v[204:207], v[150:153], v[38:41]
	global_load_dwordx4 v[170:173], v220, s[8:9] offset:1024
	ds_read_b128 v[150:153], v216 offset:57344
	s_waitcnt lgkmcnt(7)
	v_mfma_f32_16x16x32_bf16 v[42:45], v[196:199], v[154:157], v[42:45]
	global_load_dwordx4 v[174:177], v221, s[8:9]
	v_mfma_f32_16x16x32_bf16 v[46:49], v[204:207], v[154:157], v[46:49]
	global_load_dwordx4 v[178:181], v221, s[8:9] offset:1024
	ds_read_b128 v[154:157], v216 offset:59392
	s_waitcnt lgkmcnt(7)
	v_mfma_f32_16x16x32_bf16 v[50:53], v[196:199], v[158:161], v[50:53]
	v_mfma_f32_16x16x32_bf16 v[54:57], v[204:207], v[158:161], v[54:57]
	ds_read_b128 v[158:161], v216 offset:61440
	s_waitcnt lgkmcnt(7)
	v_mfma_f32_16x16x32_bf16 v[58:61], v[196:199], v[162:165], v[58:61]
	v_mfma_f32_16x16x32_bf16 v[62:65], v[204:207], v[162:165], v[62:65]
	ds_read_b128 v[162:165], v216 offset:63488
	s_waitcnt lgkmcnt(7)
	v_mfma_f32_16x16x32_bf16 v[66:69], v[196:199], v[134:137], v[66:69]
	v_mfma_f32_16x16x32_bf16 v[70:73], v[204:207], v[134:137], v[70:73]
	ds_read_b128 v[134:137], v216 offset:33792
	s_waitcnt lgkmcnt(7)
	v_mfma_f32_16x16x32_bf16 v[74:77], v[196:199], v[138:141], v[74:77]
	v_mfma_f32_16x16x32_bf16 v[78:81], v[204:207], v[138:141], v[78:81]
	ds_read_b128 v[138:141], v216 offset:35840
	s_waitcnt lgkmcnt(7)
	v_mfma_f32_16x16x32_bf16 v[82:85], v[196:199], v[142:145], v[82:85]
	v_mfma_f32_16x16x32_bf16 v[86:89], v[204:207], v[142:145], v[86:89]
	ds_read_b128 v[142:145], v216 offset:37888
	s_waitcnt lgkmcnt(7)
	v_mfma_f32_16x16x32_bf16 v[90:93], v[196:199], v[146:149], v[90:93]
	v_mfma_f32_16x16x32_bf16 v[94:97], v[204:207], v[146:149], v[94:97]
	ds_read_b128 v[146:149], v216 offset:39936
	s_waitcnt lgkmcnt(7)
	v_mfma_f32_16x16x32_bf16 v[98:101], v[196:199], v[150:153], v[98:101]
	v_mfma_f32_16x16x32_bf16 v[102:105], v[204:207], v[150:153], v[102:105]
	ds_read_b128 v[150:153], v216 offset:41984
	s_waitcnt lgkmcnt(7)
	v_mfma_f32_16x16x32_bf16 v[106:109], v[196:199], v[154:157], v[106:109]
	v_mfma_f32_16x16x32_bf16 v[110:113], v[204:207], v[154:157], v[110:113]
	ds_read_b128 v[154:157], v216 offset:44032
	s_waitcnt lgkmcnt(7)
	v_mfma_f32_16x16x32_bf16 v[114:117], v[196:199], v[158:161], v[114:117]
	v_mfma_f32_16x16x32_bf16 v[118:121], v[204:207], v[158:161], v[118:121]
	ds_read_b128 v[158:161], v216 offset:46080
	s_waitcnt lgkmcnt(7)
	v_mfma_f32_16x16x32_bf16 v[122:125], v[196:199], v[162:165], v[122:125]
	v_mfma_f32_16x16x32_bf16 v[126:129], v[204:207], v[162:165], v[126:129]
	ds_read_b128 v[162:165], v216 offset:48128
	s_waitcnt lgkmcnt(7)
	v_mfma_f32_16x16x32_bf16 v[2:5], v[200:203], v[134:137], v[2:5]
	v_mfma_f32_16x16x32_bf16 v[6:9], v[212:215], v[134:137], v[6:9]
	ds_read_b128 v[134:137], v216 offset:50176
	s_waitcnt lgkmcnt(7)
	v_mfma_f32_16x16x32_bf16 v[10:13], v[200:203], v[138:141], v[10:13]
	v_mfma_f32_16x16x32_bf16 v[14:17], v[212:215], v[138:141], v[14:17]
	ds_read_b128 v[138:141], v216 offset:52224
	s_waitcnt lgkmcnt(7)
	v_mfma_f32_16x16x32_bf16 v[18:21], v[200:203], v[142:145], v[18:21]
	v_mfma_f32_16x16x32_bf16 v[22:25], v[212:215], v[142:145], v[22:25]
	ds_read_b128 v[142:145], v216 offset:54272
	s_waitcnt lgkmcnt(7)
	v_mfma_f32_16x16x32_bf16 v[26:29], v[200:203], v[146:149], v[26:29]
	v_mfma_f32_16x16x32_bf16 v[30:33], v[212:215], v[146:149], v[30:33]
	ds_read_b128 v[146:149], v216 offset:56320
	s_waitcnt lgkmcnt(7)
	v_mfma_f32_16x16x32_bf16 v[34:37], v[200:203], v[150:153], v[34:37]
	v_mfma_f32_16x16x32_bf16 v[38:41], v[212:215], v[150:153], v[38:41]
	ds_read_b128 v[150:153], v216 offset:58368
	s_waitcnt lgkmcnt(7)
	v_mfma_f32_16x16x32_bf16 v[42:45], v[200:203], v[154:157], v[42:45]
	v_mfma_f32_16x16x32_bf16 v[46:49], v[212:215], v[154:157], v[46:49]
	ds_read_b128 v[154:157], v216 offset:60416
	s_waitcnt lgkmcnt(7)
	v_mfma_f32_16x16x32_bf16 v[50:53], v[200:203], v[158:161], v[50:53]
	v_mfma_f32_16x16x32_bf16 v[54:57], v[212:215], v[158:161], v[54:57]
	ds_read_b128 v[158:161], v216 offset:62464
	s_waitcnt lgkmcnt(7)
	v_mfma_f32_16x16x32_bf16 v[58:61], v[200:203], v[162:165], v[58:61]
	v_mfma_f32_16x16x32_bf16 v[62:65], v[212:215], v[162:165], v[62:65]
	ds_read_b128 v[162:165], v216 offset:64512
	s_waitcnt vmcnt(4) lgkmcnt(0)
	s_barrier
	v_mfma_f32_16x16x32_bf16 v[66:69], v[200:203], v[134:137], v[66:69]
	s_add_u32 m0, s22, 0x8000
	v_mov_b32_e32 v223, v217
	global_load_lds_dwordx4 v223, s[6:7]
	v_mfma_f32_16x16x32_bf16 v[70:73], v[212:215], v[134:137], v[70:73]
	s_add_u32 m0, s22, 0x8400
	v_add_u32_e32 v224, 0x40, v217
	global_load_lds_dwordx4 v224, s[6:7]
	ds_read_b128 v[134:137], v216
	s_waitcnt lgkmcnt(7)
	v_mfma_f32_16x16x32_bf16 v[74:77], v[200:203], v[138:141], v[74:77]
	s_add_u32 m0, s22, 0x8800
	v_add_u32_e32 v223, 0x8000, v217
	global_load_lds_dwordx4 v223, s[6:7]
	v_mfma_f32_16x16x32_bf16 v[78:81], v[212:215], v[138:141], v[78:81]
	s_add_u32 m0, s22, 0x8c00
	v_add_u32_e32 v224, 0x8040, v217
	global_load_lds_dwordx4 v224, s[6:7]
	ds_read_b128 v[138:141], v216 offset:2048
	s_waitcnt lgkmcnt(7)
	v_mfma_f32_16x16x32_bf16 v[82:85], v[200:203], v[142:145], v[82:85]
	s_add_u32 m0, s22, 0x9000
	v_add_u32_e32 v223, 0x10000, v217
	global_load_lds_dwordx4 v223, s[6:7]
	v_mfma_f32_16x16x32_bf16 v[86:89], v[212:215], v[142:145], v[86:89]
	s_add_u32 m0, s22, 0x9400
	v_add_u32_e32 v224, 0x10040, v217
	global_load_lds_dwordx4 v224, s[6:7]
	ds_read_b128 v[142:145], v216 offset:4096
	s_waitcnt lgkmcnt(7)
	v_mfma_f32_16x16x32_bf16 v[90:93], v[200:203], v[146:149], v[90:93]
	s_add_u32 m0, s22, 0x9800
	v_add_u32_e32 v223, 0x18000, v217
	global_load_lds_dwordx4 v223, s[6:7]
	v_mfma_f32_16x16x32_bf16 v[94:97], v[212:215], v[146:149], v[94:97]
	s_add_u32 m0, s22, 0x9c00
	v_add_u32_e32 v224, 0x18040, v217
	global_load_lds_dwordx4 v224, s[6:7]
	ds_read_b128 v[146:149], v216 offset:6144
	s_waitcnt lgkmcnt(7)
	v_mfma_f32_16x16x32_bf16 v[98:101], v[200:203], v[150:153], v[98:101]
	v_mfma_f32_16x16x32_bf16 v[102:105], v[212:215], v[150:153], v[102:105]
	ds_read_b128 v[150:153], v216 offset:8192
	s_waitcnt lgkmcnt(7)
	v_mfma_f32_16x16x32_bf16 v[106:109], v[200:203], v[154:157], v[106:109]
	v_mfma_f32_16x16x32_bf16 v[110:113], v[212:215], v[154:157], v[110:113]
	ds_read_b128 v[154:157], v216 offset:10240
	s_waitcnt lgkmcnt(7)
	v_mfma_f32_16x16x32_bf16 v[114:117], v[200:203], v[158:161], v[114:117]
	v_mfma_f32_16x16x32_bf16 v[118:121], v[212:215], v[158:161], v[118:121]
	ds_read_b128 v[158:161], v216 offset:12288
	s_waitcnt lgkmcnt(7)
	v_mfma_f32_16x16x32_bf16 v[122:125], v[200:203], v[162:165], v[122:125]
	v_mfma_f32_16x16x32_bf16 v[126:129], v[212:215], v[162:165], v[126:129]
	v_add_u32_e32 v217, 0x80, v217
	v_add_u32_e32 v220, 0x800, v220
	v_add_u32_e32 v221, 0x800, v221
	s_mov_b32 s16, 6

.Lg256b_wo_next_retry:
	s_cmp_ge_u32 s12, 64
	s_cbranch_scc1 .Lg256b_wo_nonext
	s_lshr_b32 s3, s12, 6
	s_lshl_b32 s3, s3, 3
	s_add_u32 s3, s3, s65
	s_mov_b32 s17, s3
	s_mov_b32 s3, 0
	s_lshl_b32 s17, s17, 3
	s_bfe_u32 s23, s12, 0x30003
	s_add_u32 s13, s17, s23
	s_lshl_b32 s3, s3, 3
	s_and_b32 s23, s12, 7
	s_add_u32 s14, s3, s23
	s_lshl_b32 s13, s13, 8
	s_lshl_b32 s14, s14, 7
	s_lshl_b32 s3, s15, 6
	s_add_u32 s17, s3, s13
	s_mul_i32 s17, s17, 0x800
	s_add_u32 s6, s18, s17
	s_addc_u32 s7, s19, 0
	v_mov_b32_e32 v217, v218
	ds_read_b128 v[162:165], v216 offset:14336
	s_waitcnt vmcnt(8) lgkmcnt(7)
	v_mfma_f32_16x16x32_bf16 v[2:5], v[166:169], v[134:137], v[2:5]
	v_mfma_f32_16x16x32_bf16 v[6:9], v[174:177], v[134:137], v[6:9]
	ds_read_b128 v[134:137], v216 offset:16384
	s_waitcnt lgkmcnt(7)
	v_mfma_f32_16x16x32_bf16 v[10:13], v[166:169], v[138:141], v[10:13]
	v_mfma_f32_16x16x32_bf16 v[14:17], v[174:177], v[138:141], v[14:17]
	ds_read_b128 v[138:141], v216 offset:18432
	s_waitcnt lgkmcnt(7)
	v_mfma_f32_16x16x32_bf16 v[18:21], v[166:169], v[142:145], v[18:21]
	v_mfma_f32_16x16x32_bf16 v[22:25], v[174:177], v[142:145], v[22:25]
	ds_read_b128 v[142:145], v216 offset:20480
	s_waitcnt lgkmcnt(7)
	v_mfma_f32_16x16x32_bf16 v[26:29], v[166:169], v[146:149], v[26:29]
	v_mfma_f32_16x16x32_bf16 v[30:33], v[174:177], v[146:149], v[30:33]
	ds_read_b128 v[146:149], v216 offset:22528
	s_waitcnt lgkmcnt(7)
	v_mfma_f32_16x16x32_bf16 v[34:37], v[166:169], v[150:153], v[34:37]
	global_load_dwordx4 v[196:199], v220, s[8:9]
	v_mfma_f32_16x16x32_bf16 v[38:41], v[174:177], v[150:153], v[38:41]
	global_load_dwordx4 v[200:203], v220, s[8:9] offset:1024
	ds_read_b128 v[150:153], v216 offset:24576
	s_waitcnt lgkmcnt(7)
	v_mfma_f32_16x16x32_bf16 v[42:45], v[166:169], v[154:157], v[42:45]
	global_load_dwordx4 v[204:207], v221, s[8:9]
	v_mfma_f32_16x16x32_bf16 v[46:49], v[174:177], v[154:157], v[46:49]
	global_load_dwordx4 v[212:215], v221, s[8:9] offset:1024
	ds_read_b128 v[154:157], v216 offset:26624
	s_waitcnt lgkmcnt(7)
	v_mfma_f32_16x16x32_bf16 v[50:53], v[166:169], v[158:161], v[50:53]
	v_mfma_f32_16x16x32_bf16 v[54:57], v[174:177], v[158:161], v[54:57]
	ds_read_b128 v[158:161], v216 offset:28672
	s_waitcnt lgkmcnt(7)
	v_mfma_f32_16x16x32_bf16 v[58:61], v[166:169], v[162:165], v[58:61]
	v_mfma_f32_16x16x32_bf16 v[62:65], v[174:177], v[162:165], v[62:65]
	ds_read_b128 v[162:165], v216 offset:30720
	s_waitcnt lgkmcnt(7)
	v_mfma_f32_16x16x32_bf16 v[66:69], v[166:169], v[134:137], v[66:69]
	v_mfma_f32_16x16x32_bf16 v[70:73], v[174:177], v[134:137], v[70:73]
	ds_read_b128 v[134:137], v216 offset:1024
	s_waitcnt lgkmcnt(7)
	v_mfma_f32_16x16x32_bf16 v[74:77], v[166:169], v[138:141], v[74:77]
	v_mfma_f32_16x16x32_bf16 v[78:81], v[174:177], v[138:141], v[78:81]
	ds_read_b128 v[138:141], v216 offset:3072
	s_waitcnt lgkmcnt(7)
	v_mfma_f32_16x16x32_bf16 v[82:85], v[166:169], v[142:145], v[82:85]
	v_mfma_f32_16x16x32_bf16 v[86:89], v[174:177], v[142:145], v[86:89]
	ds_read_b128 v[142:145], v216 offset:5120
	s_waitcnt lgkmcnt(7)
	v_mfma_f32_16x16x32_bf16 v[90:93], v[166:169], v[146:149], v[90:93]
	v_mfma_f32_16x16x32_bf16 v[94:97], v[174:177], v[146:149], v[94:97]
	ds_read_b128 v[146:149], v216 offset:7168
	s_waitcnt lgkmcnt(7)
	v_mfma_f32_16x16x32_bf16 v[98:101], v[166:169], v[150:153], v[98:101]
	v_mfma_f32_16x16x32_bf16 v[102:105], v[174:177], v[150:153], v[102:105]
	ds_read_b128 v[150:153], v216 offset:9216
	s_waitcnt lgkmcnt(7)
	v_mfma_f32_16x16x32_bf16 v[106:109], v[166:169], v[154:157], v[106:109]
	v_mfma_f32_16x16x32_bf16 v[110:113], v[174:177], v[154:157], v[110:113]
	ds_read_b128 v[154:157], v216 offset:11264
	s_waitcnt lgkmcnt(7)
	v_mfma_f32_16x16x32_bf16 v[114:117], v[166:169], v[158:161], v[114:117]
	v_mfma_f32_16x16x32_bf16 v[118:121], v[174:177], v[158:161], v[118:121]
	ds_read_b128 v[158:161], v216 offset:13312
	s_waitcnt lgkmcnt(7)
	v_mfma_f32_16x16x32_bf16 v[122:125], v[166:169], v[162:165], v[122:125]
	v_mfma_f32_16x16x32_bf16 v[126:129], v[174:177], v[162:165], v[126:129]
	ds_read_b128 v[162:165], v216 offset:15360
	s_waitcnt lgkmcnt(7)
	v_mfma_f32_16x16x32_bf16 v[2:5], v[170:173], v[134:137], v[2:5]
	v_mfma_f32_16x16x32_bf16 v[6:9], v[178:181], v[134:137], v[6:9]
	ds_read_b128 v[134:137], v216 offset:17408
	s_waitcnt lgkmcnt(7)
	v_mfma_f32_16x16x32_bf16 v[10:13], v[170:173], v[138:141], v[10:13]
	v_mfma_f32_16x16x32_bf16 v[14:17], v[178:181], v[138:141], v[14:17]
	ds_read_b128 v[138:141], v216 offset:19456
	s_waitcnt lgkmcnt(7)
	v_mfma_f32_16x16x32_bf16 v[18:21], v[170:173], v[142:145], v[18:21]
	v_mfma_f32_16x16x32_bf16 v[22:25], v[178:181], v[142:145], v[22:25]
	ds_read_b128 v[142:145], v216 offset:21504
	s_waitcnt lgkmcnt(7)
	v_mfma_f32_16x16x32_bf16 v[26:29], v[170:173], v[146:149], v[26:29]
	v_mfma_f32_16x16x32_bf16 v[30:33], v[178:181], v[146:149], v[30:33]
	ds_read_b128 v[146:149], v216 offset:23552
	s_waitcnt lgkmcnt(7)
	v_mfma_f32_16x16x32_bf16 v[34:37], v[170:173], v[150:153], v[34:37]
	v_mfma_f32_16x16x32_bf16 v[38:41], v[178:181], v[150:153], v[38:41]
	ds_read_b128 v[150:153], v216 offset:25600
	s_waitcnt lgkmcnt(7)
	v_mfma_f32_16x16x32_bf16 v[42:45], v[170:173], v[154:157], v[42:45]
	v_mfma_f32_16x16x32_bf16 v[46:49], v[178:181], v[154:157], v[46:49]
	ds_read_b128 v[154:157], v216 offset:27648
	s_waitcnt lgkmcnt(7)
	v_mfma_f32_16x16x32_bf16 v[50:53], v[170:173], v[158:161], v[50:53]
	v_mfma_f32_16x16x32_bf16 v[54:57], v[178:181], v[158:161], v[54:57]
	ds_read_b128 v[158:161], v216 offset:29696
	s_waitcnt lgkmcnt(7)
	v_mfma_f32_16x16x32_bf16 v[58:61], v[170:173], v[162:165], v[58:61]
	v_mfma_f32_16x16x32_bf16 v[62:65], v[178:181], v[162:165], v[62:65]
	ds_read_b128 v[162:165], v216 offset:31744
	s_waitcnt vmcnt(4) lgkmcnt(0)
	s_barrier
	v_mfma_f32_16x16x32_bf16 v[66:69], v[170:173], v[134:137], v[66:69]
	s_add_u32 m0, s22, 0x0
	v_mov_b32_e32 v223, v217
	global_load_lds_dwordx4 v223, s[6:7]
	v_mfma_f32_16x16x32_bf16 v[70:73], v[178:181], v[134:137], v[70:73]
	s_add_u32 m0, s22, 0x400
	v_add_u32_e32 v224, 0x40, v217
	global_load_lds_dwordx4 v224, s[6:7]
	ds_read_b128 v[134:137], v216 offset:32768
	s_waitcnt lgkmcnt(7)
	v_mfma_f32_16x16x32_bf16 v[74:77], v[170:173], v[138:141], v[74:77]
	s_add_u32 m0, s22, 0x800
	v_add_u32_e32 v223, 0x8000, v217
	global_load_lds_dwordx4 v223, s[6:7]
	v_mfma_f32_16x16x32_bf16 v[78:81], v[178:181], v[138:141], v[78:81]
	s_add_u32 m0, s22, 0xc00
	v_add_u32_e32 v224, 0x8040, v217
	global_load_lds_dwordx4 v224, s[6:7]
	ds_read_b128 v[138:141], v216 offset:34816
	s_waitcnt lgkmcnt(7)
	v_mfma_f32_16x16x32_bf16 v[82:85], v[170:173], v[142:145], v[82:85]
	s_add_u32 m0, s22, 0x1000
	v_add_u32_e32 v223, 0x10000, v217
	global_load_lds_dwordx4 v223, s[6:7]
	v_mfma_f32_16x16x32_bf16 v[86:89], v[178:181], v[142:145], v[86:89]
	s_add_u32 m0, s22, 0x1400
	v_add_u32_e32 v224, 0x10040, v217
	global_load_lds_dwordx4 v224, s[6:7]
	ds_read_b128 v[142:145], v216 offset:36864
	s_waitcnt lgkmcnt(7)
	v_mfma_f32_16x16x32_bf16 v[90:93], v[170:173], v[146:149], v[90:93]
	s_add_u32 m0, s22, 0x1800
	v_add_u32_e32 v223, 0x18000, v217
	global_load_lds_dwordx4 v223, s[6:7]
	v_mfma_f32_16x16x32_bf16 v[94:97], v[178:181], v[146:149], v[94:97]
	s_add_u32 m0, s22, 0x1c00
	v_add_u32_e32 v224, 0x18040, v217
	global_load_lds_dwordx4 v224, s[6:7]
	ds_read_b128 v[146:149], v216 offset:38912
	s_waitcnt lgkmcnt(7)
	v_mfma_f32_16x16x32_bf16 v[98:101], v[170:173], v[150:153], v[98:101]
	v_mfma_f32_16x16x32_bf16 v[102:105], v[178:181], v[150:153], v[102:105]
	ds_read_b128 v[150:153], v216 offset:40960
	s_waitcnt lgkmcnt(7)
	v_mfma_f32_16x16x32_bf16 v[106:109], v[170:173], v[154:157], v[106:109]
	v_mfma_f32_16x16x32_bf16 v[110:113], v[178:181], v[154:157], v[110:113]
	ds_read_b128 v[154:157], v216 offset:43008
	s_waitcnt lgkmcnt(7)
	v_mfma_f32_16x16x32_bf16 v[114:117], v[170:173], v[158:161], v[114:117]
	v_mfma_f32_16x16x32_bf16 v[118:121], v[178:181], v[158:161], v[118:121]
	ds_read_b128 v[158:161], v216 offset:45056
	s_waitcnt lgkmcnt(7)
	v_mfma_f32_16x16x32_bf16 v[122:125], v[170:173], v[162:165], v[122:125]
	v_mfma_f32_16x16x32_bf16 v[126:129], v[178:181], v[162:165], v[126:129]
	v_add_u32_e32 v217, 0x80, v217
	v_add_u32_e32 v220, 0x800, v220
	v_add_u32_e32 v221, 0x800, v221
	s_lshr_b32 s3, s14, 4
	s_lshl_b32 s17, s15, 1
	s_add_u32 s3, s3, s17
	s_mul_i32 s17, s3, 0x8000
	s_add_u32 s8, s20, s17
	s_addc_u32 s9, s21, 0
	v_mov_b32_e32 v220, v222
	v_add_u32_e32 v221, 0x8000, v222
	ds_read_b128 v[162:165], v216 offset:47104
	s_waitcnt vmcnt(8) lgkmcnt(7)
	v_mfma_f32_16x16x32_bf16 v[2:5], v[196:199], v[134:137], v[2:5]
	v_mfma_f32_16x16x32_bf16 v[6:9], v[204:207], v[134:137], v[6:9]
	ds_read_b128 v[134:137], v216 offset:49152
	s_waitcnt lgkmcnt(7)
	v_mfma_f32_16x16x32_bf16 v[10:13], v[196:199], v[138:141], v[10:13]
	v_mfma_f32_16x16x32_bf16 v[14:17], v[204:207], v[138:141], v[14:17]
	ds_read_b128 v[138:141], v216 offset:51200
	s_waitcnt lgkmcnt(7)
	v_mfma_f32_16x16x32_bf16 v[18:21], v[196:199], v[142:145], v[18:21]
	v_mfma_f32_16x16x32_bf16 v[22:25], v[204:207], v[142:145], v[22:25]
	ds_read_b128 v[142:145], v216 offset:53248
	s_waitcnt lgkmcnt(7)
	v_mfma_f32_16x16x32_bf16 v[26:29], v[196:199], v[146:149], v[26:29]
	v_mfma_f32_16x16x32_bf16 v[30:33], v[204:207], v[146:149], v[30:33]
	ds_read_b128 v[146:149], v216 offset:55296
	s_waitcnt lgkmcnt(7)
	v_mfma_f32_16x16x32_bf16 v[34:37], v[196:199], v[150:153], v[34:37]
	global_load_dwordx4 v[166:169], v220, s[8:9]
	v_mfma_f32_16x16x32_bf16 v[38:41], v[204:207], v[150:153], v[38:41]
	global_load_dwordx4 v[170:173], v220, s[8:9] offset:1024
	ds_read_b128 v[150:153], v216 offset:57344
	s_waitcnt lgkmcnt(7)
	v_mfma_f32_16x16x32_bf16 v[42:45], v[196:199], v[154:157], v[42:45]
	global_load_dwordx4 v[174:177], v221, s[8:9]
	v_mfma_f32_16x16x32_bf16 v[46:49], v[204:207], v[154:157], v[46:49]
	global_load_dwordx4 v[178:181], v221, s[8:9] offset:1024
	ds_read_b128 v[154:157], v216 offset:59392
	s_waitcnt lgkmcnt(7)
	v_mfma_f32_16x16x32_bf16 v[50:53], v[196:199], v[158:161], v[50:53]
	v_mfma_f32_16x16x32_bf16 v[54:57], v[204:207], v[158:161], v[54:57]
	ds_read_b128 v[158:161], v216 offset:61440
	s_waitcnt lgkmcnt(7)
	v_mfma_f32_16x16x32_bf16 v[58:61], v[196:199], v[162:165], v[58:61]
	v_mfma_f32_16x16x32_bf16 v[62:65], v[204:207], v[162:165], v[62:65]
	ds_read_b128 v[162:165], v216 offset:63488
	s_waitcnt lgkmcnt(7)
	v_mfma_f32_16x16x32_bf16 v[66:69], v[196:199], v[134:137], v[66:69]
	v_mfma_f32_16x16x32_bf16 v[70:73], v[204:207], v[134:137], v[70:73]
	ds_read_b128 v[134:137], v216 offset:33792
	s_waitcnt lgkmcnt(7)
	v_mfma_f32_16x16x32_bf16 v[74:77], v[196:199], v[138:141], v[74:77]
	v_mfma_f32_16x16x32_bf16 v[78:81], v[204:207], v[138:141], v[78:81]
	ds_read_b128 v[138:141], v216 offset:35840
	s_waitcnt lgkmcnt(7)
	v_mfma_f32_16x16x32_bf16 v[82:85], v[196:199], v[142:145], v[82:85]
	v_mfma_f32_16x16x32_bf16 v[86:89], v[204:207], v[142:145], v[86:89]
	ds_read_b128 v[142:145], v216 offset:37888
	s_waitcnt lgkmcnt(7)
	v_mfma_f32_16x16x32_bf16 v[90:93], v[196:199], v[146:149], v[90:93]
	v_mfma_f32_16x16x32_bf16 v[94:97], v[204:207], v[146:149], v[94:97]
	ds_read_b128 v[146:149], v216 offset:39936
	s_waitcnt lgkmcnt(7)
	v_mfma_f32_16x16x32_bf16 v[98:101], v[196:199], v[150:153], v[98:101]
	v_mfma_f32_16x16x32_bf16 v[102:105], v[204:207], v[150:153], v[102:105]
	ds_read_b128 v[150:153], v216 offset:41984
	s_waitcnt lgkmcnt(7)
	v_mfma_f32_16x16x32_bf16 v[106:109], v[196:199], v[154:157], v[106:109]
	v_mfma_f32_16x16x32_bf16 v[110:113], v[204:207], v[154:157], v[110:113]
	ds_read_b128 v[154:157], v216 offset:44032
	s_waitcnt lgkmcnt(7)
	v_mfma_f32_16x16x32_bf16 v[114:117], v[196:199], v[158:161], v[114:117]
	v_mfma_f32_16x16x32_bf16 v[118:121], v[204:207], v[158:161], v[118:121]
	ds_read_b128 v[158:161], v216 offset:46080
	s_waitcnt lgkmcnt(7)
	v_mfma_f32_16x16x32_bf16 v[122:125], v[196:199], v[162:165], v[122:125]
	v_mfma_f32_16x16x32_bf16 v[126:129], v[204:207], v[162:165], v[126:129]
	ds_read_b128 v[162:165], v216 offset:48128
	s_waitcnt lgkmcnt(7)
	v_mfma_f32_16x16x32_bf16 v[2:5], v[200:203], v[134:137], v[2:5]
	v_mfma_f32_16x16x32_bf16 v[6:9], v[212:215], v[134:137], v[6:9]
	ds_read_b128 v[134:137], v216 offset:50176
	s_waitcnt lgkmcnt(7)
	v_mfma_f32_16x16x32_bf16 v[10:13], v[200:203], v[138:141], v[10:13]
	v_mfma_f32_16x16x32_bf16 v[14:17], v[212:215], v[138:141], v[14:17]
	ds_read_b128 v[138:141], v216 offset:52224
	s_waitcnt lgkmcnt(7)
	v_mfma_f32_16x16x32_bf16 v[18:21], v[200:203], v[142:145], v[18:21]
	v_mfma_f32_16x16x32_bf16 v[22:25], v[212:215], v[142:145], v[22:25]
	ds_read_b128 v[142:145], v216 offset:54272
	s_waitcnt lgkmcnt(7)
	v_mfma_f32_16x16x32_bf16 v[26:29], v[200:203], v[146:149], v[26:29]
	v_mfma_f32_16x16x32_bf16 v[30:33], v[212:215], v[146:149], v[30:33]
	ds_read_b128 v[146:149], v216 offset:56320
	s_waitcnt lgkmcnt(7)
	v_mfma_f32_16x16x32_bf16 v[34:37], v[200:203], v[150:153], v[34:37]
	v_mfma_f32_16x16x32_bf16 v[38:41], v[212:215], v[150:153], v[38:41]
	ds_read_b128 v[150:153], v216 offset:58368
	s_waitcnt lgkmcnt(7)
	v_mfma_f32_16x16x32_bf16 v[42:45], v[200:203], v[154:157], v[42:45]
	v_mfma_f32_16x16x32_bf16 v[46:49], v[212:215], v[154:157], v[46:49]
	ds_read_b128 v[154:157], v216 offset:60416
	s_waitcnt lgkmcnt(7)
	v_mfma_f32_16x16x32_bf16 v[50:53], v[200:203], v[158:161], v[50:53]
	v_mfma_f32_16x16x32_bf16 v[54:57], v[212:215], v[158:161], v[54:57]
	ds_read_b128 v[158:161], v216 offset:62464
	s_waitcnt lgkmcnt(7)
	v_mfma_f32_16x16x32_bf16 v[58:61], v[200:203], v[162:165], v[58:61]
	v_mfma_f32_16x16x32_bf16 v[62:65], v[212:215], v[162:165], v[62:65]
	ds_read_b128 v[162:165], v216 offset:64512
	s_waitcnt vmcnt(4) lgkmcnt(0)
	s_barrier
	v_mfma_f32_16x16x32_bf16 v[66:69], v[200:203], v[134:137], v[66:69]
	s_add_u32 m0, s22, 0x8000
	v_mov_b32_e32 v223, v217
	global_load_lds_dwordx4 v223, s[6:7]
	v_mfma_f32_16x16x32_bf16 v[70:73], v[212:215], v[134:137], v[70:73]
	s_add_u32 m0, s22, 0x8400
	v_add_u32_e32 v224, 0x40, v217
	global_load_lds_dwordx4 v224, s[6:7]
	ds_read_b128 v[134:137], v216
	s_waitcnt lgkmcnt(7)
	v_mfma_f32_16x16x32_bf16 v[74:77], v[200:203], v[138:141], v[74:77]
	s_add_u32 m0, s22, 0x8800
	v_add_u32_e32 v223, 0x8000, v217
	global_load_lds_dwordx4 v223, s[6:7]
	v_mfma_f32_16x16x32_bf16 v[78:81], v[212:215], v[138:141], v[78:81]
	s_add_u32 m0, s22, 0x8c00
	v_add_u32_e32 v224, 0x8040, v217
	global_load_lds_dwordx4 v224, s[6:7]
	ds_read_b128 v[138:141], v216 offset:2048
	s_waitcnt lgkmcnt(7)
	v_mfma_f32_16x16x32_bf16 v[82:85], v[200:203], v[142:145], v[82:85]
	s_add_u32 m0, s22, 0x9000
	v_add_u32_e32 v223, 0x10000, v217
	global_load_lds_dwordx4 v223, s[6:7]
	v_mfma_f32_16x16x32_bf16 v[86:89], v[212:215], v[142:145], v[86:89]
	s_add_u32 m0, s22, 0x9400
	v_add_u32_e32 v224, 0x10040, v217
	global_load_lds_dwordx4 v224, s[6:7]
	ds_read_b128 v[142:145], v216 offset:4096
	s_waitcnt lgkmcnt(7)
	v_mfma_f32_16x16x32_bf16 v[90:93], v[200:203], v[146:149], v[90:93]
	s_add_u32 m0, s22, 0x9800
	v_add_u32_e32 v223, 0x18000, v217
	global_load_lds_dwordx4 v223, s[6:7]
	v_mfma_f32_16x16x32_bf16 v[94:97], v[212:215], v[146:149], v[94:97]
	s_add_u32 m0, s22, 0x9c00
	v_add_u32_e32 v224, 0x18040, v217
	global_load_lds_dwordx4 v224, s[6:7]
	ds_read_b128 v[146:149], v216 offset:6144
	s_waitcnt lgkmcnt(7)
	v_mfma_f32_16x16x32_bf16 v[98:101], v[200:203], v[150:153], v[98:101]
	v_mfma_f32_16x16x32_bf16 v[102:105], v[212:215], v[150:153], v[102:105]
	ds_read_b128 v[150:153], v216 offset:8192
	s_waitcnt lgkmcnt(7)
	v_mfma_f32_16x16x32_bf16 v[106:109], v[200:203], v[154:157], v[106:109]
	v_mfma_f32_16x16x32_bf16 v[110:113], v[212:215], v[154:157], v[110:113]
	ds_read_b128 v[154:157], v216 offset:10240
	s_waitcnt lgkmcnt(7)
	v_mfma_f32_16x16x32_bf16 v[114:117], v[200:203], v[158:161], v[114:117]
	v_mfma_f32_16x16x32_bf16 v[118:121], v[212:215], v[158:161], v[118:121]
	ds_read_b128 v[158:161], v216 offset:12288
	s_waitcnt lgkmcnt(7)
	v_mfma_f32_16x16x32_bf16 v[122:125], v[200:203], v[162:165], v[122:125]
	v_mfma_f32_16x16x32_bf16 v[126:129], v[212:215], v[162:165], v[126:129]
	v_add_u32_e32 v217, 0x80, v217
	v_add_u32_e32 v220, 0x800, v220
	v_add_u32_e32 v221, 0x800, v221
	s_mov_b32 s16, 1
	s_branch .Lg256b_wo_epi

.Lg256b_ip_first_ok:
	s_lshl_b32 s13, s13, 8
	s_lshl_b32 s14, s14, 7
	s_lshl_b32 s3, s15, 6
	s_add_u32 s17, s3, s13
	s_mul_i32 s17, s17, 0x800
	s_add_u32 s6, s18, s17
	s_addc_u32 s7, s19, 0
	s_lshr_b32 s3, s14, 4
	s_lshl_b32 s17, s15, 1
	s_add_u32 s3, s3, s17
	s_mul_i32 s17, s3, 0x8000
	s_add_u32 s8, s20, s17
	s_addc_u32 s9, s21, 0
	s_barrier
	v_mov_b32_e32 v217, v218
	v_mov_b32_e32 v220, v222
	v_add_u32_e32 v221, 0x8000, v222
	s_add_u32 m0, s22, 0x0
	v_mov_b32_e32 v223, v217
	global_load_lds_dwordx4 v223, s[6:7]
	s_add_u32 m0, s22, 0x400
	v_add_u32_e32 v224, 0x40, v217
	global_load_lds_dwordx4 v224, s[6:7]
	s_add_u32 m0, s22, 0x800
	v_add_u32_e32 v223, 0x8000, v217
	global_load_lds_dwordx4 v223, s[6:7]
	s_add_u32 m0, s22, 0xc00
	v_add_u32_e32 v224, 0x8040, v217
	global_load_lds_dwordx4 v224, s[6:7]
	s_add_u32 m0, s22, 0x1000
	v_add_u32_e32 v223, 0x10000, v217
	global_load_lds_dwordx4 v223, s[6:7]
	s_add_u32 m0, s22, 0x1400
	v_add_u32_e32 v224, 0x10040, v217
	global_load_lds_dwordx4 v224, s[6:7]
	s_add_u32 m0, s22, 0x1800
	v_add_u32_e32 v223, 0x18000, v217
	global_load_lds_dwordx4 v223, s[6:7]
	s_add_u32 m0, s22, 0x1c00
	v_add_u32_e32 v224, 0x18040, v217
	global_load_lds_dwordx4 v224, s[6:7]
	v_add_u32_e32 v217, 0x80, v217
	s_add_u32 m0, s22, 0x8000
	v_mov_b32_e32 v223, v217
	global_load_lds_dwordx4 v223, s[6:7]
	s_add_u32 m0, s22, 0x8400
	v_add_u32_e32 v224, 0x40, v217
	global_load_lds_dwordx4 v224, s[6:7]
	s_add_u32 m0, s22, 0x8800
	v_add_u32_e32 v223, 0x8000, v217
	global_load_lds_dwordx4 v223, s[6:7]
	s_add_u32 m0, s22, 0x8c00
	v_add_u32_e32 v224, 0x8040, v217
	global_load_lds_dwordx4 v224, s[6:7]
	s_add_u32 m0, s22, 0x9000
	v_add_u32_e32 v223, 0x10000, v217
	global_load_lds_dwordx4 v223, s[6:7]
	s_add_u32 m0, s22, 0x9400
	v_add_u32_e32 v224, 0x10040, v217
	global_load_lds_dwordx4 v224, s[6:7]
	s_add_u32 m0, s22, 0x9800
	v_add_u32_e32 v223, 0x18000, v217
	global_load_lds_dwordx4 v223, s[6:7]
	s_add_u32 m0, s22, 0x9c00
	v_add_u32_e32 v224, 0x18040, v217
	global_load_lds_dwordx4 v224, s[6:7]
	v_add_u32_e32 v217, 0x80, v217
	global_load_dwordx4 v[166:169], v220, s[8:9]
	global_load_dwordx4 v[170:173], v220, s[8:9] offset:1024
	global_load_dwordx4 v[174:177], v221, s[8:9]
	global_load_dwordx4 v[178:181], v221, s[8:9] offset:1024
	v_add_u32_e32 v220, 0x800, v220
	v_add_u32_e32 v221, 0x800, v221
	s_waitcnt vmcnt(0)
	s_barrier
	ds_read_b128 v[134:137], v216
	ds_read_b128 v[138:141], v216 offset:2048
	ds_read_b128 v[142:145], v216 offset:4096
	ds_read_b128 v[146:149], v216 offset:6144
	ds_read_b128 v[150:153], v216 offset:8192
	ds_read_b128 v[154:157], v216 offset:10240
	ds_read_b128 v[158:161], v216 offset:12288
.Lg256b_ip_tile:
	s_mul_i32 s17, s13, 0x1440
	s_lshl_b32 s3, s15, 5
	s_add_u32 s3, s3, s14
	s_mul_i32 s3, s3, 2
	s_add_u32 s17, s17, s3
	s_add_u32 s10, s24, s17
	s_addc_u32 s11, s25, 0
	s_cmp_eq_u32 s14, 2560
	s_cselect_b32 s27, 1, 0
	s_cmp_lg_u32 s15, 0
	s_cselect_b32 s3, 1, 0
	s_and_b32 s27, s27, s3
	ds_read_b128 v[162:165], v216 offset:14336
	s_waitcnt vmcnt(0) lgkmcnt(7)
	v_mfma_f32_16x16x32_bf16 v[2:5], v[166:169], v[134:137], 0
	v_mfma_f32_16x16x32_bf16 v[6:9], v[174:177], v[134:137], 0
	ds_read_b128 v[134:137], v216 offset:16384
	s_waitcnt lgkmcnt(7)
	v_mfma_f32_16x16x32_bf16 v[10:13], v[166:169], v[138:141], 0
	v_mfma_f32_16x16x32_bf16 v[14:17], v[174:177], v[138:141], 0
	ds_read_b128 v[138:141], v216 offset:18432
	s_waitcnt lgkmcnt(7)
	v_mfma_f32_16x16x32_bf16 v[18:21], v[166:169], v[142:145], 0
	v_mfma_f32_16x16x32_bf16 v[22:25], v[174:177], v[142:145], 0
	ds_read_b128 v[142:145], v216 offset:20480
	s_waitcnt lgkmcnt(7)
	v_mfma_f32_16x16x32_bf16 v[26:29], v[166:169], v[146:149], 0
	v_mfma_f32_16x16x32_bf16 v[30:33], v[174:177], v[146:149], 0
	ds_read_b128 v[146:149], v216 offset:22528
	s_waitcnt lgkmcnt(7)
	v_mfma_f32_16x16x32_bf16 v[34:37], v[166:169], v[150:153], 0
	global_load_dwordx4 v[196:199], v220, s[8:9]
	v_mfma_f32_16x16x32_bf16 v[38:41], v[174:177], v[150:153], 0
	global_load_dwordx4 v[200:203], v220, s[8:9] offset:1024
	ds_read_b128 v[150:153], v216 offset:24576
	s_waitcnt lgkmcnt(7)
	v_mfma_f32_16x16x32_bf16 v[42:45], v[166:169], v[154:157], 0
	global_load_dwordx4 v[204:207], v221, s[8:9]
	v_mfma_f32_16x16x32_bf16 v[46:49], v[174:177], v[154:157], 0
	global_load_dwordx4 v[212:215], v221, s[8:9] offset:1024
	ds_read_b128 v[154:157], v216 offset:26624
	s_waitcnt lgkmcnt(7)
	v_mfma_f32_16x16x32_bf16 v[50:53], v[166:169], v[158:161], 0
	v_mfma_f32_16x16x32_bf16 v[54:57], v[174:177], v[158:161], 0
	ds_read_b128 v[158:161], v216 offset:28672
	s_waitcnt lgkmcnt(7)
	v_mfma_f32_16x16x32_bf16 v[58:61], v[166:169], v[162:165], 0
	v_mfma_f32_16x16x32_bf16 v[62:65], v[174:177], v[162:165], 0
	ds_read_b128 v[162:165], v216 offset:30720
	s_waitcnt lgkmcnt(7)
	v_mfma_f32_16x16x32_bf16 v[66:69], v[166:169], v[134:137], 0
	v_mfma_f32_16x16x32_bf16 v[70:73], v[174:177], v[134:137], 0
	ds_read_b128 v[134:137], v216 offset:1024
	s_waitcnt lgkmcnt(7)
	v_mfma_f32_16x16x32_bf16 v[74:77], v[166:169], v[138:141], 0
	v_mfma_f32_16x16x32_bf16 v[78:81], v[174:177], v[138:141], 0
	ds_read_b128 v[138:141], v216 offset:3072
	s_waitcnt lgkmcnt(7)
	v_mfma_f32_16x16x32_bf16 v[82:85], v[166:169], v[142:145], 0
	v_mfma_f32_16x16x32_bf16 v[86:89], v[174:177], v[142:145], 0
	ds_read_b128 v[142:145], v216 offset:5120
	s_waitcnt lgkmcnt(7)
	v_mfma_f32_16x16x32_bf16 v[90:93], v[166:169], v[146:149], 0
	v_mfma_f32_16x16x32_bf16 v[94:97], v[174:177], v[146:149], 0
	ds_read_b128 v[146:149], v216 offset:7168
	s_waitcnt lgkmcnt(7)
	v_mfma_f32_16x16x32_bf16 v[98:101], v[166:169], v[150:153], 0
	v_mfma_f32_16x16x32_bf16 v[102:105], v[174:177], v[150:153], 0
	ds_read_b128 v[150:153], v216 offset:9216
	s_waitcnt lgkmcnt(7)
	v_mfma_f32_16x16x32_bf16 v[106:109], v[166:169], v[154:157], 0
	v_mfma_f32_16x16x32_bf16 v[110:113], v[174:177], v[154:157], 0
	ds_read_b128 v[154:157], v216 offset:11264
	s_waitcnt lgkmcnt(7)
	v_mfma_f32_16x16x32_bf16 v[114:117], v[166:169], v[158:161], 0
	v_mfma_f32_16x16x32_bf16 v[118:121], v[174:177], v[158:161], 0
	ds_read_b128 v[158:161], v216 offset:13312
	s_waitcnt lgkmcnt(7)
	v_mfma_f32_16x16x32_bf16 v[122:125], v[166:169], v[162:165], 0
	v_mfma_f32_16x16x32_bf16 v[126:129], v[174:177], v[162:165], 0
	ds_read_b128 v[162:165], v216 offset:15360
	s_waitcnt lgkmcnt(7)
	v_mfma_f32_16x16x32_bf16 v[2:5], v[170:173], v[134:137], v[2:5]
	v_mfma_f32_16x16x32_bf16 v[6:9], v[178:181], v[134:137], v[6:9]
	ds_read_b128 v[134:137], v216 offset:17408
	s_waitcnt lgkmcnt(7)
	v_mfma_f32_16x16x32_bf16 v[10:13], v[170:173], v[138:141], v[10:13]
	v_mfma_f32_16x16x32_bf16 v[14:17], v[178:181], v[138:141], v[14:17]
	ds_read_b128 v[138:141], v216 offset:19456
	s_waitcnt lgkmcnt(7)
	v_mfma_f32_16x16x32_bf16 v[18:21], v[170:173], v[142:145], v[18:21]
	v_mfma_f32_16x16x32_bf16 v[22:25], v[178:181], v[142:145], v[22:25]
	ds_read_b128 v[142:145], v216 offset:21504
	s_waitcnt lgkmcnt(7)
	v_mfma_f32_16x16x32_bf16 v[26:29], v[170:173], v[146:149], v[26:29]
	v_mfma_f32_16x16x32_bf16 v[30:33], v[178:181], v[146:149], v[30:33]
	ds_read_b128 v[146:149], v216 offset:23552
	s_waitcnt lgkmcnt(7)
	v_mfma_f32_16x16x32_bf16 v[34:37], v[170:173], v[150:153], v[34:37]
	v_mfma_f32_16x16x32_bf16 v[38:41], v[178:181], v[150:153], v[38:41]
	ds_read_b128 v[150:153], v216 offset:25600
	s_waitcnt lgkmcnt(7)
	v_mfma_f32_16x16x32_bf16 v[42:45], v[170:173], v[154:157], v[42:45]
	v_mfma_f32_16x16x32_bf16 v[46:49], v[178:181], v[154:157], v[46:49]
	ds_read_b128 v[154:157], v216 offset:27648
	s_waitcnt lgkmcnt(7)
	v_mfma_f32_16x16x32_bf16 v[50:53], v[170:173], v[158:161], v[50:53]
	v_mfma_f32_16x16x32_bf16 v[54:57], v[178:181], v[158:161], v[54:57]
	ds_read_b128 v[158:161], v216 offset:29696
	s_waitcnt lgkmcnt(7)
	v_mfma_f32_16x16x32_bf16 v[58:61], v[170:173], v[162:165], v[58:61]
	v_mfma_f32_16x16x32_bf16 v[62:65], v[178:181], v[162:165], v[62:65]
	ds_read_b128 v[162:165], v216 offset:31744
	s_waitcnt vmcnt(0) lgkmcnt(0)
	s_barrier
	v_mfma_f32_16x16x32_bf16 v[66:69], v[170:173], v[134:137], v[66:69]
	s_add_u32 m0, s22, 0x0
	v_mov_b32_e32 v223, v217
	global_load_lds_dwordx4 v223, s[6:7]
	v_mfma_f32_16x16x32_bf16 v[70:73], v[178:181], v[134:137], v[70:73]
	s_add_u32 m0, s22, 0x400
	v_add_u32_e32 v224, 0x40, v217
	global_load_lds_dwordx4 v224, s[6:7]
	ds_read_b128 v[134:137], v216 offset:32768
	s_waitcnt lgkmcnt(7)
	v_mfma_f32_16x16x32_bf16 v[74:77], v[170:173], v[138:141], v[74:77]
	s_add_u32 m0, s22, 0x800
	v_add_u32_e32 v223, 0x8000, v217
	global_load_lds_dwordx4 v223, s[6:7]
	v_mfma_f32_16x16x32_bf16 v[78:81], v[178:181], v[138:141], v[78:81]
	s_add_u32 m0, s22, 0xc00
	v_add_u32_e32 v224, 0x8040, v217
	global_load_lds_dwordx4 v224, s[6:7]
	ds_read_b128 v[138:141], v216 offset:34816
	s_waitcnt lgkmcnt(7)
	v_mfma_f32_16x16x32_bf16 v[82:85], v[170:173], v[142:145], v[82:85]
	s_add_u32 m0, s22, 0x1000
	v_add_u32_e32 v223, 0x10000, v217
	global_load_lds_dwordx4 v223, s[6:7]
	v_mfma_f32_16x16x32_bf16 v[86:89], v[178:181], v[142:145], v[86:89]
	s_add_u32 m0, s22, 0x1400
	v_add_u32_e32 v224, 0x10040, v217
	global_load_lds_dwordx4 v224, s[6:7]
	ds_read_b128 v[142:145], v216 offset:36864
	s_waitcnt lgkmcnt(7)
	v_mfma_f32_16x16x32_bf16 v[90:93], v[170:173], v[146:149], v[90:93]
	s_add_u32 m0, s22, 0x1800
	v_add_u32_e32 v223, 0x18000, v217
	global_load_lds_dwordx4 v223, s[6:7]
	v_mfma_f32_16x16x32_bf16 v[94:97], v[178:181], v[146:149], v[94:97]
	s_add_u32 m0, s22, 0x1c00
	v_add_u32_e32 v224, 0x18040, v217
	global_load_lds_dwordx4 v224, s[6:7]
	ds_read_b128 v[146:149], v216 offset:38912
	s_waitcnt lgkmcnt(7)
	v_mfma_f32_16x16x32_bf16 v[98:101], v[170:173], v[150:153], v[98:101]
	v_mfma_f32_16x16x32_bf16 v[102:105], v[178:181], v[150:153], v[102:105]
	ds_read_b128 v[150:153], v216 offset:40960
	s_waitcnt lgkmcnt(7)
	v_mfma_f32_16x16x32_bf16 v[106:109], v[170:173], v[154:157], v[106:109]
	v_mfma_f32_16x16x32_bf16 v[110:113], v[178:181], v[154:157], v[110:113]
	ds_read_b128 v[154:157], v216 offset:43008
	s_waitcnt lgkmcnt(7)
	v_mfma_f32_16x16x32_bf16 v[114:117], v[170:173], v[158:161], v[114:117]
	v_mfma_f32_16x16x32_bf16 v[118:121], v[178:181], v[158:161], v[118:121]
	ds_read_b128 v[158:161], v216 offset:45056
	s_waitcnt lgkmcnt(7)
	v_mfma_f32_16x16x32_bf16 v[122:125], v[170:173], v[162:165], v[122:125]
	v_mfma_f32_16x16x32_bf16 v[126:129], v[178:181], v[162:165], v[126:129]
	v_add_u32_e32 v217, 0x80, v217
	v_add_u32_e32 v220, 0x800, v220
	v_add_u32_e32 v221, 0x800, v221
	ds_read_b128 v[162:165], v216 offset:47104
	s_waitcnt vmcnt(8) lgkmcnt(7)
	v_mfma_f32_16x16x32_bf16 v[2:5], v[196:199], v[134:137], v[2:5]
	v_mfma_f32_16x16x32_bf16 v[6:9], v[204:207], v[134:137], v[6:9]
	ds_read_b128 v[134:137], v216 offset:49152
	s_waitcnt lgkmcnt(7)
	v_mfma_f32_16x16x32_bf16 v[10:13], v[196:199], v[138:141], v[10:13]
	v_mfma_f32_16x16x32_bf16 v[14:17], v[204:207], v[138:141], v[14:17]
	ds_read_b128 v[138:141], v216 offset:51200
	s_waitcnt lgkmcnt(7)
	v_mfma_f32_16x16x32_bf16 v[18:21], v[196:199], v[142:145], v[18:21]
	v_mfma_f32_16x16x32_bf16 v[22:25], v[204:207], v[142:145], v[22:25]
	ds_read_b128 v[142:145], v216 offset:53248
	s_waitcnt lgkmcnt(7)
	v_mfma_f32_16x16x32_bf16 v[26:29], v[196:199], v[146:149], v[26:29]
	v_mfma_f32_16x16x32_bf16 v[30:33], v[204:207], v[146:149], v[30:33]
	ds_read_b128 v[146:149], v216 offset:55296
	s_waitcnt lgkmcnt(7)
	v_mfma_f32_16x16x32_bf16 v[34:37], v[196:199], v[150:153], v[34:37]
	global_load_dwordx4 v[166:169], v220, s[8:9]
	v_mfma_f32_16x16x32_bf16 v[38:41], v[204:207], v[150:153], v[38:41]
	global_load_dwordx4 v[170:173], v220, s[8:9] offset:1024
	ds_read_b128 v[150:153], v216 offset:57344
	s_waitcnt lgkmcnt(7)
	v_mfma_f32_16x16x32_bf16 v[42:45], v[196:199], v[154:157], v[42:45]
	global_load_dwordx4 v[174:177], v221, s[8:9]
	v_mfma_f32_16x16x32_bf16 v[46:49], v[204:207], v[154:157], v[46:49]
	global_load_dwordx4 v[178:181], v221, s[8:9] offset:1024
	ds_read_b128 v[154:157], v216 offset:59392
	s_waitcnt lgkmcnt(7)
	v_mfma_f32_16x16x32_bf16 v[50:53], v[196:199], v[158:161], v[50:53]
	v_mfma_f32_16x16x32_bf16 v[54:57], v[204:207], v[158:161], v[54:57]
	ds_read_b128 v[158:161], v216 offset:61440
	s_waitcnt lgkmcnt(7)
	v_mfma_f32_16x16x32_bf16 v[58:61], v[196:199], v[162:165], v[58:61]
	v_mfma_f32_16x16x32_bf16 v[62:65], v[204:207], v[162:165], v[62:65]
	ds_read_b128 v[162:165], v216 offset:63488
	s_waitcnt lgkmcnt(7)
	v_mfma_f32_16x16x32_bf16 v[66:69], v[196:199], v[134:137], v[66:69]
	v_mfma_f32_16x16x32_bf16 v[70:73], v[204:207], v[134:137], v[70:73]
	ds_read_b128 v[134:137], v216 offset:33792
	s_waitcnt lgkmcnt(7)
	v_mfma_f32_16x16x32_bf16 v[74:77], v[196:199], v[138:141], v[74:77]
	v_mfma_f32_16x16x32_bf16 v[78:81], v[204:207], v[138:141], v[78:81]
	ds_read_b128 v[138:141], v216 offset:35840
	s_waitcnt lgkmcnt(7)
	v_mfma_f32_16x16x32_bf16 v[82:85], v[196:199], v[142:145], v[82:85]
	v_mfma_f32_16x16x32_bf16 v[86:89], v[204:207], v[142:145], v[86:89]
	ds_read_b128 v[142:145], v216 offset:37888
	s_waitcnt lgkmcnt(7)
	v_mfma_f32_16x16x32_bf16 v[90:93], v[196:199], v[146:149], v[90:93]
	v_mfma_f32_16x16x32_bf16 v[94:97], v[204:207], v[146:149], v[94:97]
	ds_read_b128 v[146:149], v216 offset:39936
	s_waitcnt lgkmcnt(7)
	v_mfma_f32_16x16x32_bf16 v[98:101], v[196:199], v[150:153], v[98:101]
	v_mfma_f32_16x16x32_bf16 v[102:105], v[204:207], v[150:153], v[102:105]
	ds_read_b128 v[150:153], v216 offset:41984
	s_waitcnt lgkmcnt(7)
	v_mfma_f32_16x16x32_bf16 v[106:109], v[196:199], v[154:157], v[106:109]
	v_mfma_f32_16x16x32_bf16 v[110:113], v[204:207], v[154:157], v[110:113]
	ds_read_b128 v[154:157], v216 offset:44032
	s_waitcnt lgkmcnt(7)
	v_mfma_f32_16x16x32_bf16 v[114:117], v[196:199], v[158:161], v[114:117]
	v_mfma_f32_16x16x32_bf16 v[118:121], v[204:207], v[158:161], v[118:121]
	ds_read_b128 v[158:161], v216 offset:46080
	s_waitcnt lgkmcnt(7)
	v_mfma_f32_16x16x32_bf16 v[122:125], v[196:199], v[162:165], v[122:125]
	v_mfma_f32_16x16x32_bf16 v[126:129], v[204:207], v[162:165], v[126:129]
	ds_read_b128 v[162:165], v216 offset:48128
	s_waitcnt lgkmcnt(7)
	v_mfma_f32_16x16x32_bf16 v[2:5], v[200:203], v[134:137], v[2:5]
	v_mfma_f32_16x16x32_bf16 v[6:9], v[212:215], v[134:137], v[6:9]
	ds_read_b128 v[134:137], v216 offset:50176
	s_waitcnt lgkmcnt(7)
	v_mfma_f32_16x16x32_bf16 v[10:13], v[200:203], v[138:141], v[10:13]
	v_mfma_f32_16x16x32_bf16 v[14:17], v[212:215], v[138:141], v[14:17]
	ds_read_b128 v[138:141], v216 offset:52224
	s_waitcnt lgkmcnt(7)
	v_mfma_f32_16x16x32_bf16 v[18:21], v[200:203], v[142:145], v[18:21]
	v_mfma_f32_16x16x32_bf16 v[22:25], v[212:215], v[142:145], v[22:25]
	ds_read_b128 v[142:145], v216 offset:54272
	s_waitcnt lgkmcnt(7)
	v_mfma_f32_16x16x32_bf16 v[26:29], v[200:203], v[146:149], v[26:29]
	v_mfma_f32_16x16x32_bf16 v[30:33], v[212:215], v[146:149], v[30:33]
	ds_read_b128 v[146:149], v216 offset:56320
	s_waitcnt lgkmcnt(7)
	v_mfma_f32_16x16x32_bf16 v[34:37], v[200:203], v[150:153], v[34:37]
	v_mfma_f32_16x16x32_bf16 v[38:41], v[212:215], v[150:153], v[38:41]
	ds_read_b128 v[150:153], v216 offset:58368
	s_waitcnt lgkmcnt(7)
	v_mfma_f32_16x16x32_bf16 v[42:45], v[200:203], v[154:157], v[42:45]
	v_mfma_f32_16x16x32_bf16 v[46:49], v[212:215], v[154:157], v[46:49]
	ds_read_b128 v[154:157], v216 offset:60416
	s_waitcnt lgkmcnt(7)
	v_mfma_f32_16x16x32_bf16 v[50:53], v[200:203], v[158:161], v[50:53]
	v_mfma_f32_16x16x32_bf16 v[54:57], v[212:215], v[158:161], v[54:57]
	ds_read_b128 v[158:161], v216 offset:62464
	s_waitcnt lgkmcnt(7)
	v_mfma_f32_16x16x32_bf16 v[58:61], v[200:203], v[162:165], v[58:61]
	v_mfma_f32_16x16x32_bf16 v[62:65], v[212:215], v[162:165], v[62:65]
	ds_read_b128 v[162:165], v216 offset:64512
	s_waitcnt vmcnt(4) lgkmcnt(0)
	s_barrier
	v_mfma_f32_16x16x32_bf16 v[66:69], v[200:203], v[134:137], v[66:69]
	s_add_u32 m0, s22, 0x8000
	v_mov_b32_e32 v223, v217
	global_load_lds_dwordx4 v223, s[6:7]
	v_mfma_f32_16x16x32_bf16 v[70:73], v[212:215], v[134:137], v[70:73]
	s_add_u32 m0, s22, 0x8400
	v_add_u32_e32 v224, 0x40, v217
	global_load_lds_dwordx4 v224, s[6:7]
	ds_read_b128 v[134:137], v216
	s_waitcnt lgkmcnt(7)
	v_mfma_f32_16x16x32_bf16 v[74:77], v[200:203], v[138:141], v[74:77]
	s_add_u32 m0, s22, 0x8800
	v_add_u32_e32 v223, 0x8000, v217
	global_load_lds_dwordx4 v223, s[6:7]
	v_mfma_f32_16x16x32_bf16 v[78:81], v[212:215], v[138:141], v[78:81]
	s_add_u32 m0, s22, 0x8c00
	v_add_u32_e32 v224, 0x8040, v217
	global_load_lds_dwordx4 v224, s[6:7]
	ds_read_b128 v[138:141], v216 offset:2048
	s_waitcnt lgkmcnt(7)
	v_mfma_f32_16x16x32_bf16 v[82:85], v[200:203], v[142:145], v[82:85]
	s_add_u32 m0, s22, 0x9000
	v_add_u32_e32 v223, 0x10000, v217
	global_load_lds_dwordx4 v223, s[6:7]
	v_mfma_f32_16x16x32_bf16 v[86:89], v[212:215], v[142:145], v[86:89]
	s_add_u32 m0, s22, 0x9400
	v_add_u32_e32 v224, 0x10040, v217
	global_load_lds_dwordx4 v224, s[6:7]
	ds_read_b128 v[142:145], v216 offset:4096
	s_waitcnt lgkmcnt(7)
	v_mfma_f32_16x16x32_bf16 v[90:93], v[200:203], v[146:149], v[90:93]
	s_add_u32 m0, s22, 0x9800
	v_add_u32_e32 v223, 0x18000, v217
	global_load_lds_dwordx4 v223, s[6:7]
	v_mfma_f32_16x16x32_bf16 v[94:97], v[212:215], v[146:149], v[94:97]
	s_add_u32 m0, s22, 0x9c00
	v_add_u32_e32 v224, 0x18040, v217
	global_load_lds_dwordx4 v224, s[6:7]
	ds_read_b128 v[146:149], v216 offset:6144
	s_waitcnt lgkmcnt(7)
	v_mfma_f32_16x16x32_bf16 v[98:101], v[200:203], v[150:153], v[98:101]
	v_mfma_f32_16x16x32_bf16 v[102:105], v[212:215], v[150:153], v[102:105]
	ds_read_b128 v[150:153], v216 offset:8192
	s_waitcnt lgkmcnt(7)
	v_mfma_f32_16x16x32_bf16 v[106:109], v[200:203], v[154:157], v[106:109]
	v_mfma_f32_16x16x32_bf16 v[110:113], v[212:215], v[154:157], v[110:113]
	ds_read_b128 v[154:157], v216 offset:10240
	s_waitcnt lgkmcnt(7)
	v_mfma_f32_16x16x32_bf16 v[114:117], v[200:203], v[158:161], v[114:117]
	v_mfma_f32_16x16x32_bf16 v[118:121], v[212:215], v[158:161], v[118:121]
	ds_read_b128 v[158:161], v216 offset:12288
	s_waitcnt lgkmcnt(7)
	v_mfma_f32_16x16x32_bf16 v[122:125], v[200:203], v[162:165], v[122:125]
	v_mfma_f32_16x16x32_bf16 v[126:129], v[212:215], v[162:165], v[126:129]
	v_add_u32_e32 v217, 0x80, v217
	v_add_u32_e32 v220, 0x800, v220
	v_add_u32_e32 v221, 0x800, v221
	s_mov_b32 s16, 6

.Lg256b_ip_next_ok:
	s_lshl_b32 s13, s13, 8
	s_lshl_b32 s14, s14, 7
	s_lshl_b32 s3, s15, 6
	s_add_u32 s17, s3, s13
	s_mul_i32 s17, s17, 0x800
	s_add_u32 s6, s18, s17
	s_addc_u32 s7, s19, 0
	v_mov_b32_e32 v217, v218
	ds_read_b128 v[162:165], v216 offset:14336
	s_waitcnt vmcnt(8) lgkmcnt(7)
	v_mfma_f32_16x16x32_bf16 v[2:5], v[166:169], v[134:137], v[2:5]
	v_mfma_f32_16x16x32_bf16 v[6:9], v[174:177], v[134:137], v[6:9]
	ds_read_b128 v[134:137], v216 offset:16384
	s_waitcnt lgkmcnt(7)
	v_mfma_f32_16x16x32_bf16 v[10:13], v[166:169], v[138:141], v[10:13]
	v_mfma_f32_16x16x32_bf16 v[14:17], v[174:177], v[138:141], v[14:17]
	ds_read_b128 v[138:141], v216 offset:18432
	s_waitcnt lgkmcnt(7)
	v_mfma_f32_16x16x32_bf16 v[18:21], v[166:169], v[142:145], v[18:21]
	v_mfma_f32_16x16x32_bf16 v[22:25], v[174:177], v[142:145], v[22:25]
	ds_read_b128 v[142:145], v216 offset:20480
	s_waitcnt lgkmcnt(7)
	v_mfma_f32_16x16x32_bf16 v[26:29], v[166:169], v[146:149], v[26:29]
	v_mfma_f32_16x16x32_bf16 v[30:33], v[174:177], v[146:149], v[30:33]
	ds_read_b128 v[146:149], v216 offset:22528
	s_waitcnt lgkmcnt(7)
	v_mfma_f32_16x16x32_bf16 v[34:37], v[166:169], v[150:153], v[34:37]
	global_load_dwordx4 v[196:199], v220, s[8:9]
	v_mfma_f32_16x16x32_bf16 v[38:41], v[174:177], v[150:153], v[38:41]
	global_load_dwordx4 v[200:203], v220, s[8:9] offset:1024
	ds_read_b128 v[150:153], v216 offset:24576
	s_waitcnt lgkmcnt(7)
	v_mfma_f32_16x16x32_bf16 v[42:45], v[166:169], v[154:157], v[42:45]
	global_load_dwordx4 v[204:207], v221, s[8:9]
	v_mfma_f32_16x16x32_bf16 v[46:49], v[174:177], v[154:157], v[46:49]
	global_load_dwordx4 v[212:215], v221, s[8:9] offset:1024
	ds_read_b128 v[154:157], v216 offset:26624
	s_waitcnt lgkmcnt(7)
	v_mfma_f32_16x16x32_bf16 v[50:53], v[166:169], v[158:161], v[50:53]
	v_mfma_f32_16x16x32_bf16 v[54:57], v[174:177], v[158:161], v[54:57]
	ds_read_b128 v[158:161], v216 offset:28672
	s_waitcnt lgkmcnt(7)
	v_mfma_f32_16x16x32_bf16 v[58:61], v[166:169], v[162:165], v[58:61]
	v_mfma_f32_16x16x32_bf16 v[62:65], v[174:177], v[162:165], v[62:65]
	ds_read_b128 v[162:165], v216 offset:30720
	s_waitcnt lgkmcnt(7)
	v_mfma_f32_16x16x32_bf16 v[66:69], v[166:169], v[134:137], v[66:69]
	v_mfma_f32_16x16x32_bf16 v[70:73], v[174:177], v[134:137], v[70:73]
	ds_read_b128 v[134:137], v216 offset:1024
	s_waitcnt lgkmcnt(7)
	v_mfma_f32_16x16x32_bf16 v[74:77], v[166:169], v[138:141], v[74:77]
	v_mfma_f32_16x16x32_bf16 v[78:81], v[174:177], v[138:141], v[78:81]
	ds_read_b128 v[138:141], v216 offset:3072
	s_waitcnt lgkmcnt(7)
	v_mfma_f32_16x16x32_bf16 v[82:85], v[166:169], v[142:145], v[82:85]
	v_mfma_f32_16x16x32_bf16 v[86:89], v[174:177], v[142:145], v[86:89]
	ds_read_b128 v[142:145], v216 offset:5120
	s_waitcnt lgkmcnt(7)
	v_mfma_f32_16x16x32_bf16 v[90:93], v[166:169], v[146:149], v[90:93]
	v_mfma_f32_16x16x32_bf16 v[94:97], v[174:177], v[146:149], v[94:97]
	ds_read_b128 v[146:149], v216 offset:7168
	s_waitcnt lgkmcnt(7)
	v_mfma_f32_16x16x32_bf16 v[98:101], v[166:169], v[150:153], v[98:101]
	v_mfma_f32_16x16x32_bf16 v[102:105], v[174:177], v[150:153], v[102:105]
	ds_read_b128 v[150:153], v216 offset:9216
	s_waitcnt lgkmcnt(7)
	v_mfma_f32_16x16x32_bf16 v[106:109], v[166:169], v[154:157], v[106:109]
	v_mfma_f32_16x16x32_bf16 v[110:113], v[174:177], v[154:157], v[110:113]
	ds_read_b128 v[154:157], v216 offset:11264
	s_waitcnt lgkmcnt(7)
	v_mfma_f32_16x16x32_bf16 v[114:117], v[166:169], v[158:161], v[114:117]
	v_mfma_f32_16x16x32_bf16 v[118:121], v[174:177], v[158:161], v[118:121]
	ds_read_b128 v[158:161], v216 offset:13312
	s_waitcnt lgkmcnt(7)
	v_mfma_f32_16x16x32_bf16 v[122:125], v[166:169], v[162:165], v[122:125]
	v_mfma_f32_16x16x32_bf16 v[126:129], v[174:177], v[162:165], v[126:129]
	ds_read_b128 v[162:165], v216 offset:15360
	s_waitcnt lgkmcnt(7)
	v_mfma_f32_16x16x32_bf16 v[2:5], v[170:173], v[134:137], v[2:5]
	v_mfma_f32_16x16x32_bf16 v[6:9], v[178:181], v[134:137], v[6:9]
	ds_read_b128 v[134:137], v216 offset:17408
	s_waitcnt lgkmcnt(7)
	v_mfma_f32_16x16x32_bf16 v[10:13], v[170:173], v[138:141], v[10:13]
	v_mfma_f32_16x16x32_bf16 v[14:17], v[178:181], v[138:141], v[14:17]
	ds_read_b128 v[138:141], v216 offset:19456
	s_waitcnt lgkmcnt(7)
	v_mfma_f32_16x16x32_bf16 v[18:21], v[170:173], v[142:145], v[18:21]
	v_mfma_f32_16x16x32_bf16 v[22:25], v[178:181], v[142:145], v[22:25]
	ds_read_b128 v[142:145], v216 offset:21504
	s_waitcnt lgkmcnt(7)
	v_mfma_f32_16x16x32_bf16 v[26:29], v[170:173], v[146:149], v[26:29]
	v_mfma_f32_16x16x32_bf16 v[30:33], v[178:181], v[146:149], v[30:33]
	ds_read_b128 v[146:149], v216 offset:23552
	s_waitcnt lgkmcnt(7)
	v_mfma_f32_16x16x32_bf16 v[34:37], v[170:173], v[150:153], v[34:37]
	v_mfma_f32_16x16x32_bf16 v[38:41], v[178:181], v[150:153], v[38:41]
	ds_read_b128 v[150:153], v216 offset:25600
	s_waitcnt lgkmcnt(7)
	v_mfma_f32_16x16x32_bf16 v[42:45], v[170:173], v[154:157], v[42:45]
	v_mfma_f32_16x16x32_bf16 v[46:49], v[178:181], v[154:157], v[46:49]
	ds_read_b128 v[154:157], v216 offset:27648
	s_waitcnt lgkmcnt(7)
	v_mfma_f32_16x16x32_bf16 v[50:53], v[170:173], v[158:161], v[50:53]
	v_mfma_f32_16x16x32_bf16 v[54:57], v[178:181], v[158:161], v[54:57]
	ds_read_b128 v[158:161], v216 offset:29696
	s_waitcnt lgkmcnt(7)
	v_mfma_f32_16x16x32_bf16 v[58:61], v[170:173], v[162:165], v[58:61]
	v_mfma_f32_16x16x32_bf16 v[62:65], v[178:181], v[162:165], v[62:65]
	ds_read_b128 v[162:165], v216 offset:31744
	s_waitcnt vmcnt(4) lgkmcnt(0)
	s_barrier
	v_mfma_f32_16x16x32_bf16 v[66:69], v[170:173], v[134:137], v[66:69]
	s_add_u32 m0, s22, 0x0
	v_mov_b32_e32 v223, v217
	global_load_lds_dwordx4 v223, s[6:7]
	v_mfma_f32_16x16x32_bf16 v[70:73], v[178:181], v[134:137], v[70:73]
	s_add_u32 m0, s22, 0x400
	v_add_u32_e32 v224, 0x40, v217
	global_load_lds_dwordx4 v224, s[6:7]
	ds_read_b128 v[134:137], v216 offset:32768
	s_waitcnt lgkmcnt(7)
	v_mfma_f32_16x16x32_bf16 v[74:77], v[170:173], v[138:141], v[74:77]
	s_add_u32 m0, s22, 0x800
	v_add_u32_e32 v223, 0x8000, v217
	global_load_lds_dwordx4 v223, s[6:7]
	v_mfma_f32_16x16x32_bf16 v[78:81], v[178:181], v[138:141], v[78:81]
	s_add_u32 m0, s22, 0xc00
	v_add_u32_e32 v224, 0x8040, v217
	global_load_lds_dwordx4 v224, s[6:7]
	ds_read_b128 v[138:141], v216 offset:34816
	s_waitcnt lgkmcnt(7)
	v_mfma_f32_16x16x32_bf16 v[82:85], v[170:173], v[142:145], v[82:85]
	s_add_u32 m0, s22, 0x1000
	v_add_u32_e32 v223, 0x10000, v217
	global_load_lds_dwordx4 v223, s[6:7]
	v_mfma_f32_16x16x32_bf16 v[86:89], v[178:181], v[142:145], v[86:89]
	s_add_u32 m0, s22, 0x1400
	v_add_u32_e32 v224, 0x10040, v217
	global_load_lds_dwordx4 v224, s[6:7]
	ds_read_b128 v[142:145], v216 offset:36864
	s_waitcnt lgkmcnt(7)
	v_mfma_f32_16x16x32_bf16 v[90:93], v[170:173], v[146:149], v[90:93]
	s_add_u32 m0, s22, 0x1800
	v_add_u32_e32 v223, 0x18000, v217
	global_load_lds_dwordx4 v223, s[6:7]
	v_mfma_f32_16x16x32_bf16 v[94:97], v[178:181], v[146:149], v[94:97]
	s_add_u32 m0, s22, 0x1c00
	v_add_u32_e32 v224, 0x18040, v217
	global_load_lds_dwordx4 v224, s[6:7]
	ds_read_b128 v[146:149], v216 offset:38912
	s_waitcnt lgkmcnt(7)
	v_mfma_f32_16x16x32_bf16 v[98:101], v[170:173], v[150:153], v[98:101]
	v_mfma_f32_16x16x32_bf16 v[102:105], v[178:181], v[150:153], v[102:105]
	ds_read_b128 v[150:153], v216 offset:40960
	s_waitcnt lgkmcnt(7)
	v_mfma_f32_16x16x32_bf16 v[106:109], v[170:173], v[154:157], v[106:109]
	v_mfma_f32_16x16x32_bf16 v[110:113], v[178:181], v[154:157], v[110:113]
	ds_read_b128 v[154:157], v216 offset:43008
	s_waitcnt lgkmcnt(7)
	v_mfma_f32_16x16x32_bf16 v[114:117], v[170:173], v[158:161], v[114:117]
	v_mfma_f32_16x16x32_bf16 v[118:121], v[178:181], v[158:161], v[118:121]
	ds_read_b128 v[158:161], v216 offset:45056
	s_waitcnt lgkmcnt(7)
	v_mfma_f32_16x16x32_bf16 v[122:125], v[170:173], v[162:165], v[122:125]
	v_mfma_f32_16x16x32_bf16 v[126:129], v[178:181], v[162:165], v[126:129]
	v_add_u32_e32 v217, 0x80, v217
	v_add_u32_e32 v220, 0x800, v220
	v_add_u32_e32 v221, 0x800, v221
	s_lshr_b32 s3, s14, 4
	s_lshl_b32 s17, s15, 1
	s_add_u32 s3, s3, s17
	s_mul_i32 s17, s3, 0x8000
	s_add_u32 s8, s20, s17
	s_addc_u32 s9, s21, 0
	v_mov_b32_e32 v220, v222
	v_add_u32_e32 v221, 0x8000, v222
	ds_read_b128 v[162:165], v216 offset:47104
	s_waitcnt vmcnt(8) lgkmcnt(7)
	v_mfma_f32_16x16x32_bf16 v[2:5], v[196:199], v[134:137], v[2:5]
	v_mfma_f32_16x16x32_bf16 v[6:9], v[204:207], v[134:137], v[6:9]
	ds_read_b128 v[134:137], v216 offset:49152
	s_waitcnt lgkmcnt(7)
	v_mfma_f32_16x16x32_bf16 v[10:13], v[196:199], v[138:141], v[10:13]
	v_mfma_f32_16x16x32_bf16 v[14:17], v[204:207], v[138:141], v[14:17]
	ds_read_b128 v[138:141], v216 offset:51200
	s_waitcnt lgkmcnt(7)
	v_mfma_f32_16x16x32_bf16 v[18:21], v[196:199], v[142:145], v[18:21]
	v_mfma_f32_16x16x32_bf16 v[22:25], v[204:207], v[142:145], v[22:25]
	ds_read_b128 v[142:145], v216 offset:53248
	s_waitcnt lgkmcnt(7)
	v_mfma_f32_16x16x32_bf16 v[26:29], v[196:199], v[146:149], v[26:29]
	v_mfma_f32_16x16x32_bf16 v[30:33], v[204:207], v[146:149], v[30:33]
	ds_read_b128 v[146:149], v216 offset:55296
	s_waitcnt lgkmcnt(7)
	v_mfma_f32_16x16x32_bf16 v[34:37], v[196:199], v[150:153], v[34:37]
	global_load_dwordx4 v[166:169], v220, s[8:9]
	v_mfma_f32_16x16x32_bf16 v[38:41], v[204:207], v[150:153], v[38:41]
	global_load_dwordx4 v[170:173], v220, s[8:9] offset:1024
	ds_read_b128 v[150:153], v216 offset:57344
	s_waitcnt lgkmcnt(7)
	v_mfma_f32_16x16x32_bf16 v[42:45], v[196:199], v[154:157], v[42:45]
	global_load_dwordx4 v[174:177], v221, s[8:9]
	v_mfma_f32_16x16x32_bf16 v[46:49], v[204:207], v[154:157], v[46:49]
	global_load_dwordx4 v[178:181], v221, s[8:9] offset:1024
	ds_read_b128 v[154:157], v216 offset:59392
	s_waitcnt lgkmcnt(7)
	v_mfma_f32_16x16x32_bf16 v[50:53], v[196:199], v[158:161], v[50:53]
	v_mfma_f32_16x16x32_bf16 v[54:57], v[204:207], v[158:161], v[54:57]
	ds_read_b128 v[158:161], v216 offset:61440
	s_waitcnt lgkmcnt(7)
	v_mfma_f32_16x16x32_bf16 v[58:61], v[196:199], v[162:165], v[58:61]
	v_mfma_f32_16x16x32_bf16 v[62:65], v[204:207], v[162:165], v[62:65]
	ds_read_b128 v[162:165], v216 offset:63488
	s_waitcnt lgkmcnt(7)
	v_mfma_f32_16x16x32_bf16 v[66:69], v[196:199], v[134:137], v[66:69]
	v_mfma_f32_16x16x32_bf16 v[70:73], v[204:207], v[134:137], v[70:73]
	ds_read_b128 v[134:137], v216 offset:33792
	s_waitcnt lgkmcnt(7)
	v_mfma_f32_16x16x32_bf16 v[74:77], v[196:199], v[138:141], v[74:77]
	v_mfma_f32_16x16x32_bf16 v[78:81], v[204:207], v[138:141], v[78:81]
	ds_read_b128 v[138:141], v216 offset:35840
	s_waitcnt lgkmcnt(7)
	v_mfma_f32_16x16x32_bf16 v[82:85], v[196:199], v[142:145], v[82:85]
	v_mfma_f32_16x16x32_bf16 v[86:89], v[204:207], v[142:145], v[86:89]
	ds_read_b128 v[142:145], v216 offset:37888
	s_waitcnt lgkmcnt(7)
	v_mfma_f32_16x16x32_bf16 v[90:93], v[196:199], v[146:149], v[90:93]
	v_mfma_f32_16x16x32_bf16 v[94:97], v[204:207], v[146:149], v[94:97]
	ds_read_b128 v[146:149], v216 offset:39936
	s_waitcnt lgkmcnt(7)
	v_mfma_f32_16x16x32_bf16 v[98:101], v[196:199], v[150:153], v[98:101]
	v_mfma_f32_16x16x32_bf16 v[102:105], v[204:207], v[150:153], v[102:105]
	ds_read_b128 v[150:153], v216 offset:41984
	s_waitcnt lgkmcnt(7)
	v_mfma_f32_16x16x32_bf16 v[106:109], v[196:199], v[154:157], v[106:109]
	v_mfma_f32_16x16x32_bf16 v[110:113], v[204:207], v[154:157], v[110:113]
	ds_read_b128 v[154:157], v216 offset:44032
	s_waitcnt lgkmcnt(7)
	v_mfma_f32_16x16x32_bf16 v[114:117], v[196:199], v[158:161], v[114:117]
	v_mfma_f32_16x16x32_bf16 v[118:121], v[204:207], v[158:161], v[118:121]
	ds_read_b128 v[158:161], v216 offset:46080
	s_waitcnt lgkmcnt(7)
	v_mfma_f32_16x16x32_bf16 v[122:125], v[196:199], v[162:165], v[122:125]
	v_mfma_f32_16x16x32_bf16 v[126:129], v[204:207], v[162:165], v[126:129]
	ds_read_b128 v[162:165], v216 offset:48128
	s_waitcnt lgkmcnt(7)
	v_mfma_f32_16x16x32_bf16 v[2:5], v[200:203], v[134:137], v[2:5]
	v_mfma_f32_16x16x32_bf16 v[6:9], v[212:215], v[134:137], v[6:9]
	ds_read_b128 v[134:137], v216 offset:50176
	s_waitcnt lgkmcnt(7)
	v_mfma_f32_16x16x32_bf16 v[10:13], v[200:203], v[138:141], v[10:13]
	v_mfma_f32_16x16x32_bf16 v[14:17], v[212:215], v[138:141], v[14:17]
	ds_read_b128 v[138:141], v216 offset:52224
	s_waitcnt lgkmcnt(7)
	v_mfma_f32_16x16x32_bf16 v[18:21], v[200:203], v[142:145], v[18:21]
	v_mfma_f32_16x16x32_bf16 v[22:25], v[212:215], v[142:145], v[22:25]
	ds_read_b128 v[142:145], v216 offset:54272
	s_waitcnt lgkmcnt(7)
	v_mfma_f32_16x16x32_bf16 v[26:29], v[200:203], v[146:149], v[26:29]
	v_mfma_f32_16x16x32_bf16 v[30:33], v[212:215], v[146:149], v[30:33]
	ds_read_b128 v[146:149], v216 offset:56320
	s_waitcnt lgkmcnt(7)
	v_mfma_f32_16x16x32_bf16 v[34:37], v[200:203], v[150:153], v[34:37]
	v_mfma_f32_16x16x32_bf16 v[38:41], v[212:215], v[150:153], v[38:41]
	ds_read_b128 v[150:153], v216 offset:58368
	s_waitcnt lgkmcnt(7)
	v_mfma_f32_16x16x32_bf16 v[42:45], v[200:203], v[154:157], v[42:45]
	v_mfma_f32_16x16x32_bf16 v[46:49], v[212:215], v[154:157], v[46:49]
	ds_read_b128 v[154:157], v216 offset:60416
	s_waitcnt lgkmcnt(7)
	v_mfma_f32_16x16x32_bf16 v[50:53], v[200:203], v[158:161], v[50:53]
	v_mfma_f32_16x16x32_bf16 v[54:57], v[212:215], v[158:161], v[54:57]
	ds_read_b128 v[158:161], v216 offset:62464
	s_waitcnt lgkmcnt(7)
	v_mfma_f32_16x16x32_bf16 v[58:61], v[200:203], v[162:165], v[58:61]
	v_mfma_f32_16x16x32_bf16 v[62:65], v[212:215], v[162:165], v[62:65]
	ds_read_b128 v[162:165], v216 offset:64512
	s_waitcnt vmcnt(4) lgkmcnt(0)
	s_barrier
	v_mfma_f32_16x16x32_bf16 v[66:69], v[200:203], v[134:137], v[66:69]
	s_add_u32 m0, s22, 0x8000
	v_mov_b32_e32 v223, v217
	global_load_lds_dwordx4 v223, s[6:7]
	v_mfma_f32_16x16x32_bf16 v[70:73], v[212:215], v[134:137], v[70:73]
	s_add_u32 m0, s22, 0x8400
	v_add_u32_e32 v224, 0x40, v217
	global_load_lds_dwordx4 v224, s[6:7]
	ds_read_b128 v[134:137], v216
	s_waitcnt lgkmcnt(7)
	v_mfma_f32_16x16x32_bf16 v[74:77], v[200:203], v[138:141], v[74:77]
	s_add_u32 m0, s22, 0x8800
	v_add_u32_e32 v223, 0x8000, v217
	global_load_lds_dwordx4 v223, s[6:7]
	v_mfma_f32_16x16x32_bf16 v[78:81], v[212:215], v[138:141], v[78:81]
	s_add_u32 m0, s22, 0x8c00
	v_add_u32_e32 v224, 0x8040, v217
	global_load_lds_dwordx4 v224, s[6:7]
	ds_read_b128 v[138:141], v216 offset:2048
	s_waitcnt lgkmcnt(7)
	v_mfma_f32_16x16x32_bf16 v[82:85], v[200:203], v[142:145], v[82:85]
	s_add_u32 m0, s22, 0x9000
	v_add_u32_e32 v223, 0x10000, v217
	global_load_lds_dwordx4 v223, s[6:7]
	v_mfma_f32_16x16x32_bf16 v[86:89], v[212:215], v[142:145], v[86:89]
	s_add_u32 m0, s22, 0x9400
	v_add_u32_e32 v224, 0x10040, v217
	global_load_lds_dwordx4 v224, s[6:7]
	ds_read_b128 v[142:145], v216 offset:4096
	s_waitcnt lgkmcnt(7)
	v_mfma_f32_16x16x32_bf16 v[90:93], v[200:203], v[146:149], v[90:93]
	s_add_u32 m0, s22, 0x9800
	v_add_u32_e32 v223, 0x18000, v217
	global_load_lds_dwordx4 v223, s[6:7]
	v_mfma_f32_16x16x32_bf16 v[94:97], v[212:215], v[146:149], v[94:97]
	s_add_u32 m0, s22, 0x9c00
	v_add_u32_e32 v224, 0x18040, v217
	global_load_lds_dwordx4 v224, s[6:7]
	ds_read_b128 v[146:149], v216 offset:6144
	s_waitcnt lgkmcnt(7)
	v_mfma_f32_16x16x32_bf16 v[98:101], v[200:203], v[150:153], v[98:101]
	v_mfma_f32_16x16x32_bf16 v[102:105], v[212:215], v[150:153], v[102:105]
	ds_read_b128 v[150:153], v216 offset:8192
	s_waitcnt lgkmcnt(7)
	v_mfma_f32_16x16x32_bf16 v[106:109], v[200:203], v[154:157], v[106:109]
	v_mfma_f32_16x16x32_bf16 v[110:113], v[212:215], v[154:157], v[110:113]
	ds_read_b128 v[154:157], v216 offset:10240
	s_waitcnt lgkmcnt(7)
	v_mfma_f32_16x16x32_bf16 v[114:117], v[200:203], v[158:161], v[114:117]
	v_mfma_f32_16x16x32_bf16 v[118:121], v[212:215], v[158:161], v[118:121]
	ds_read_b128 v[158:161], v216 offset:12288
	s_waitcnt lgkmcnt(7)
	v_mfma_f32_16x16x32_bf16 v[122:125], v[200:203], v[162:165], v[122:125]
	v_mfma_f32_16x16x32_bf16 v[126:129], v[212:215], v[162:165], v[126:129]
	v_add_u32_e32 v217, 0x80, v217
	v_add_u32_e32 v220, 0x800, v220
	v_add_u32_e32 v221, 0x800, v221
	s_mov_b32 s16, 1
	s_branch .Lg256b_ip_epi
